# baseline (speedup 1.0000x reference)
; #define MFMA16(a, b, c) __builtin_amdgcn_mfma_f32_16x16x32_bf16(a, b, c, 0, 0, 0)
; template <int WM, int WN> ...
;     ...
; #pragma unroll
;   for (int n = 0; n < 4; ++n) fb0[n] = LDSF(cur + boff + n * 1024);
; #pragma unroll
;   for (int m = 0; m < 4; ++m) fa0[m] = LDSF(cur + aoff + m * 1024);
;   acc[3][0] = MFMA16(pa, pb0, acc[3][0]);
;   acc[3][1] = MFMA16(pa, pb1, acc[3][1]);
;   acc[3][2] = MFMA16(pa, pb2, acc[3][2]);
;   acc[3][3] = MFMA16(pa, pb3, acc[3][3]);
; #pragma unroll
;   for (int n = 0; n < 4; ++n) acc[0][n] = MFMA16(fa0[0], fb0[n], acc[0][n]);
; #pragma unroll
;   for (int m = 0; m < 4; ++m) fa1[m] = LDSF(cur + aoff + APAN + m * 1024);
; #pragma unroll
;   for (int n = 0; n < 4; ++n) acc[1][n] = MFMA16(fa0[1], fb0[n], acc[1][n]);
; #pragma unroll
;   for (int n = 0; n < 4; ++n) fb1[n] = LDSF(cur + boff + BPAN + n * 1024);
; #pragma unroll
;   for (int n = 0; n < 4; ++n) acc[2][n] = MFMA16(fa0[2], fb0[n], acc[2][n]);
;   *reinterpret_cast<uint4*>(nxt + wao) = a0;
;   *reinterpret_cast<uint4*>(nxt + wao + 32 * 64) = a1;
; #pragma unroll
;   for (int n = 0; n < 4; ++n) acc[3][n] = MFMA16(fa0[3], fb0[n], acc[3][n]);
;   *reinterpret_cast<uint4*>(nxt + wao + 64 * 64) = a2;
;   *reinterpret_cast<uint4*>(nxt + wao + 96 * 64) = a3;
; #pragma unroll
;   for (int n = 0; n < 4; ++n) acc[0][n] = MFMA16(fa1[0], fb1[n], acc[0][n]);
;   *reinterpret_cast<uint4*>(nxt + wbo) = b0;
;   *reinterpret_cast<uint4*>(nxt + wbo + 32 * 64) = b1;
; #pragma unroll
;   for (int n = 0; n < 4; ++n) acc[1][n] = MFMA16(fa1[1], fb1[n], acc[1][n]);
;   *reinterpret_cast<uint4*>(nxt + wbo + 64 * 64) = b2;
;   *reinterpret_cast<uint4*>(nxt + wbo + 96 * 64) = b3;
; #pragma unroll
;   for (int n = 0; n < 4; ++n) acc[2][n] = MFMA16(fa1[2], fb1[n], acc[2][n]);
;   pa = fa1[3];
;   pb0 = fb1[0]; pb1 = fb1[1]; pb2 = fb1[2]; pb3 = fb1[3];
.LBB0_104:
	s_add_i32 s11, s6, 2
	s_add_i32 s6, s6, 4
	s_min_u32 s6, s6, 15
	s_lshl_b32 s6, s6, 7
	s_add_u32 s92, s14, s6
	s_addc_u32 s93, s15, 0
	s_add_u32 s94, s20, s6
	s_addc_u32 s95, s21, 0
	ds_read_b128 v[148:151], v119
	ds_read_b128 v[132:135], v130 offset:16512
	ds_read_b128 v[136:139], v130 offset:17536
	ds_read_b128 v[140:143], v130 offset:18560
	ds_read_b128 v[144:147], v130 offset:19584
	v_mfma_f32_16x16x32_bf16 v[84:87], v[80:83], v[84:87], v[100:103]
	v_mfma_f32_16x16x32_bf16 v[96:99], v[80:83], v[104:107], v[96:99]
	s_waitcnt vmcnt(4)
	ds_write_b128 v131, v[76:79] offset:33024
	global_load_dwordx4 v[76:79], v116, s[92:93]
	s_add_u32 s52, s14, s6
	s_addc_u32 s53, s15, 0
	v_mfma_f32_16x16x32_bf16 v[92:95], v[80:83], v[108:111], v[92:95]
	v_mfma_f32_16x16x32_bf16 v[80:83], v[80:83], v[112:115], v[88:91]
	s_waitcnt lgkmcnt(4)
	v_mfma_f32_16x16x32_bf16 v[44:47], v[148:151], v[132:135], v[44:47]
	s_nop 0
	ds_read_b128 v[88:91], v119 offset:1024
	s_waitcnt lgkmcnt(4)
	v_mfma_f32_16x16x32_bf16 v[40:43], v[148:151], v[136:139], v[40:43]
	ds_write_b128 v131, v[68:71] offset:35072
	global_load_dwordx4 v[68:71], v120, s[92:93]
	ds_read_b128 v[100:103], v119 offset:2048
	s_waitcnt lgkmcnt(5)
	v_mfma_f32_16x16x32_bf16 v[36:39], v[148:151], v[140:143], v[36:39]
	ds_read_b128 v[104:107], v119 offset:3072
	s_waitcnt lgkmcnt(5)
	v_mfma_f32_16x16x32_bf16 v[32:35], v[148:151], v[144:147], v[32:35]
	ds_read_b128 v[108:111], v119 offset:8256
	s_waitcnt lgkmcnt(4)
	v_mfma_f32_16x16x32_bf16 v[28:31], v[88:91], v[132:135], v[28:31]
	ds_read_b128 v[112:115], v119 offset:9280
	v_mfma_f32_16x16x32_bf16 v[24:27], v[88:91], v[136:139], v[24:27]
	ds_read_b128 v[148:151], v119 offset:10304
	v_mfma_f32_16x16x32_bf16 v[20:23], v[88:91], v[140:143], v[20:23]
	ds_write_b128 v131, v[64:67] offset:37120
	global_load_dwordx4 v[64:67], v122, s[92:93]
	ds_read_b128 v[152:155], v119 offset:11328
	v_mfma_f32_16x16x32_bf16 v[16:19], v[88:91], v[144:147], v[16:19]
	ds_read_b128 v[88:91], v130 offset:24768
	s_waitcnt lgkmcnt(7)
	v_mfma_f32_16x16x32_bf16 v[12:15], v[100:103], v[132:135], v[12:15]
	ds_read_b128 v[156:159], v130 offset:25792
	v_mfma_f32_16x16x32_bf16 v[8:11], v[100:103], v[136:139], v[8:11]
	ds_read_b128 v[160:163], v130 offset:26816
	v_mfma_f32_16x16x32_bf16 v[4:7], v[100:103], v[140:143], v[4:7]
	ds_write_b128 v131, v[72:75] offset:39168
	global_load_dwordx4 v[72:75], v124, s[92:93]
	ds_read_b128 v[164:167], v130 offset:27840
	v_mfma_f32_16x16x32_bf16 v[0:3], v[100:103], v[144:147], v[0:3]
	s_waitcnt lgkmcnt(10)
	v_mfma_f32_16x16x32_bf16 v[84:87], v[104:107], v[132:135], v[84:87]
	v_mfma_f32_16x16x32_bf16 v[96:99], v[104:107], v[136:139], v[96:99]
	v_mfma_f32_16x16x32_bf16 v[92:95], v[104:107], v[140:143], v[92:95]
	v_mfma_f32_16x16x32_bf16 v[80:83], v[104:107], v[144:147], v[80:83]
	s_waitcnt vmcnt(4)
	ds_write_b128 v131, v[60:63] offset:49536
	global_load_dwordx4 v[60:63], v116, s[94:95]
	s_waitcnt lgkmcnt(5)
	v_mfma_f32_16x16x32_bf16 v[44:47], v[108:111], v[88:91], v[44:47]
	s_add_u32 s52, s20, s6
	s_addc_u32 s53, s21, 0
	s_waitcnt lgkmcnt(4)
	v_mfma_f32_16x16x32_bf16 v[40:43], v[108:111], v[156:159], v[40:43]
	s_min_u32 s6, s11, 12
	s_lshl_b32 s6, s6, 7
	s_waitcnt lgkmcnt(3)
	v_mfma_f32_16x16x32_bf16 v[36:39], v[108:111], v[160:163], v[36:39]
	s_waitcnt lgkmcnt(1)
	v_mfma_f32_16x16x32_bf16 v[32:35], v[108:111], v[164:167], v[32:35]
	ds_write_b128 v131, v[56:59] offset:51584
	global_load_dwordx4 v[56:59], v120, s[94:95]
	v_mfma_f32_16x16x32_bf16 v[28:31], v[112:115], v[88:91], v[28:31]
	v_mfma_f32_16x16x32_bf16 v[24:27], v[112:115], v[156:159], v[24:27]
	v_mfma_f32_16x16x32_bf16 v[20:23], v[112:115], v[160:163], v[20:23]
	v_mfma_f32_16x16x32_bf16 v[16:19], v[112:115], v[164:167], v[16:19]
	v_mfma_f32_16x16x32_bf16 v[12:15], v[148:151], v[88:91], v[12:15]
	ds_write_b128 v131, v[52:55] offset:53632
	global_load_dwordx4 v[52:55], v122, s[94:95]
	v_mfma_f32_16x16x32_bf16 v[8:11], v[148:151], v[156:159], v[8:11]
	s_add_u32 s52, s14, s6
	s_addc_u32 s53, s15, 0
	s_add_u32 s54, s20, s6
	v_mfma_f32_16x16x32_bf16 v[4:7], v[148:151], v[160:163], v[4:7]
	s_addc_u32 s55, s21, 0
	v_mfma_f32_16x16x32_bf16 v[0:3], v[148:151], v[164:167], v[0:3]
	v_mfma_f32_16x16x32_bf16 v[88:91], v[152:155], v[88:91], v[84:87]
	ds_write_b128 v131, v[48:51] offset:55680
	global_load_dwordx4 v[48:51], v124, s[94:95]
	v_mfma_f32_16x16x32_bf16 v[96:99], v[152:155], v[156:159], v[96:99]
	v_mfma_f32_16x16x32_bf16 v[92:95], v[152:155], v[160:163], v[92:95]
	v_mfma_f32_16x16x32_bf16 v[132:135], v[152:155], v[164:167], v[80:83]
	s_waitcnt lgkmcnt(0)
	s_barrier
; template <int WM, int WN> ...
;     ...
; #pragma unroll
;   for (int n = 0; n < 4; ++n) fb0[n] = LDSF(cur + boff + n * 1024);
; #pragma unroll
;   for (int m = 0; m < 4; ++m) fa0[m] = LDSF(cur + aoff + m * 1024);
;   acc[3][0] = MFMA16(pa, pb0, acc[3][0]);
;   acc[3][1] = MFMA16(pa, pb1, acc[3][1]);
;   acc[3][2] = MFMA16(pa, pb2, acc[3][2]);
;   acc[3][3] = MFMA16(pa, pb3, acc[3][3]);
; #pragma unroll
;   for (int n = 0; n < 4; ++n) acc[0][n] = MFMA16(fa0[0], fb0[n], acc[0][n]);
; #pragma unroll
;   for (int m = 0; m < 4; ++m) fa1[m] = LDSF(cur + aoff + APAN + m * 1024);
; #pragma unroll
;   for (int n = 0; n < 4; ++n) acc[1][n] = MFMA16(fa0[1], fb0[n], acc[1][n]);
; #pragma unroll
;   for (int n = 0; n < 4; ++n) fb1[n] = LDSF(cur + boff + BPAN + n * 1024);
; #pragma unroll
;   for (int n = 0; n < 4; ++n) acc[2][n] = MFMA16(fa0[2], fb0[n], acc[2][n]);
;   *reinterpret_cast<uint4*>(nxt + wao) = a0;
;   *reinterpret_cast<uint4*>(nxt + wao + 32 * 64) = a1;
; #pragma unroll
;   for (int n = 0; n < 4; ++n) acc[3][n] = MFMA16(fa0[3], fb0[n], acc[3][n]);
;   *reinterpret_cast<uint4*>(nxt + wao + 64 * 64) = a2;
;   *reinterpret_cast<uint4*>(nxt + wao + 96 * 64) = a3;
; #pragma unroll
;   for (int n = 0; n < 4; ++n) acc[0][n] = MFMA16(fa1[0], fb1[n], acc[0][n]);
;   *reinterpret_cast<uint4*>(nxt + wbo) = b0;
;   *reinterpret_cast<uint4*>(nxt + wbo + 32 * 64) = b1;
; #pragma unroll
;   for (int n = 0; n < 4; ++n) acc[1][n] = MFMA16(fa1[1], fb1[n], acc[1][n]);
;   *reinterpret_cast<uint4*>(nxt + wbo + 64 * 64) = b2;
;   *reinterpret_cast<uint4*>(nxt + wbo + 96 * 64) = b3;
; #pragma unroll
;   for (int n = 0; n < 4; ++n) acc[2][n] = MFMA16(fa1[2], fb1[n], acc[2][n]);
;   pa = fa1[3];
;   pb0 = fb1[0]; pb1 = fb1[1]; pb2 = fb1[2]; pb3 = fb1[3];
;   SGB_(0x100, 5);
;   SGB_(0x008, 4);
; #pragma unroll
;   for (int i_ = 0; i_ < 11; ++i_) { SGB_(0x008, 1); SGB_(0x100, 1); }
; #pragma unroll
;   for (int i_ = 0; i_ < 8; ++i_) { SGB_(0x008, 2); SGB_(0x200, 1); SGB_(0x020, 1); }
;   SGB_(0x008, 1);
; }
; template <int WM, int WN, typename SrcF, typename PostF>
; __device__ __forceinline__ void gemm_stream(const int nsteps, SrcF src, PostF post, f32x4 (&acc)[WM][WN], char* smem) {
;     ...
;       TileSrc s = src(min(kt + 3, nsteps - 1));
;       GLOAD_TILE(ya, s.a, s.lda, ACH);
;       GLOAD_TILE(yb, s.b, s.ldb, BCH);
;     }
	s_nop 0
	ds_read_b128 v[80:83], v119 offset:33024
	ds_read_b128 v[100:103], v130 offset:49536
	ds_read_b128 v[112:115], v130 offset:50560
	ds_read_b128 v[136:139], v130 offset:51584
	ds_read_b128 v[140:143], v130 offset:52608
	s_waitcnt lgkmcnt(3)
	v_mfma_f32_16x16x32_bf16 v[44:47], v[80:83], v[100:103], v[44:47]
	s_waitcnt lgkmcnt(2)
	v_mfma_f32_16x16x32_bf16 v[40:43], v[80:83], v[112:115], v[40:43]
	s_waitcnt vmcnt(4)
	ds_write_b128 v131, v[76:79]
	global_load_dwordx4 v[76:79], v116, s[52:53] offset:384
	s_waitcnt lgkmcnt(2)
	v_mfma_f32_16x16x32_bf16 v[36:39], v[80:83], v[136:139], v[36:39]
	s_waitcnt lgkmcnt(0)
	v_mfma_f32_16x16x32_bf16 v[32:35], v[80:83], v[140:143], v[32:35]
	ds_read_b128 v[80:83], v119 offset:34048
	s_waitcnt lgkmcnt(0)
	v_mfma_f32_16x16x32_bf16 v[28:31], v[80:83], v[100:103], v[28:31]
	ds_write_b128 v131, v[68:71] offset:2048
	global_load_dwordx4 v[68:71], v120, s[52:53] offset:384
	ds_read_b128 v[104:107], v119 offset:35072
	v_mfma_f32_16x16x32_bf16 v[24:27], v[80:83], v[112:115], v[24:27]
	ds_read_b128 v[144:147], v119 offset:36096
	v_mfma_f32_16x16x32_bf16 v[20:23], v[80:83], v[136:139], v[20:23]
	ds_read_b128 v[148:151], v119 offset:41280
	v_mfma_f32_16x16x32_bf16 v[16:19], v[80:83], v[140:143], v[16:19]
	ds_read_b128 v[152:155], v119 offset:42304
	s_waitcnt lgkmcnt(3)
	v_mfma_f32_16x16x32_bf16 v[12:15], v[104:107], v[100:103], v[12:15]
	ds_write_b128 v131, v[64:67] offset:4096
	global_load_dwordx4 v[64:67], v122, s[52:53] offset:384
	ds_read_b128 v[156:159], v119 offset:43328
	v_mfma_f32_16x16x32_bf16 v[8:11], v[104:107], v[112:115], v[8:11]
	ds_read_b128 v[80:83], v119 offset:44352
	v_mfma_f32_16x16x32_bf16 v[4:7], v[104:107], v[136:139], v[4:7]
	ds_read_b128 v[84:87], v130 offset:57792
	v_mfma_f32_16x16x32_bf16 v[0:3], v[104:107], v[140:143], v[0:3]
	ds_write_b128 v131, v[72:75] offset:6144
	global_load_dwordx4 v[72:75], v124, s[52:53] offset:384
	ds_read_b128 v[104:107], v130 offset:58816
	s_waitcnt lgkmcnt(8)
	v_mfma_f32_16x16x32_bf16 v[100:103], v[144:147], v[100:103], v[88:91]
	ds_read_b128 v[108:111], v130 offset:59840
	v_mfma_f32_16x16x32_bf16 v[96:99], v[144:147], v[112:115], v[96:99]
	ds_read_b128 v[112:115], v130 offset:60864
	v_mfma_f32_16x16x32_bf16 v[92:95], v[144:147], v[136:139], v[92:95]
	v_mfma_f32_16x16x32_bf16 v[88:91], v[144:147], v[140:143], v[132:135]
	s_waitcnt vmcnt(4)
	ds_write_b128 v131, v[60:63] offset:16512
	global_load_dwordx4 v[60:63], v116, s[54:55] offset:384
	s_waitcnt lgkmcnt(5)
	v_mfma_f32_16x16x32_bf16 v[44:47], v[148:151], v[84:87], v[44:47]
	s_waitcnt lgkmcnt(3)
	v_mfma_f32_16x16x32_bf16 v[40:43], v[148:151], v[104:107], v[40:43]
	s_waitcnt lgkmcnt(2)
	v_mfma_f32_16x16x32_bf16 v[36:39], v[148:151], v[108:111], v[36:39]
	ds_write_b128 v131, v[56:59] offset:18560
	global_load_dwordx4 v[56:59], v120, s[54:55] offset:384
	s_waitcnt lgkmcnt(2)
	v_mfma_f32_16x16x32_bf16 v[32:35], v[148:151], v[112:115], v[32:35]
	v_mfma_f32_16x16x32_bf16 v[28:31], v[152:155], v[84:87], v[28:31]
	v_mfma_f32_16x16x32_bf16 v[24:27], v[152:155], v[104:107], v[24:27]
	v_mfma_f32_16x16x32_bf16 v[20:23], v[152:155], v[108:111], v[20:23]
	ds_write_b128 v131, v[52:55] offset:20608
	global_load_dwordx4 v[52:55], v122, s[54:55] offset:384
	v_mfma_f32_16x16x32_bf16 v[16:19], v[152:155], v[112:115], v[16:19]
	v_mfma_f32_16x16x32_bf16 v[12:15], v[156:159], v[84:87], v[12:15]
	v_mfma_f32_16x16x32_bf16 v[8:11], v[156:159], v[104:107], v[8:11]
	ds_write_b128 v131, v[48:51] offset:22656
	global_load_dwordx4 v[48:51], v124, s[54:55] offset:384
	v_mfma_f32_16x16x32_bf16 v[4:7], v[156:159], v[108:111], v[4:7]
	v_mfma_f32_16x16x32_bf16 v[0:3], v[156:159], v[112:115], v[0:3]
	s_cmp_lt_u32 s11, 12
	s_mov_b32 s6, s11
	s_waitcnt lgkmcnt(0)
	s_barrier
	s_cbranch_scc1 .LBB0_104
	ds_read_b128 v[148:151], v119
	ds_read_b128 v[132:135], v130 offset:16512
	ds_read_b128 v[136:139], v130 offset:17536
	ds_read_b128 v[140:143], v130 offset:18560
	ds_read_b128 v[144:147], v130 offset:19584
	v_mfma_f32_16x16x32_bf16 v[84:87], v[80:83], v[84:87], v[100:103]
	s_add_i32 s11, s6, 2
	s_add_i32 s6, s6, 4
	s_min_u32 s6, s6, 15
	v_mfma_f32_16x16x32_bf16 v[96:99], v[80:83], v[104:107], v[96:99]
	s_lshl_b32 s6, s6, 7
	s_add_u32 s52, s14, s6
	s_addc_u32 s53, s15, 0
	v_mfma_f32_16x16x32_bf16 v[92:95], v[80:83], v[108:111], v[92:95]
	v_mfma_f32_16x16x32_bf16 v[80:83], v[80:83], v[112:115], v[88:91]
	s_waitcnt lgkmcnt(3)
	v_mfma_f32_16x16x32_bf16 v[44:47], v[148:151], v[132:135], v[44:47]
	s_nop 0
	ds_read_b128 v[88:91], v119 offset:1024
	s_waitcnt lgkmcnt(3)
	v_mfma_f32_16x16x32_bf16 v[40:43], v[148:151], v[136:139], v[40:43]
	ds_read_b128 v[100:103], v119 offset:2048
	s_waitcnt lgkmcnt(3)
	v_mfma_f32_16x16x32_bf16 v[36:39], v[148:151], v[140:143], v[36:39]
	ds_read_b128 v[104:107], v119 offset:3072
	s_waitcnt lgkmcnt(3)
	v_mfma_f32_16x16x32_bf16 v[32:35], v[148:151], v[144:147], v[32:35]
	ds_read_b128 v[108:111], v119 offset:8256
	s_waitcnt lgkmcnt(3)
	v_mfma_f32_16x16x32_bf16 v[28:31], v[88:91], v[132:135], v[28:31]
	ds_read_b128 v[112:115], v119 offset:9280
	v_mfma_f32_16x16x32_bf16 v[24:27], v[88:91], v[136:139], v[24:27]
	ds_read_b128 v[148:151], v119 offset:10304
	v_mfma_f32_16x16x32_bf16 v[20:23], v[88:91], v[140:143], v[20:23]
	ds_read_b128 v[152:155], v119 offset:11328
	v_mfma_f32_16x16x32_bf16 v[16:19], v[88:91], v[144:147], v[16:19]
	ds_read_b128 v[88:91], v130 offset:24768
	s_waitcnt lgkmcnt(6)
	v_mfma_f32_16x16x32_bf16 v[12:15], v[100:103], v[132:135], v[12:15]
	ds_read_b128 v[156:159], v130 offset:25792
	v_mfma_f32_16x16x32_bf16 v[8:11], v[100:103], v[136:139], v[8:11]
	ds_read_b128 v[160:163], v130 offset:26816
	v_mfma_f32_16x16x32_bf16 v[4:7], v[100:103], v[140:143], v[4:7]
	ds_read_b128 v[164:167], v130 offset:27840
	v_mfma_f32_16x16x32_bf16 v[0:3], v[100:103], v[144:147], v[0:3]
	s_waitcnt lgkmcnt(8)
; template <int WM, int WN> ...
;     ...
; #pragma unroll
;   for (int n = 0; n < 4; ++n) fb0[n] = LDSF(cur + boff + n * 1024);
; #pragma unroll
;   for (int m = 0; m < 4; ++m) fa0[m] = LDSF(cur + aoff + m * 1024);
;   acc[3][0] = MFMA16(pa, pb0, acc[3][0]);
;   acc[3][1] = MFMA16(pa, pb1, acc[3][1]);
;   acc[3][2] = MFMA16(pa, pb2, acc[3][2]);
;   acc[3][3] = MFMA16(pa, pb3, acc[3][3]);
; #pragma unroll
;   for (int n = 0; n < 4; ++n) acc[0][n] = MFMA16(fa0[0], fb0[n], acc[0][n]);
; #pragma unroll
;   for (int m = 0; m < 4; ++m) fa1[m] = LDSF(cur + aoff + APAN + m * 1024);
; #pragma unroll
;   for (int n = 0; n < 4; ++n) acc[1][n] = MFMA16(fa0[1], fb0[n], acc[1][n]);
; #pragma unroll
;   for (int n = 0; n < 4; ++n) fb1[n] = LDSF(cur + boff + BPAN + n * 1024);
; #pragma unroll
;   for (int n = 0; n < 4; ++n) acc[2][n] = MFMA16(fa0[2], fb0[n], acc[2][n]);
;   *reinterpret_cast<uint4*>(nxt + wao) = a0;
;   *reinterpret_cast<uint4*>(nxt + wao + 32 * 64) = a1;
; #pragma unroll
;   for (int n = 0; n < 4; ++n) acc[3][n] = MFMA16(fa0[3], fb0[n], acc[3][n]);
;   *reinterpret_cast<uint4*>(nxt + wao + 64 * 64) = a2;
;   *reinterpret_cast<uint4*>(nxt + wao + 96 * 64) = a3;
; #pragma unroll
;   for (int n = 0; n < 4; ++n) acc[0][n] = MFMA16(fa1[0], fb1[n], acc[0][n]);
;   *reinterpret_cast<uint4*>(nxt + wbo) = b0;
;   *reinterpret_cast<uint4*>(nxt + wbo + 32 * 64) = b1;
; #pragma unroll
;   for (int n = 0; n < 4; ++n) acc[1][n] = MFMA16(fa1[1], fb1[n], acc[1][n]);
;   *reinterpret_cast<uint4*>(nxt + wbo + 64 * 64) = b2;
;   *reinterpret_cast<uint4*>(nxt + wbo + 96 * 64) = b3;
; #pragma unroll
;   for (int n = 0; n < 4; ++n) acc[2][n] = MFMA16(fa1[2], fb1[n], acc[2][n]);
;   pa = fa1[3];
;   pb0 = fb1[0]; pb1 = fb1[1]; pb2 = fb1[2]; pb3 = fb1[3];
;   SGB_(0x100, 5);
;   SGB_(0x008, 4);
; #pragma unroll
;   for (int i_ = 0; i_ < 11; ++i_) { SGB_(0x008, 1); SGB_(0x100, 1); }
; #pragma unroll
;   for (int i_ = 0; i_ < 8; ++i_) { SGB_(0x008, 2); SGB_(0x200, 1); SGB_(0x020, 1); }
;   SGB_(0x008, 1);
; }
; template <int WM, int WN, typename SrcF, typename PostF>
; __device__ __forceinline__ void gemm_stream(const int nsteps, SrcF src, PostF post, f32x4 (&acc)[WM][WN], char* smem) {
;     ...
;   acc[3][0] = MFMA16(pa, pb0, acc[3][0]);
;   acc[3][1] = MFMA16(pa, pb1, acc[3][1]);
;   acc[3][2] = MFMA16(pa, pb2, acc[3][2]);
;   acc[3][3] = MFMA16(pa, pb3, acc[3][3]);
	v_mfma_f32_16x16x32_bf16 v[84:87], v[104:107], v[132:135], v[84:87]
	s_waitcnt vmcnt(7)
	ds_write_b128 v131, v[76:79] offset:33024
	v_mfma_f32_16x16x32_bf16 v[96:99], v[104:107], v[136:139], v[96:99]
	v_mfma_f32_16x16x32_bf16 v[92:95], v[104:107], v[140:143], v[92:95]
	s_waitcnt vmcnt(6)
	ds_write_b128 v131, v[68:71] offset:35072
	v_mfma_f32_16x16x32_bf16 v[80:83], v[104:107], v[144:147], v[80:83]
	s_waitcnt lgkmcnt(5)
	v_mfma_f32_16x16x32_bf16 v[44:47], v[108:111], v[88:91], v[44:47]
	s_waitcnt vmcnt(5)
	ds_write_b128 v131, v[64:67] offset:37120
	s_add_u32 s52, s20, s6
	s_addc_u32 s53, s21, 0
	s_waitcnt lgkmcnt(5)
	v_mfma_f32_16x16x32_bf16 v[40:43], v[108:111], v[156:159], v[40:43]
	s_min_u32 s6, s11, 12
	s_lshl_b32 s6, s6, 7
	s_waitcnt lgkmcnt(4)
	v_mfma_f32_16x16x32_bf16 v[36:39], v[108:111], v[160:163], v[36:39]
	s_waitcnt vmcnt(4)
	ds_write_b128 v131, v[72:75] offset:39168
	s_waitcnt lgkmcnt(4)
	v_mfma_f32_16x16x32_bf16 v[32:35], v[108:111], v[164:167], v[32:35]
	v_mfma_f32_16x16x32_bf16 v[28:31], v[112:115], v[88:91], v[28:31]
	s_waitcnt vmcnt(3)
	ds_write_b128 v131, v[60:63] offset:49536
	v_mfma_f32_16x16x32_bf16 v[24:27], v[112:115], v[156:159], v[24:27]
	v_mfma_f32_16x16x32_bf16 v[20:23], v[112:115], v[160:163], v[20:23]
	s_waitcnt vmcnt(2)
	ds_write_b128 v131, v[56:59] offset:51584
	v_mfma_f32_16x16x32_bf16 v[16:19], v[112:115], v[164:167], v[16:19]
	v_mfma_f32_16x16x32_bf16 v[12:15], v[148:151], v[88:91], v[12:15]
	s_waitcnt vmcnt(1)
	ds_write_b128 v131, v[52:55] offset:53632
	v_mfma_f32_16x16x32_bf16 v[8:11], v[148:151], v[156:159], v[8:11]
	s_add_u32 s52, s14, s6
	s_addc_u32 s53, s15, 0
	s_add_u32 s54, s20, s6
	v_mfma_f32_16x16x32_bf16 v[4:7], v[148:151], v[160:163], v[4:7]
	s_waitcnt vmcnt(0)
	ds_write_b128 v131, v[48:51] offset:55680
	s_addc_u32 s55, s21, 0
	v_mfma_f32_16x16x32_bf16 v[0:3], v[148:151], v[164:167], v[0:3]
	v_mfma_f32_16x16x32_bf16 v[88:91], v[152:155], v[88:91], v[84:87]
	v_mfma_f32_16x16x32_bf16 v[96:99], v[152:155], v[156:159], v[96:99]
	v_mfma_f32_16x16x32_bf16 v[92:95], v[152:155], v[160:163], v[92:95]
	v_mfma_f32_16x16x32_bf16 v[132:135], v[152:155], v[164:167], v[80:83]
	s_waitcnt lgkmcnt(0)
	s_barrier
	s_nop 0
	ds_read_b128 v[80:83], v119 offset:33024
	ds_read_b128 v[100:103], v130 offset:49536
	ds_read_b128 v[112:115], v130 offset:50560
	ds_read_b128 v[136:139], v130 offset:51584
	ds_read_b128 v[140:143], v130 offset:52608
	s_waitcnt lgkmcnt(3)
	v_mfma_f32_16x16x32_bf16 v[44:47], v[80:83], v[100:103], v[44:47]
	s_waitcnt lgkmcnt(2)
	v_mfma_f32_16x16x32_bf16 v[40:43], v[80:83], v[112:115], v[40:43]
	s_waitcnt lgkmcnt(1)
	v_mfma_f32_16x16x32_bf16 v[36:39], v[80:83], v[136:139], v[36:39]
	s_waitcnt lgkmcnt(0)
	v_mfma_f32_16x16x32_bf16 v[32:35], v[80:83], v[140:143], v[32:35]
	ds_read_b128 v[80:83], v119 offset:34048
	s_waitcnt lgkmcnt(0)
	v_mfma_f32_16x16x32_bf16 v[28:31], v[80:83], v[100:103], v[28:31]
	ds_read_b128 v[104:107], v119 offset:35072
	v_mfma_f32_16x16x32_bf16 v[24:27], v[80:83], v[112:115], v[24:27]
	ds_read_b128 v[144:147], v119 offset:36096
	v_mfma_f32_16x16x32_bf16 v[20:23], v[80:83], v[136:139], v[20:23]
	ds_read_b128 v[148:151], v119 offset:41280
	v_mfma_f32_16x16x32_bf16 v[16:19], v[80:83], v[140:143], v[16:19]
	ds_read_b128 v[152:155], v119 offset:42304
	s_waitcnt lgkmcnt(3)
	v_mfma_f32_16x16x32_bf16 v[12:15], v[104:107], v[100:103], v[12:15]
	ds_read_b128 v[156:159], v119 offset:43328
	v_mfma_f32_16x16x32_bf16 v[8:11], v[104:107], v[112:115], v[8:11]
	ds_read_b128 v[80:83], v119 offset:44352
	v_mfma_f32_16x16x32_bf16 v[4:7], v[104:107], v[136:139], v[4:7]
	ds_read_b128 v[84:87], v130 offset:57792
	v_mfma_f32_16x16x32_bf16 v[0:3], v[104:107], v[140:143], v[0:3]
	ds_read_b128 v[104:107], v130 offset:58816
	s_waitcnt lgkmcnt(6)
	v_mfma_f32_16x16x32_bf16 v[100:103], v[144:147], v[100:103], v[88:91]
	ds_read_b128 v[108:111], v130 offset:59840
	v_mfma_f32_16x16x32_bf16 v[96:99], v[144:147], v[112:115], v[96:99]
	ds_read_b128 v[112:115], v130 offset:60864
	v_mfma_f32_16x16x32_bf16 v[92:95], v[144:147], v[136:139], v[92:95]
	v_mfma_f32_16x16x32_bf16 v[88:91], v[144:147], v[140:143], v[132:135]
	ds_write_b128 v131, v[76:79]
	s_waitcnt lgkmcnt(4)
	v_mfma_f32_16x16x32_bf16 v[44:47], v[148:151], v[84:87], v[44:47]
	s_waitcnt lgkmcnt(3)
	v_mfma_f32_16x16x32_bf16 v[40:43], v[148:151], v[104:107], v[40:43]
	ds_write_b128 v131, v[68:71] offset:2048
	s_waitcnt lgkmcnt(3)
	v_mfma_f32_16x16x32_bf16 v[36:39], v[148:151], v[108:111], v[36:39]
	s_waitcnt lgkmcnt(2)
	v_mfma_f32_16x16x32_bf16 v[32:35], v[148:151], v[112:115], v[32:35]
	ds_write_b128 v131, v[64:67] offset:4096
	v_mfma_f32_16x16x32_bf16 v[28:31], v[152:155], v[84:87], v[28:31]
	v_mfma_f32_16x16x32_bf16 v[24:27], v[152:155], v[104:107], v[24:27]
	ds_write_b128 v131, v[72:75] offset:6144
	v_mfma_f32_16x16x32_bf16 v[20:23], v[152:155], v[108:111], v[20:23]
	v_mfma_f32_16x16x32_bf16 v[16:19], v[152:155], v[112:115], v[16:19]
	ds_write_b128 v131, v[60:63] offset:16512
	v_mfma_f32_16x16x32_bf16 v[12:15], v[156:159], v[84:87], v[12:15]
	v_mfma_f32_16x16x32_bf16 v[8:11], v[156:159], v[104:107], v[8:11]
	ds_write_b128 v131, v[56:59] offset:18560
	v_mfma_f32_16x16x32_bf16 v[4:7], v[156:159], v[108:111], v[4:7]
	v_mfma_f32_16x16x32_bf16 v[0:3], v[156:159], v[112:115], v[0:3]
	ds_write_b128 v131, v[52:55] offset:20608
	ds_write_b128 v131, v[48:51] offset:22656
	s_cmp_lt_u32 s11, 14
	s_mov_b32 s6, s11
	s_waitcnt lgkmcnt(0)
	s_barrier
	s_waitcnt vmcnt(3)
	v_mfma_f32_16x16x32_bf16 v[60:63], v[80:83], v[84:87], v[100:103]
	s_add_i32 s6, s12, -12
	s_cmp_gt_u32 s6, 4
	s_waitcnt vmcnt(2)
	v_mfma_f32_16x16x32_bf16 v[56:59], v[80:83], v[104:107], v[96:99]
	s_waitcnt vmcnt(1)
	v_mfma_f32_16x16x32_bf16 v[52:55], v[80:83], v[108:111], v[92:95]
	s_waitcnt vmcnt(0)
	v_mfma_f32_16x16x32_bf16 v[48:51], v[80:83], v[112:115], v[88:91]
	s_cbranch_scc1 .LBB0_107
; __device__ void phase_inproj(const Params& p, int layer, char* smem) {
;     ...
;     const int row0 = rb * 128 + wr * 64, col0 = cb * 128 + wc * 64;
;     if (cb >= 12 && cb <= 16) {
; #pragma unroll
;       for (int m = 0; m < 4; ++m)
; #pragma unroll
;         for (int j = 0; j < 4; ++j) {
;           int row = row0 + m * 16 + fq * 4 + j;
;           int pos = row & (SEQ - 1);
; #pragma unroll
;           for (int n = 0; n < 2; ++n) {
;             float2 cs2 = RT[pos * 32 + n * 16 + fr];
;             float c = cs2.x, s = cs2.y;
;             float x1 = acc[m][n][j], x2 = acc[m][n + 2][j];
;             acc[m][n][j] = x1 * c - x2 * s;
;             acc[m][n + 2][j] = x2 * c + x1 * s;
;           }
;         }
;     }
	v_lshl_add_u32 v64, s10, 7, v126
	v_and_or_b32 v64, v64, s40, v127
	v_lshl_or_b32 v116, v64, 8, v128
	v_lshl_add_u64 v[92:93], s[8:9], 0, v[116:117]
	v_add_co_u32_e32 v94, vcc, s44, v92
	global_load_dwordx2 v[68:69], v116, s[8:9]
	global_load_dwordx2 v[64:65], v116, s[8:9] offset:256
	global_load_dwordx2 v[66:67], v116, s[8:9] offset:384
	global_load_dwordx2 v[72:73], v116, s[8:9] offset:512
	global_load_dwordx2 v[76:77], v116, s[8:9] offset:128
	global_load_dwordx2 v[74:75], v116, s[8:9] offset:640
	global_load_dwordx2 v[70:71], v116, s[8:9] offset:768
	global_load_dwordx2 v[78:79], v116, s[8:9] offset:896
	v_addc_co_u32_e32 v95, vcc, 0, v93, vcc
	v_add_co_u32_e32 v96, vcc, s45, v92
	s_waitcnt vmcnt(7)
	v_mov_b32_e32 v124, v68
	v_addc_co_u32_e32 v97, vcc, 0, v93, vcc
	global_load_dwordx2 v[82:83], v[96:97], off offset:-4096
	global_load_dwordx2 v[80:81], v[94:95], off offset:256
	global_load_dwordx2 v[84:85], v[94:95], off offset:384
	global_load_dwordx2 v[88:89], v[94:95], off offset:512
	global_load_dwordx2 v[98:99], v[94:95], off offset:128
	global_load_dwordx2 v[90:91], v[94:95], off offset:640
	global_load_dwordx2 v[86:87], v[94:95], off offset:768
	s_waitcnt vmcnt(13)
	v_mov_b32_e32 v125, v64
	v_mov_b32_e32 v64, v69
	s_waitcnt vmcnt(10)
	v_mov_b32_e32 v68, v76
	v_mul_f32_e32 v76, v46, v72
	v_mul_f32_e32 v130, v38, v73
	v_mul_f32_e32 v72, v38, v72
	v_mul_f32_e32 v132, v46, v73
	s_waitcnt vmcnt(9)
	v_mul_f32_e32 v134, v42, v74
	v_mul_f32_e32 v138, v42, v75
	v_mov_b32_e32 v38, v47
	v_mov_b32_e32 v46, v39
	v_mov_b32_e32 v42, v35
	v_add_co_u32_e32 v92, vcc, s46, v92
	v_mov_b32_e32 v69, v66
	v_mov_b32_e32 v66, v77
	v_mul_f32_e32 v136, v34, v75
	v_mul_f32_e32 v74, v34, v74
	v_mov_b32_e32 v34, v43
	v_pk_mul_f32 v[140:141], v[44:45], v[64:65]
	v_pk_mul_f32 v[64:65], v[36:37], v[64:65]
	s_waitcnt vmcnt(8)
	v_pk_mul_f32 v[38:39], v[38:39], v[70:71]
	v_pk_mul_f32 v[46:47], v[46:47], v[70:71]
	s_waitcnt vmcnt(7)
	v_pk_mul_f32 v[42:43], v[42:43], v[78:79]
	v_addc_co_u32_e32 v93, vcc, 0, v93, vcc
	v_pk_mul_f32 v[142:143], v[40:41], v[66:67]
	v_pk_mul_f32 v[66:67], v[32:33], v[66:67]
	v_pk_mul_f32 v[34:35], v[34:35], v[78:79]
	v_mov_b32_e32 v77, v38
	v_mov_b32_e32 v131, v39
	v_pk_fma_f32 v[44:45], v[44:45], v[124:125], v[64:65] neg_lo:[0,0,1] neg_hi:[0,0,1]
	v_mov_b32_e32 v73, v46
	v_mov_b32_e32 v133, v47
	v_mov_b32_e32 v75, v42
	v_mov_b32_e32 v139, v43
	global_load_dwordx2 v[94:95], v[94:95], off offset:896
	s_nop 0
	global_load_dwordx2 v[100:101], v[96:97], off
	global_load_dwordx2 v[102:103], v[96:97], off offset:256
	global_load_dwordx2 v[104:105], v[96:97], off offset:384
	global_load_dwordx2 v[106:107], v[96:97], off offset:128
	global_load_dwordx2 v[108:109], v[96:97], off offset:512
	global_load_dwordx2 v[110:111], v[96:97], off offset:640
	global_load_dwordx2 v[112:113], v[96:97], off offset:768
	s_nop 0
	global_load_dwordx2 v[96:97], v[96:97], off offset:896
	s_nop 0
	global_load_dwordx2 v[114:115], v[92:93], off offset:640
	global_load_dwordx2 v[120:121], v[92:93], off offset:768
	global_load_dwordx2 v[122:123], v[92:93], off offset:896
	v_mov_b32_e32 v135, v34
	v_mov_b32_e32 v137, v35
	v_pk_fma_f32 v[40:41], v[40:41], v[68:69], v[66:67] neg_lo:[0,0,1] neg_hi:[0,0,1]
	v_pk_fma_f32 v[32:33], v[32:33], v[68:69], v[142:143]
	v_pk_add_f32 v[46:47], v[76:77], v[130:131] neg_lo:[0,1] neg_hi:[0,1]
	v_pk_add_f32 v[38:39], v[72:73], v[132:133]
	v_pk_add_f32 v[34:35], v[74:75], v[138:139]
	global_load_dwordx2 v[74:75], v[92:93], off
	global_load_dwordx2 v[76:77], v[92:93], off offset:256
	v_pk_fma_f32 v[36:37], v[36:37], v[124:125], v[140:141]
	v_pk_add_f32 v[42:43], v[134:135], v[136:137] neg_lo:[0,1] neg_hi:[0,1]
	s_waitcnt vmcnt(20)
	v_mov_b32_e32 v64, v82
	s_waitcnt vmcnt(19)
	v_mov_b32_e32 v65, v80
	v_mov_b32_e32 v80, v83
	s_waitcnt vmcnt(18)
	v_mov_b32_e32 v71, v84
	s_waitcnt vmcnt(16)
	v_mov_b32_e32 v84, v99
	v_pk_mul_f32 v[66:67], v[28:29], v[80:81]
	v_pk_mul_f32 v[68:69], v[20:21], v[80:81]
	v_pk_mul_f32 v[72:73], v[24:25], v[84:85]
	v_pk_mul_f32 v[78:79], v[16:17], v[84:85]
	global_load_dwordx2 v[80:81], v[92:93], off offset:384
	global_load_dwordx2 v[82:83], v[92:93], off offset:512
	global_load_dwordx2 v[84:85], v[92:93], off offset:128
	v_mov_b32_e32 v70, v98
	v_mul_f32_e32 v92, v30, v88
	v_mul_f32_e32 v98, v22, v89
	v_mul_f32_e32 v88, v22, v88
	v_mul_f32_e32 v124, v30, v89
	s_waitcnt vmcnt(18)
	v_mul_f32_e32 v130, v26, v90
	v_mul_f32_e32 v132, v18, v91
	v_mul_f32_e32 v90, v18, v90
	v_mul_f32_e32 v134, v26, v91
	v_mov_b32_e32 v22, v31
	v_mov_b32_e32 v30, v23
	v_mov_b32_e32 v18, v27
	v_mov_b32_e32 v26, v19
	s_waitcnt vmcnt(17)
; __device__ void phase_inproj(const Params& p, int layer, char* smem) {
;     ...
; #pragma unroll
;       for (int m = 0; m < 4; ++m)
; #pragma unroll
;         for (int j = 0; j < 4; ++j) {
;           int row = row0 + m * 16 + fq * 4 + j;
;           int pos = row & (SEQ - 1);
; #pragma unroll
;           for (int n = 0; n < 2; ++n) {
;             float2 cs2 = RT[pos * 32 + n * 16 + fr];
;             float c = cs2.x, s = cs2.y;
;             float x1 = acc[m][n][j], x2 = acc[m][n + 2][j];
;             acc[m][n][j] = x1 * c - x2 * s;
;             acc[m][n + 2][j] = x2 * c + x1 * s;
;           }
;         }
	v_pk_mul_f32 v[136:137], v[22:23], v[86:87]
	v_pk_mul_f32 v[22:23], v[30:31], v[86:87]
	v_mov_b32_e32 v93, v136
	v_mov_b32_e32 v89, v22
	v_mov_b32_e32 v125, v23
	v_mov_b32_e32 v99, v137
	v_pk_add_f32 v[22:23], v[88:89], v[124:125]
	v_pk_fma_f32 v[24:25], v[24:25], v[70:71], v[78:79] neg_lo:[0,0,1] neg_hi:[0,0,1]
	v_pk_fma_f32 v[16:17], v[16:17], v[70:71], v[72:73]
	s_waitcnt vmcnt(16)
	v_pk_mul_f32 v[30:31], v[18:19], v[94:95]
	v_pk_mul_f32 v[18:19], v[26:27], v[94:95]
	s_waitcnt vmcnt(14)
	v_mov_b32_e32 v27, v102
	v_mov_b32_e32 v91, v18
	v_mov_b32_e32 v135, v19
	v_pk_add_f32 v[18:19], v[90:91], v[134:135]
	v_mov_b32_e32 v102, v101
	s_waitcnt vmcnt(13)
	v_mov_b32_e32 v71, v104
	s_waitcnt vmcnt(12)
	v_mov_b32_e32 v104, v107
	s_waitcnt vmcnt(11)
	v_mul_f32_e32 v88, v6, v109
	v_mul_f32_e32 v90, v6, v108
	v_mov_b32_e32 v6, v15
	v_pk_fma_f32 v[28:29], v[28:29], v[64:65], v[68:69] neg_lo:[0,0,1] neg_hi:[0,0,1]
	v_pk_add_f32 v[68:69], v[92:93], v[98:99] neg_lo:[0,1] neg_hi:[0,1]
	v_pk_fma_f32 v[20:21], v[20:21], v[64:65], v[66:67]
	v_mov_b32_e32 v26, v100
	v_pk_mul_f32 v[64:65], v[12:13], v[102:103]
	v_pk_mul_f32 v[66:67], v[4:5], v[102:103]
	v_mov_b32_e32 v70, v106
	v_pk_mul_f32 v[72:73], v[8:9], v[104:105]
	v_pk_mul_f32 v[78:79], v[0:1], v[104:105]
	v_mul_f32_e32 v86, v14, v108
	v_mul_f32_e32 v92, v14, v109
	s_waitcnt vmcnt(10)
	v_mul_f32_e32 v94, v10, v110
	v_mul_f32_e32 v98, v2, v111
	v_mul_f32_e32 v100, v2, v110
	v_mul_f32_e32 v102, v10, v111
	s_waitcnt vmcnt(9)
	v_pk_mul_f32 v[104:105], v[6:7], v[112:113]
	v_mov_b32_e32 v14, v7
	v_mov_b32_e32 v2, v11
	v_mov_b32_e32 v10, v3
	v_mov_b32_e32 v87, v104
	v_mov_b32_e32 v89, v105
	v_pk_mul_f32 v[6:7], v[14:15], v[112:113]
	s_waitcnt vmcnt(8)
	v_pk_mul_f32 v[14:15], v[2:3], v[96:97]
	v_pk_fma_f32 v[8:9], v[8:9], v[70:71], v[78:79] neg_lo:[0,0,1] neg_hi:[0,0,1]
	v_pk_mul_f32 v[2:3], v[10:11], v[96:97]
	v_pk_fma_f32 v[0:1], v[0:1], v[70:71], v[72:73]
	s_waitcnt vmcnt(3)
	v_mov_b32_e32 v11, v76
	v_mov_b32_e32 v76, v75
	v_pk_fma_f32 v[12:13], v[12:13], v[26:27], v[66:67] neg_lo:[0,0,1] neg_hi:[0,0,1]
	v_pk_add_f32 v[66:67], v[86:87], v[88:89] neg_lo:[0,1] neg_hi:[0,1]
	v_mov_b32_e32 v91, v6
	v_mov_b32_e32 v93, v7
	v_pk_fma_f32 v[4:5], v[4:5], v[26:27], v[64:65]
	v_mov_b32_e32 v10, v74
	v_pk_mul_f32 v[26:27], v[60:61], v[76:77]
	v_pk_mul_f32 v[64:65], v[52:53], v[76:77]
	v_mul_f32_e32 v86, v50, v115
	v_mul_f32_e32 v88, v50, v114
	v_mov_b32_e32 v50, v59
	v_pk_add_f32 v[6:7], v[90:91], v[92:93]
	v_mul_f32_e32 v90, v58, v115
	v_pk_fma_f32 v[60:61], v[60:61], v[10:11], v[64:65] neg_lo:[0,0,1] neg_hi:[0,0,1]
	v_pk_fma_f32 v[52:53], v[52:53], v[10:11], v[26:27]
	s_waitcnt vmcnt(2)
	v_mov_b32_e32 v71, v80
	s_waitcnt vmcnt(1)
	v_mul_f32_e32 v78, v54, v83
	s_waitcnt vmcnt(0)
	v_mov_b32_e32 v80, v85
	v_pk_mul_f32 v[72:73], v[56:57], v[80:81]
	v_pk_mul_f32 v[74:75], v[48:49], v[80:81]
	v_mul_f32_e32 v80, v54, v82
	v_mov_b32_e32 v54, v63
	v_mov_b32_e32 v70, v84
	v_mul_f32_e32 v76, v62, v82
	v_mul_f32_e32 v82, v62, v83
	v_mul_f32_e32 v84, v58, v114
	v_pk_mul_f32 v[92:93], v[54:55], v[120:121]
	v_mov_b32_e32 v62, v55
	v_pk_mul_f32 v[10:11], v[50:51], v[122:123]
	v_mov_b32_e32 v58, v51
	v_mov_b32_e32 v131, v30
	v_mov_b32_e32 v133, v31
	v_mov_b32_e32 v95, v14
	v_mov_b32_e32 v99, v15
	v_mov_b32_e32 v77, v92
	v_mov_b32_e32 v79, v93
	v_pk_mul_f32 v[54:55], v[62:63], v[120:121]
	v_mov_b32_e32 v85, v10
	v_mov_b32_e32 v87, v11
	v_pk_mul_f32 v[26:27], v[58:59], v[122:123]
	v_pk_add_f32 v[30:31], v[130:131], v[132:133] neg_lo:[0,1] neg_hi:[0,1]
	v_pk_add_f32 v[14:15], v[94:95], v[98:99] neg_lo:[0,1] neg_hi:[0,1]
	v_mov_b32_e32 v101, v2
	v_mov_b32_e32 v103, v3
	v_pk_add_f32 v[64:65], v[76:77], v[78:79] neg_lo:[0,1] neg_hi:[0,1]
	v_mov_b32_e32 v81, v54
	v_mov_b32_e32 v83, v55
	v_pk_add_f32 v[10:11], v[84:85], v[86:87] neg_lo:[0,1] neg_hi:[0,1]
	v_mov_b32_e32 v89, v26
	v_mov_b32_e32 v91, v27
	v_pk_add_f32 v[2:3], v[100:101], v[102:103]
	v_pk_add_f32 v[54:55], v[80:81], v[82:83]
	v_pk_fma_f32 v[56:57], v[56:57], v[70:71], v[74:75] neg_lo:[0,0,1] neg_hi:[0,0,1]
	v_pk_fma_f32 v[48:49], v[48:49], v[70:71], v[72:73]
	v_pk_add_f32 v[50:51], v[88:89], v[90:91]
	v_mov_b32_e32 v58, v10
	v_mov_b32_e32 v59, v11
	v_mov_b32_e32 v62, v64
	v_mov_b32_e32 v63, v65
	v_mov_b32_e32 v10, v14
	v_mov_b32_e32 v11, v15
	v_mov_b32_e32 v14, v66
	v_mov_b32_e32 v15, v67
	v_mov_b32_e32 v26, v30
	v_mov_b32_e32 v27, v31
	v_mov_b32_e32 v30, v68
	v_mov_b32_e32 v31, v69

; #define MFMA16(a, b, c) __builtin_amdgcn_mfma_f32_16x16x32_bf16(a, b, c, 0, 0, 0)
; template <int WM, int WN> ...
;     ...
; #pragma unroll
;   for (int n = 0; n < 4; ++n) fb0[n] = LDSF(cur + boff + n * 1024);
; #pragma unroll
;   for (int m = 0; m < 4; ++m) fa0[m] = LDSF(cur + aoff + m * 1024);
;   acc[3][0] = MFMA16(pa, pb0, acc[3][0]);
;   acc[3][1] = MFMA16(pa, pb1, acc[3][1]);
;   acc[3][2] = MFMA16(pa, pb2, acc[3][2]);
;   acc[3][3] = MFMA16(pa, pb3, acc[3][3]);
; #pragma unroll
;   for (int n = 0; n < 4; ++n) acc[0][n] = MFMA16(fa0[0], fb0[n], acc[0][n]);
; #pragma unroll
;   for (int m = 0; m < 4; ++m) fa1[m] = LDSF(cur + aoff + APAN + m * 1024);
; #pragma unroll
;   for (int n = 0; n < 4; ++n) acc[1][n] = MFMA16(fa0[1], fb0[n], acc[1][n]);
; #pragma unroll
;   for (int n = 0; n < 4; ++n) fb1[n] = LDSF(cur + boff + BPAN + n * 1024);
; #pragma unroll
;   for (int n = 0; n < 4; ++n) acc[2][n] = MFMA16(fa0[2], fb0[n], acc[2][n]);
;   *reinterpret_cast<uint4*>(nxt + wao) = a0;
;   *reinterpret_cast<uint4*>(nxt + wao + 32 * 64) = a1;
; #pragma unroll
;   for (int n = 0; n < 4; ++n) acc[3][n] = MFMA16(fa0[3], fb0[n], acc[3][n]);
;   *reinterpret_cast<uint4*>(nxt + wao + 64 * 64) = a2;
;   *reinterpret_cast<uint4*>(nxt + wao + 96 * 64) = a3;
; #pragma unroll
;   for (int n = 0; n < 4; ++n) acc[0][n] = MFMA16(fa1[0], fb1[n], acc[0][n]);
;   *reinterpret_cast<uint4*>(nxt + wbo) = b0;
;   *reinterpret_cast<uint4*>(nxt + wbo + 32 * 64) = b1;
; #pragma unroll
;   for (int n = 0; n < 4; ++n) acc[1][n] = MFMA16(fa1[1], fb1[n], acc[1][n]);
;   *reinterpret_cast<uint4*>(nxt + wbo + 64 * 64) = b2;
;   *reinterpret_cast<uint4*>(nxt + wbo + 96 * 64) = b3;
; #pragma unroll
;   for (int n = 0; n < 4; ++n) acc[2][n] = MFMA16(fa1[2], fb1[n], acc[2][n]);
;   pa = fa1[3];
;   pb0 = fb1[0]; pb1 = fb1[1]; pb2 = fb1[2]; pb3 = fb1[3];
.LBB0_318:
	s_add_i32 s44, s7, 2
	s_add_i32 s7, s7, 4
	s_min_u32 s7, s7, 15
	s_lshl_b32 s7, s7, 7
	s_add_u32 s92, s10, s7
	s_addc_u32 s93, s11, 0
	s_add_u32 s94, s12, s7
	s_addc_u32 s95, s13, 0
	ds_read_b128 v[144:147], v124
	ds_read_b128 v[128:131], v125 offset:16512
	ds_read_b128 v[132:135], v125 offset:17536
	ds_read_b128 v[136:139], v125 offset:18560
	ds_read_b128 v[140:143], v125 offset:19584
	v_mfma_f32_16x16x32_bf16 v[64:67], v[48:51], v[64:67], v[92:95]
	v_mfma_f32_16x16x32_bf16 v[88:91], v[48:51], v[104:107], v[88:91]
	s_waitcnt vmcnt(4)
	ds_write_b128 v126, v[32:35] offset:33024
	global_load_dwordx4 v[32:35], v116, s[92:93]
	s_add_u32 s48, s10, s7
	s_addc_u32 s49, s11, 0
	v_mfma_f32_16x16x32_bf16 v[80:83], v[48:51], v[112:115], v[80:83]
	v_mfma_f32_16x16x32_bf16 v[48:51], v[48:51], v[108:111], v[56:59]
	s_waitcnt lgkmcnt(4)
	v_mfma_f32_16x16x32_bf16 v[56:59], v[144:147], v[128:131], v[100:103]
	ds_read_b128 v[92:95], v124 offset:1024
	s_waitcnt lgkmcnt(4)
	v_mfma_f32_16x16x32_bf16 v[96:99], v[144:147], v[132:135], v[96:99]
	ds_write_b128 v126, v[20:23] offset:35072
	global_load_dwordx4 v[20:23], v118, s[92:93]
	ds_read_b128 v[100:103], v124 offset:2048
	s_waitcnt lgkmcnt(5)
	v_mfma_f32_16x16x32_bf16 v[84:87], v[144:147], v[136:139], v[84:87]
	ds_read_b128 v[104:107], v124 offset:3072
	s_waitcnt lgkmcnt(5)
	v_mfma_f32_16x16x32_bf16 v[76:79], v[144:147], v[140:143], v[76:79]
	ds_read_b128 v[108:111], v124 offset:8256
	s_waitcnt lgkmcnt(4)
	v_mfma_f32_16x16x32_bf16 v[72:75], v[92:95], v[128:131], v[72:75]
	ds_read_b128 v[112:115], v124 offset:9280
	v_mfma_f32_16x16x32_bf16 v[68:71], v[92:95], v[132:135], v[68:71]
	ds_read_b128 v[144:147], v124 offset:10304
	v_mfma_f32_16x16x32_bf16 v[60:63], v[92:95], v[136:139], v[60:63]
	ds_write_b128 v126, v[16:19] offset:37120
	global_load_dwordx4 v[16:19], v120, s[92:93]
	ds_read_b128 v[148:151], v124 offset:11328
	v_mfma_f32_16x16x32_bf16 v[52:55], v[92:95], v[140:143], v[52:55]
	ds_read_b128 v[92:95], v125 offset:24768
	s_waitcnt lgkmcnt(7)
	v_mfma_f32_16x16x32_bf16 v[44:47], v[100:103], v[128:131], v[44:47]
	ds_read_b128 v[152:155], v125 offset:25792
	v_mfma_f32_16x16x32_bf16 v[40:43], v[100:103], v[132:135], v[40:43]
	ds_read_b128 v[156:159], v125 offset:26816
	v_mfma_f32_16x16x32_bf16 v[36:39], v[100:103], v[136:139], v[36:39]
	ds_write_b128 v126, v[24:27] offset:39168
	global_load_dwordx4 v[24:27], v122, s[92:93]
	ds_read_b128 v[160:163], v125 offset:27840
	v_mfma_f32_16x16x32_bf16 v[28:31], v[100:103], v[140:143], v[28:31]
	s_waitcnt lgkmcnt(10)
	v_mfma_f32_16x16x32_bf16 v[64:67], v[104:107], v[128:131], v[64:67]
	v_mfma_f32_16x16x32_bf16 v[88:91], v[104:107], v[132:135], v[88:91]
	v_mfma_f32_16x16x32_bf16 v[80:83], v[104:107], v[136:139], v[80:83]
	v_mfma_f32_16x16x32_bf16 v[48:51], v[104:107], v[140:143], v[48:51]
	s_waitcnt vmcnt(4)
	ds_write_b128 v126, v[12:15] offset:49536
	global_load_dwordx4 v[12:15], v116, s[94:95]
	s_waitcnt lgkmcnt(5)
	v_mfma_f32_16x16x32_bf16 v[56:59], v[108:111], v[92:95], v[56:59]
	s_add_u32 s48, s12, s7
	s_addc_u32 s49, s13, 0
	s_waitcnt lgkmcnt(4)
	v_mfma_f32_16x16x32_bf16 v[96:99], v[108:111], v[152:155], v[96:99]
	s_min_u32 s7, s44, 12
	s_lshl_b32 s7, s7, 7
	s_waitcnt lgkmcnt(3)
	v_mfma_f32_16x16x32_bf16 v[84:87], v[108:111], v[156:159], v[84:87]
	s_waitcnt lgkmcnt(1)
	v_mfma_f32_16x16x32_bf16 v[76:79], v[108:111], v[160:163], v[76:79]
	ds_write_b128 v126, v[8:11] offset:51584
	global_load_dwordx4 v[8:11], v118, s[94:95]
	v_mfma_f32_16x16x32_bf16 v[72:75], v[112:115], v[92:95], v[72:75]
	v_mfma_f32_16x16x32_bf16 v[68:71], v[112:115], v[152:155], v[68:71]
	v_mfma_f32_16x16x32_bf16 v[60:63], v[112:115], v[156:159], v[60:63]
	v_mfma_f32_16x16x32_bf16 v[52:55], v[112:115], v[160:163], v[52:55]
	v_mfma_f32_16x16x32_bf16 v[44:47], v[144:147], v[92:95], v[44:47]
	ds_write_b128 v126, v[4:7] offset:53632
	global_load_dwordx4 v[4:7], v120, s[94:95]
	v_mfma_f32_16x16x32_bf16 v[40:43], v[144:147], v[152:155], v[40:43]
	s_add_u32 s48, s10, s7
	s_addc_u32 s49, s11, 0
	s_add_u32 s50, s12, s7
	v_mfma_f32_16x16x32_bf16 v[36:39], v[144:147], v[156:159], v[36:39]
	s_addc_u32 s51, s13, 0
	v_mfma_f32_16x16x32_bf16 v[28:31], v[144:147], v[160:163], v[28:31]
	v_mfma_f32_16x16x32_bf16 v[92:95], v[148:151], v[92:95], v[64:67]
	ds_write_b128 v126, v[0:3] offset:55680
	global_load_dwordx4 v[0:3], v122, s[94:95]
	v_mfma_f32_16x16x32_bf16 v[88:91], v[148:151], v[152:155], v[88:91]
	v_mfma_f32_16x16x32_bf16 v[80:83], v[148:151], v[156:159], v[80:83]
	v_mfma_f32_16x16x32_bf16 v[100:103], v[148:151], v[160:163], v[48:51]
	s_waitcnt lgkmcnt(0)
	s_barrier
; template <int WM, int WN> ...
;     ...
; #pragma unroll
;   for (int n = 0; n < 4; ++n) fb0[n] = LDSF(cur + boff + n * 1024);
; #pragma unroll
;   for (int m = 0; m < 4; ++m) fa0[m] = LDSF(cur + aoff + m * 1024);
;   acc[3][0] = MFMA16(pa, pb0, acc[3][0]);
;   acc[3][1] = MFMA16(pa, pb1, acc[3][1]);
;   acc[3][2] = MFMA16(pa, pb2, acc[3][2]);
;   acc[3][3] = MFMA16(pa, pb3, acc[3][3]);
; #pragma unroll
;   for (int n = 0; n < 4; ++n) acc[0][n] = MFMA16(fa0[0], fb0[n], acc[0][n]);
; #pragma unroll
;   for (int m = 0; m < 4; ++m) fa1[m] = LDSF(cur + aoff + APAN + m * 1024);
; #pragma unroll
;   for (int n = 0; n < 4; ++n) acc[1][n] = MFMA16(fa0[1], fb0[n], acc[1][n]);
; #pragma unroll
;   for (int n = 0; n < 4; ++n) fb1[n] = LDSF(cur + boff + BPAN + n * 1024);
; #pragma unroll
;   for (int n = 0; n < 4; ++n) acc[2][n] = MFMA16(fa0[2], fb0[n], acc[2][n]);
;   *reinterpret_cast<uint4*>(nxt + wao) = a0;
;   *reinterpret_cast<uint4*>(nxt + wao + 32 * 64) = a1;
; #pragma unroll
;   for (int n = 0; n < 4; ++n) acc[3][n] = MFMA16(fa0[3], fb0[n], acc[3][n]);
;   *reinterpret_cast<uint4*>(nxt + wao + 64 * 64) = a2;
;   *reinterpret_cast<uint4*>(nxt + wao + 96 * 64) = a3;
; #pragma unroll
;   for (int n = 0; n < 4; ++n) acc[0][n] = MFMA16(fa1[0], fb1[n], acc[0][n]);
;   *reinterpret_cast<uint4*>(nxt + wbo) = b0;
;   *reinterpret_cast<uint4*>(nxt + wbo + 32 * 64) = b1;
; #pragma unroll
;   for (int n = 0; n < 4; ++n) acc[1][n] = MFMA16(fa1[1], fb1[n], acc[1][n]);
;   *reinterpret_cast<uint4*>(nxt + wbo + 64 * 64) = b2;
;   *reinterpret_cast<uint4*>(nxt + wbo + 96 * 64) = b3;
; #pragma unroll
;   for (int n = 0; n < 4; ++n) acc[2][n] = MFMA16(fa1[2], fb1[n], acc[2][n]);
;   pa = fa1[3];
;   pb0 = fb1[0]; pb1 = fb1[1]; pb2 = fb1[2]; pb3 = fb1[3];
;   SGB_(0x100, 5);
;   SGB_(0x008, 4);
; #pragma unroll
;   for (int i_ = 0; i_ < 11; ++i_) { SGB_(0x008, 1); SGB_(0x100, 1); }
; #pragma unroll
;   for (int i_ = 0; i_ < 8; ++i_) { SGB_(0x008, 2); SGB_(0x200, 1); SGB_(0x020, 1); }
;   SGB_(0x008, 1);
; }
; template <int WM, int WN, typename SrcF, typename PostF>
; __device__ __forceinline__ void gemm_stream(const int nsteps, SrcF src, PostF post, f32x4 (&acc)[WM][WN], char* smem) {
;     ...
;       TileSrc s = src(min(kt + 3, nsteps - 1));
;       GLOAD_TILE(ya, s.a, s.lda, ACH);
;       GLOAD_TILE(yb, s.b, s.ldb, BCH);
;     }
	s_nop 0
	ds_read_b128 v[48:51], v124 offset:33024
	ds_read_b128 v[108:111], v125 offset:49536
	ds_read_b128 v[128:131], v125 offset:50560
	ds_read_b128 v[132:135], v125 offset:51584
	ds_read_b128 v[136:139], v125 offset:52608
	s_waitcnt lgkmcnt(3)
	v_mfma_f32_16x16x32_bf16 v[140:143], v[48:51], v[108:111], v[56:59]
	s_waitcnt lgkmcnt(2)
	v_mfma_f32_16x16x32_bf16 v[96:99], v[48:51], v[128:131], v[96:99]
	s_waitcnt vmcnt(4)
	ds_write_b128 v126, v[32:35]
	global_load_dwordx4 v[32:35], v116, s[48:49] offset:384
	s_waitcnt lgkmcnt(2)
	v_mfma_f32_16x16x32_bf16 v[84:87], v[48:51], v[132:135], v[84:87]
	s_waitcnt lgkmcnt(0)
	v_mfma_f32_16x16x32_bf16 v[76:79], v[48:51], v[136:139], v[76:79]
	ds_read_b128 v[48:51], v124 offset:34048
	s_waitcnt lgkmcnt(0)
	v_mfma_f32_16x16x32_bf16 v[72:75], v[48:51], v[108:111], v[72:75]
	ds_write_b128 v126, v[20:23] offset:2048
	global_load_dwordx4 v[20:23], v118, s[48:49] offset:384
	ds_read_b128 v[56:59], v124 offset:35072
	v_mfma_f32_16x16x32_bf16 v[68:71], v[48:51], v[128:131], v[68:71]
	ds_read_b128 v[144:147], v124 offset:36096
	v_mfma_f32_16x16x32_bf16 v[60:63], v[48:51], v[132:135], v[60:63]
	ds_read_b128 v[148:151], v124 offset:41280
	v_mfma_f32_16x16x32_bf16 v[52:55], v[48:51], v[136:139], v[52:55]
	ds_read_b128 v[152:155], v124 offset:42304
	s_waitcnt lgkmcnt(3)
	v_mfma_f32_16x16x32_bf16 v[44:47], v[56:59], v[108:111], v[44:47]
	ds_write_b128 v126, v[16:19] offset:4096
	global_load_dwordx4 v[16:19], v120, s[48:49] offset:384
	ds_read_b128 v[156:159], v124 offset:43328
	v_mfma_f32_16x16x32_bf16 v[40:43], v[56:59], v[128:131], v[40:43]
	ds_read_b128 v[48:51], v124 offset:44352
	v_mfma_f32_16x16x32_bf16 v[36:39], v[56:59], v[132:135], v[36:39]
	ds_read_b128 v[64:67], v125 offset:57792
	v_mfma_f32_16x16x32_bf16 v[28:31], v[56:59], v[136:139], v[28:31]
	ds_write_b128 v126, v[24:27] offset:6144
	global_load_dwordx4 v[24:27], v122, s[48:49] offset:384
	ds_read_b128 v[104:107], v125 offset:58816
	s_waitcnt lgkmcnt(8)
	v_mfma_f32_16x16x32_bf16 v[92:95], v[144:147], v[108:111], v[92:95]
	ds_read_b128 v[112:115], v125 offset:59840
	v_mfma_f32_16x16x32_bf16 v[88:91], v[144:147], v[128:131], v[88:91]
	ds_read_b128 v[108:111], v125 offset:60864
	v_mfma_f32_16x16x32_bf16 v[80:83], v[144:147], v[132:135], v[80:83]
	v_mfma_f32_16x16x32_bf16 v[56:59], v[144:147], v[136:139], v[100:103]
	s_waitcnt vmcnt(4)
	ds_write_b128 v126, v[12:15] offset:16512
	global_load_dwordx4 v[12:15], v116, s[50:51] offset:384
	s_waitcnt lgkmcnt(5)
	v_mfma_f32_16x16x32_bf16 v[100:103], v[148:151], v[64:67], v[140:143]
	s_waitcnt lgkmcnt(3)
	v_mfma_f32_16x16x32_bf16 v[96:99], v[148:151], v[104:107], v[96:99]
	s_waitcnt lgkmcnt(2)
	v_mfma_f32_16x16x32_bf16 v[84:87], v[148:151], v[112:115], v[84:87]
	ds_write_b128 v126, v[8:11] offset:18560
	global_load_dwordx4 v[8:11], v118, s[50:51] offset:384
	s_waitcnt lgkmcnt(2)
	v_mfma_f32_16x16x32_bf16 v[76:79], v[148:151], v[108:111], v[76:79]
	v_mfma_f32_16x16x32_bf16 v[72:75], v[152:155], v[64:67], v[72:75]
	v_mfma_f32_16x16x32_bf16 v[68:71], v[152:155], v[104:107], v[68:71]
	v_mfma_f32_16x16x32_bf16 v[60:63], v[152:155], v[112:115], v[60:63]
	ds_write_b128 v126, v[4:7] offset:20608
	global_load_dwordx4 v[4:7], v120, s[50:51] offset:384
	v_mfma_f32_16x16x32_bf16 v[52:55], v[152:155], v[108:111], v[52:55]
	v_mfma_f32_16x16x32_bf16 v[44:47], v[156:159], v[64:67], v[44:47]
	v_mfma_f32_16x16x32_bf16 v[40:43], v[156:159], v[104:107], v[40:43]
	ds_write_b128 v126, v[0:3] offset:22656
	global_load_dwordx4 v[0:3], v122, s[50:51] offset:384
	v_mfma_f32_16x16x32_bf16 v[36:39], v[156:159], v[112:115], v[36:39]
	v_mfma_f32_16x16x32_bf16 v[28:31], v[156:159], v[108:111], v[28:31]
	s_cmp_lt_u32 s44, 12
	s_mov_b32 s7, s44
	s_waitcnt lgkmcnt(0)
	s_barrier
	s_cbranch_scc1 .LBB0_318
	ds_read_b128 v[144:147], v124
	ds_read_b128 v[128:131], v125 offset:16512
	ds_read_b128 v[132:135], v125 offset:17536
	ds_read_b128 v[136:139], v125 offset:18560
	ds_read_b128 v[140:143], v125 offset:19584
	v_mfma_f32_16x16x32_bf16 v[64:67], v[48:51], v[64:67], v[92:95]
	s_add_i32 s44, s7, 2
	s_add_i32 s7, s7, 4
	s_min_u32 s7, s7, 15
	v_mfma_f32_16x16x32_bf16 v[88:91], v[48:51], v[104:107], v[88:91]
	s_lshl_b32 s7, s7, 7
	s_add_u32 s48, s10, s7
	s_addc_u32 s49, s11, 0
	v_mfma_f32_16x16x32_bf16 v[80:83], v[48:51], v[112:115], v[80:83]
	v_mfma_f32_16x16x32_bf16 v[48:51], v[48:51], v[108:111], v[56:59]
	s_waitcnt lgkmcnt(3)
	v_mfma_f32_16x16x32_bf16 v[56:59], v[144:147], v[128:131], v[100:103]
	ds_read_b128 v[92:95], v124 offset:1024
	s_waitcnt lgkmcnt(3)
	v_mfma_f32_16x16x32_bf16 v[96:99], v[144:147], v[132:135], v[96:99]
	ds_read_b128 v[100:103], v124 offset:2048
	s_waitcnt lgkmcnt(3)
	v_mfma_f32_16x16x32_bf16 v[84:87], v[144:147], v[136:139], v[84:87]
	ds_read_b128 v[104:107], v124 offset:3072
	s_waitcnt lgkmcnt(3)
	v_mfma_f32_16x16x32_bf16 v[76:79], v[144:147], v[140:143], v[76:79]
	ds_read_b128 v[108:111], v124 offset:8256
	s_waitcnt lgkmcnt(3)
	v_mfma_f32_16x16x32_bf16 v[72:75], v[92:95], v[128:131], v[72:75]
	ds_read_b128 v[112:115], v124 offset:9280
	v_mfma_f32_16x16x32_bf16 v[68:71], v[92:95], v[132:135], v[68:71]
	ds_read_b128 v[144:147], v124 offset:10304
	v_mfma_f32_16x16x32_bf16 v[60:63], v[92:95], v[136:139], v[60:63]
	ds_read_b128 v[148:151], v124 offset:11328
	v_mfma_f32_16x16x32_bf16 v[52:55], v[92:95], v[140:143], v[52:55]
	ds_read_b128 v[92:95], v125 offset:24768
	s_waitcnt lgkmcnt(6)
	v_mfma_f32_16x16x32_bf16 v[44:47], v[100:103], v[128:131], v[44:47]
	ds_read_b128 v[152:155], v125 offset:25792
	v_mfma_f32_16x16x32_bf16 v[40:43], v[100:103], v[132:135], v[40:43]
	ds_read_b128 v[156:159], v125 offset:26816
	v_mfma_f32_16x16x32_bf16 v[36:39], v[100:103], v[136:139], v[36:39]
	ds_read_b128 v[160:163], v125 offset:27840
	v_mfma_f32_16x16x32_bf16 v[28:31], v[100:103], v[140:143], v[28:31]
	s_waitcnt lgkmcnt(8)
; template <int WM, int WN> ...
;     ...
; #pragma unroll
;   for (int n = 0; n < 4; ++n) fb0[n] = LDSF(cur + boff + n * 1024);
; #pragma unroll
;   for (int m = 0; m < 4; ++m) fa0[m] = LDSF(cur + aoff + m * 1024);
;   acc[3][0] = MFMA16(pa, pb0, acc[3][0]);
;   acc[3][1] = MFMA16(pa, pb1, acc[3][1]);
;   acc[3][2] = MFMA16(pa, pb2, acc[3][2]);
;   acc[3][3] = MFMA16(pa, pb3, acc[3][3]);
; #pragma unroll
;   for (int n = 0; n < 4; ++n) acc[0][n] = MFMA16(fa0[0], fb0[n], acc[0][n]);
; #pragma unroll
;   for (int m = 0; m < 4; ++m) fa1[m] = LDSF(cur + aoff + APAN + m * 1024);
; #pragma unroll
;   for (int n = 0; n < 4; ++n) acc[1][n] = MFMA16(fa0[1], fb0[n], acc[1][n]);
; #pragma unroll
;   for (int n = 0; n < 4; ++n) fb1[n] = LDSF(cur + boff + BPAN + n * 1024);
; #pragma unroll
;   for (int n = 0; n < 4; ++n) acc[2][n] = MFMA16(fa0[2], fb0[n], acc[2][n]);
;   *reinterpret_cast<uint4*>(nxt + wao) = a0;
;   *reinterpret_cast<uint4*>(nxt + wao + 32 * 64) = a1;
; #pragma unroll
;   for (int n = 0; n < 4; ++n) acc[3][n] = MFMA16(fa0[3], fb0[n], acc[3][n]);
;   *reinterpret_cast<uint4*>(nxt + wao + 64 * 64) = a2;
;   *reinterpret_cast<uint4*>(nxt + wao + 96 * 64) = a3;
; #pragma unroll
;   for (int n = 0; n < 4; ++n) acc[0][n] = MFMA16(fa1[0], fb1[n], acc[0][n]);
;   *reinterpret_cast<uint4*>(nxt + wbo) = b0;
;   *reinterpret_cast<uint4*>(nxt + wbo + 32 * 64) = b1;
; #pragma unroll
;   for (int n = 0; n < 4; ++n) acc[1][n] = MFMA16(fa1[1], fb1[n], acc[1][n]);
;   *reinterpret_cast<uint4*>(nxt + wbo + 64 * 64) = b2;
;   *reinterpret_cast<uint4*>(nxt + wbo + 96 * 64) = b3;
; #pragma unroll
;   for (int n = 0; n < 4; ++n) acc[2][n] = MFMA16(fa1[2], fb1[n], acc[2][n]);
;   pa = fa1[3];
;   pb0 = fb1[0]; pb1 = fb1[1]; pb2 = fb1[2]; pb3 = fb1[3];
;   SGB_(0x100, 5);
;   SGB_(0x008, 4);
; #pragma unroll
;   for (int i_ = 0; i_ < 11; ++i_) { SGB_(0x008, 1); SGB_(0x100, 1); }
; #pragma unroll
;   for (int i_ = 0; i_ < 8; ++i_) { SGB_(0x008, 2); SGB_(0x200, 1); SGB_(0x020, 1); }
;   SGB_(0x008, 1);
; }
; template <int WM, int WN, typename SrcF, typename PostF>
; __device__ __forceinline__ void gemm_stream(const int nsteps, SrcF src, PostF post, f32x4 (&acc)[WM][WN], char* smem) {
;     ...
;   acc[3][0] = MFMA16(pa, pb0, acc[3][0]);
;   acc[3][1] = MFMA16(pa, pb1, acc[3][1]);
;   acc[3][2] = MFMA16(pa, pb2, acc[3][2]);
;   acc[3][3] = MFMA16(pa, pb3, acc[3][3]);
	v_mfma_f32_16x16x32_bf16 v[64:67], v[104:107], v[128:131], v[64:67]
	s_waitcnt vmcnt(7)
	ds_write_b128 v126, v[32:35] offset:33024
	v_mfma_f32_16x16x32_bf16 v[88:91], v[104:107], v[132:135], v[88:91]
	v_mfma_f32_16x16x32_bf16 v[80:83], v[104:107], v[136:139], v[80:83]
	s_waitcnt vmcnt(6)
	ds_write_b128 v126, v[20:23] offset:35072
	v_mfma_f32_16x16x32_bf16 v[48:51], v[104:107], v[140:143], v[48:51]
	s_waitcnt lgkmcnt(5)
	v_mfma_f32_16x16x32_bf16 v[56:59], v[108:111], v[92:95], v[56:59]
	s_waitcnt vmcnt(5)
	ds_write_b128 v126, v[16:19] offset:37120
	s_add_u32 s48, s12, s7
	s_addc_u32 s49, s13, 0
	s_waitcnt lgkmcnt(5)
	v_mfma_f32_16x16x32_bf16 v[96:99], v[108:111], v[152:155], v[96:99]
	s_min_u32 s7, s44, 12
	s_lshl_b32 s7, s7, 7
	s_waitcnt lgkmcnt(4)
	v_mfma_f32_16x16x32_bf16 v[84:87], v[108:111], v[156:159], v[84:87]
	s_waitcnt vmcnt(4)
	ds_write_b128 v126, v[24:27] offset:39168
	s_waitcnt lgkmcnt(4)
	v_mfma_f32_16x16x32_bf16 v[76:79], v[108:111], v[160:163], v[76:79]
	v_mfma_f32_16x16x32_bf16 v[72:75], v[112:115], v[92:95], v[72:75]
	s_waitcnt vmcnt(3)
	ds_write_b128 v126, v[12:15] offset:49536
	v_mfma_f32_16x16x32_bf16 v[68:71], v[112:115], v[152:155], v[68:71]
	v_mfma_f32_16x16x32_bf16 v[60:63], v[112:115], v[156:159], v[60:63]
	s_waitcnt vmcnt(2)
	ds_write_b128 v126, v[8:11] offset:51584
	v_mfma_f32_16x16x32_bf16 v[52:55], v[112:115], v[160:163], v[52:55]
	v_mfma_f32_16x16x32_bf16 v[44:47], v[144:147], v[92:95], v[44:47]
	s_waitcnt vmcnt(1)
	ds_write_b128 v126, v[4:7] offset:53632
	v_mfma_f32_16x16x32_bf16 v[40:43], v[144:147], v[152:155], v[40:43]
	s_add_u32 s48, s10, s7
	s_addc_u32 s49, s11, 0
	s_add_u32 s50, s12, s7
	v_mfma_f32_16x16x32_bf16 v[36:39], v[144:147], v[156:159], v[36:39]
	s_waitcnt vmcnt(0)
	ds_write_b128 v126, v[0:3] offset:55680
	s_addc_u32 s51, s13, 0
	v_mfma_f32_16x16x32_bf16 v[28:31], v[144:147], v[160:163], v[28:31]
	v_mfma_f32_16x16x32_bf16 v[92:95], v[148:151], v[92:95], v[64:67]
	v_mfma_f32_16x16x32_bf16 v[88:91], v[148:151], v[152:155], v[88:91]
	v_mfma_f32_16x16x32_bf16 v[80:83], v[148:151], v[156:159], v[80:83]
	v_mfma_f32_16x16x32_bf16 v[100:103], v[148:151], v[160:163], v[48:51]
	s_waitcnt lgkmcnt(0)
	s_barrier
	s_nop 0
	ds_read_b128 v[48:51], v124 offset:33024
	ds_read_b128 v[108:111], v125 offset:49536
	ds_read_b128 v[128:131], v125 offset:50560
	ds_read_b128 v[132:135], v125 offset:51584
	ds_read_b128 v[136:139], v125 offset:52608
	s_waitcnt lgkmcnt(3)
	v_mfma_f32_16x16x32_bf16 v[140:143], v[48:51], v[108:111], v[56:59]
	s_waitcnt lgkmcnt(2)
	v_mfma_f32_16x16x32_bf16 v[96:99], v[48:51], v[128:131], v[96:99]
	s_waitcnt lgkmcnt(1)
	v_mfma_f32_16x16x32_bf16 v[84:87], v[48:51], v[132:135], v[84:87]
	s_waitcnt lgkmcnt(0)
	v_mfma_f32_16x16x32_bf16 v[76:79], v[48:51], v[136:139], v[76:79]
	ds_read_b128 v[48:51], v124 offset:34048
	s_waitcnt lgkmcnt(0)
	v_mfma_f32_16x16x32_bf16 v[72:75], v[48:51], v[108:111], v[72:75]
	ds_read_b128 v[56:59], v124 offset:35072
	v_mfma_f32_16x16x32_bf16 v[68:71], v[48:51], v[128:131], v[68:71]
	ds_read_b128 v[144:147], v124 offset:36096
	v_mfma_f32_16x16x32_bf16 v[60:63], v[48:51], v[132:135], v[60:63]
	ds_read_b128 v[148:151], v124 offset:41280
	v_mfma_f32_16x16x32_bf16 v[52:55], v[48:51], v[136:139], v[52:55]
	ds_read_b128 v[152:155], v124 offset:42304
	s_waitcnt lgkmcnt(3)
	v_mfma_f32_16x16x32_bf16 v[44:47], v[56:59], v[108:111], v[44:47]
	ds_read_b128 v[156:159], v124 offset:43328
	v_mfma_f32_16x16x32_bf16 v[40:43], v[56:59], v[128:131], v[40:43]
	ds_read_b128 v[48:51], v124 offset:44352
	v_mfma_f32_16x16x32_bf16 v[36:39], v[56:59], v[132:135], v[36:39]
	ds_read_b128 v[64:67], v125 offset:57792
	v_mfma_f32_16x16x32_bf16 v[28:31], v[56:59], v[136:139], v[28:31]
	ds_read_b128 v[104:107], v125 offset:58816
	s_waitcnt lgkmcnt(6)
	v_mfma_f32_16x16x32_bf16 v[92:95], v[144:147], v[108:111], v[92:95]
	ds_read_b128 v[112:115], v125 offset:59840
	v_mfma_f32_16x16x32_bf16 v[88:91], v[144:147], v[128:131], v[88:91]
	ds_read_b128 v[108:111], v125 offset:60864
	v_mfma_f32_16x16x32_bf16 v[80:83], v[144:147], v[132:135], v[80:83]
	v_mfma_f32_16x16x32_bf16 v[56:59], v[144:147], v[136:139], v[100:103]
	ds_write_b128 v126, v[32:35]
	s_waitcnt lgkmcnt(4)
	v_mfma_f32_16x16x32_bf16 v[100:103], v[148:151], v[64:67], v[140:143]
	s_waitcnt lgkmcnt(3)
	v_mfma_f32_16x16x32_bf16 v[96:99], v[148:151], v[104:107], v[96:99]
	ds_write_b128 v126, v[20:23] offset:2048
	s_waitcnt lgkmcnt(3)
	v_mfma_f32_16x16x32_bf16 v[84:87], v[148:151], v[112:115], v[84:87]
	s_waitcnt lgkmcnt(2)
	v_mfma_f32_16x16x32_bf16 v[76:79], v[148:151], v[108:111], v[76:79]
	ds_write_b128 v126, v[16:19] offset:4096
	v_mfma_f32_16x16x32_bf16 v[72:75], v[152:155], v[64:67], v[72:75]
	v_mfma_f32_16x16x32_bf16 v[68:71], v[152:155], v[104:107], v[68:71]
	ds_write_b128 v126, v[24:27] offset:6144
	v_mfma_f32_16x16x32_bf16 v[60:63], v[152:155], v[112:115], v[60:63]
	v_mfma_f32_16x16x32_bf16 v[52:55], v[152:155], v[108:111], v[52:55]
	ds_write_b128 v126, v[12:15] offset:16512
	v_mfma_f32_16x16x32_bf16 v[44:47], v[156:159], v[64:67], v[44:47]
	v_mfma_f32_16x16x32_bf16 v[40:43], v[156:159], v[104:107], v[40:43]
	ds_write_b128 v126, v[8:11] offset:18560
	v_mfma_f32_16x16x32_bf16 v[36:39], v[156:159], v[112:115], v[36:39]
	v_mfma_f32_16x16x32_bf16 v[28:31], v[156:159], v[108:111], v[28:31]
	ds_write_b128 v126, v[4:7] offset:20608
	ds_write_b128 v126, v[0:3] offset:22656
	s_cmp_lt_u32 s44, 14
	s_mov_b32 s7, s44
	s_waitcnt lgkmcnt(0)
	s_barrier
; #define MFMA16(a, b, c) __builtin_amdgcn_mfma_f32_16x16x32_bf16(a, b, c, 0, 0, 0)
; template <int WM, int WN, typename SrcF, typename PostF>
; __device__ __forceinline__ void gemm_stream(const int nsteps, SrcF src, PostF post, f32x4 (&acc)[WM][WN], char* smem) {
;     ...
;   acc[3][0] = MFMA16(pa, pb0, acc[3][0]);
;   acc[3][1] = MFMA16(pa, pb1, acc[3][1]);
;   acc[3][2] = MFMA16(pa, pb2, acc[3][2]);
;   acc[3][3] = MFMA16(pa, pb3, acc[3][3]);
; template <int WM, int WN>
; __device__ __forceinline__ void store_tile_bf16(const f32x4 (&acc)[WM][WN], u16* dst, int ld, char* smem) {
;   constexpr int BM = 32 * WM, BN = 32 * WN, STR = BN + 8;
;   const int tid = opaque_tid(), lane = tid & 63, wid = tid >> 6;
;   const int wr = wid >> 1, wc = wid & 1, fr = lane & 15, fq = lane >> 4;
;   u16* T = reinterpret_cast<u16*>(smem);
; #pragma unroll
;   for (int m = 0; m < WM; ++m)
; #pragma unroll
;     for (int n = 0; n < WN; ++n)
; #pragma unroll
;       for (int j = 0; j < 4; ++j)
;         T[(wr * 16 * WM + m * 16 + fq * 4 + j) * STR + wc * 16 * WN + n * 16 + fr] = f2bf(acc[m][n][j]);
;   __syncthreads();
	s_waitcnt vmcnt(5)
	v_mov_b32_e32 v16, v232
	s_waitcnt vmcnt(0)
	v_mfma_f32_16x16x32_bf16 v[0:3], v[48:51], v[64:67], v[92:95]
	v_lshrrev_b32_e32 v18, 2, v16
	v_lshrrev_b32_e32 v17, 1, v16
	v_and_b32_e32 v18, 12, v18
	v_and_or_b32 v17, v17, s40, v18
	v_and_b32_e32 v18, 0x4f, v16
	v_mul_lo_u32 v17, v17, s42
	v_lshl_add_u32 v17, v18, 1, v17
	v_cvt_pk_bf16_f32 v18, 0, v101
	ds_write_b16_d16_hi v17, v18 offset:272
	v_cvt_pk_bf16_f32 v18, 0, v102
	ds_write_b16_d16_hi v17, v18 offset:544
	v_cvt_pk_bf16_f32 v18, 0, v103
	ds_write_b16_d16_hi v17, v18 offset:816
	v_cvt_pk_bf16_f32 v18, 0, v96
	ds_write_b16_d16_hi v17, v18 offset:32
	v_cvt_pk_bf16_f32 v18, 0, v97
	ds_write_b16_d16_hi v17, v18 offset:304
	v_cvt_pk_bf16_f32 v18, 0, v98
	ds_write_b16_d16_hi v17, v18 offset:576
	v_cvt_pk_bf16_f32 v18, 0, v99
	ds_write_b16_d16_hi v17, v18 offset:848
	v_cvt_pk_bf16_f32 v18, 0, v84
	ds_write_b16_d16_hi v17, v18 offset:64
	v_cvt_pk_bf16_f32 v18, 0, v85
	ds_write_b16_d16_hi v17, v18 offset:336
	v_cvt_pk_bf16_f32 v18, 0, v86
	ds_write_b16_d16_hi v17, v18 offset:608
	v_cvt_pk_bf16_f32 v18, 0, v87
	ds_write_b16_d16_hi v17, v18 offset:880
	v_cvt_pk_bf16_f32 v18, 0, v76
	ds_write_b16_d16_hi v17, v18 offset:96
	v_cvt_pk_bf16_f32 v18, 0, v77
	ds_write_b16_d16_hi v17, v18 offset:368
	v_cvt_pk_bf16_f32 v18, 0, v78
	ds_write_b16_d16_hi v17, v18 offset:640
	v_cvt_pk_bf16_f32 v18, 0, v79
	ds_write_b16_d16_hi v17, v18 offset:912
	v_cvt_pk_bf16_f32 v18, 0, v72
	ds_write_b16_d16_hi v17, v18 offset:4352
	v_cvt_pk_bf16_f32 v18, 0, v73
	ds_write_b16_d16_hi v17, v18 offset:4624
	v_cvt_pk_bf16_f32 v18, 0, v74
	ds_write_b16_d16_hi v17, v18 offset:4896
	v_cvt_pk_bf16_f32 v18, 0, v75
	ds_write_b16_d16_hi v17, v18 offset:5168
	v_cvt_pk_bf16_f32 v18, 0, v68
	ds_write_b16_d16_hi v17, v18 offset:4384
	v_cvt_pk_bf16_f32 v18, 0, v69
	ds_write_b16_d16_hi v17, v18 offset:4656
	v_cvt_pk_bf16_f32 v18, 0, v70
	ds_write_b16_d16_hi v17, v18 offset:4928
	v_cvt_pk_bf16_f32 v18, 0, v71
	ds_write_b16_d16_hi v17, v18 offset:5200
	v_cvt_pk_bf16_f32 v18, 0, v60
	ds_write_b16_d16_hi v17, v18 offset:4416
	v_cvt_pk_bf16_f32 v18, 0, v61
	ds_write_b16_d16_hi v17, v18 offset:4688
	v_cvt_pk_bf16_f32 v18, 0, v62
	ds_write_b16_d16_hi v17, v18 offset:4960
	v_cvt_pk_bf16_f32 v18, 0, v63
	ds_write_b16_d16_hi v17, v18 offset:5232
	v_cvt_pk_bf16_f32 v18, 0, v52
	ds_write_b16_d16_hi v17, v18 offset:4448
	v_cvt_pk_bf16_f32 v18, 0, v53
	ds_write_b16_d16_hi v17, v18 offset:4720
	v_cvt_pk_bf16_f32 v18, 0, v54
	ds_write_b16_d16_hi v17, v18 offset:4992
	v_cvt_pk_bf16_f32 v18, 0, v55
	ds_write_b16_d16_hi v17, v18 offset:5264
	v_cvt_pk_bf16_f32 v18, 0, v44
	ds_write_b16_d16_hi v17, v18 offset:8704
	v_cvt_pk_bf16_f32 v18, 0, v45
	ds_write_b16_d16_hi v17, v18 offset:8976
	v_cvt_pk_bf16_f32 v18, 0, v46
	ds_write_b16_d16_hi v17, v18 offset:9248
	v_cvt_pk_bf16_f32 v18, 0, v47
	ds_write_b16_d16_hi v17, v18 offset:9520
	v_cvt_pk_bf16_f32 v18, 0, v40
	ds_write_b16_d16_hi v17, v18 offset:8736
	v_cvt_pk_bf16_f32 v18, 0, v41
	ds_write_b16_d16_hi v17, v18 offset:9008
	v_cvt_pk_bf16_f32 v18, 0, v42
	ds_write_b16_d16_hi v17, v18 offset:9280
	v_cvt_pk_bf16_f32 v18, 0, v43
	ds_write_b16_d16_hi v17, v18 offset:9552
	v_cvt_pk_bf16_f32 v18, 0, v36
	ds_write_b16_d16_hi v17, v18 offset:8768
	v_cvt_pk_bf16_f32 v18, 0, v37
	ds_write_b16_d16_hi v17, v18 offset:9040
	v_cvt_pk_bf16_f32 v18, 0, v38
	ds_write_b16_d16_hi v17, v18 offset:9312
	v_cvt_pk_bf16_f32 v18, 0, v39
	ds_write_b16_d16_hi v17, v18 offset:9584
	v_cvt_pk_bf16_f32 v18, 0, v28
	ds_write_b16_d16_hi v17, v18 offset:8800
	v_cvt_pk_bf16_f32 v18, 0, v29
	ds_write_b16_d16_hi v17, v18 offset:9072
	v_cvt_pk_bf16_f32 v18, 0, v30
	ds_write_b16_d16_hi v17, v18 offset:9344
	v_cvt_pk_bf16_f32 v18, 0, v31
	ds_write_b16_d16_hi v17, v18 offset:9616
	v_cvt_pk_bf16_f32 v0, 0, v0
	ds_write_b16_d16_hi v17, v0 offset:13056
	v_cvt_pk_bf16_f32 v0, 0, v1
	v_mfma_f32_16x16x32_bf16 v[4:7], v[48:51], v[104:107], v[88:91]
	ds_write_b16_d16_hi v17, v0 offset:13328
	v_cvt_pk_bf16_f32 v0, 0, v2
	ds_write_b16_d16_hi v17, v0 offset:13600
	v_cvt_pk_bf16_f32 v0, 0, v3
	ds_write_b16_d16_hi v17, v0 offset:13872
	s_nop 0
	s_nop 1
	v_cvt_pk_bf16_f32 v0, 0, v4
	ds_write_b16_d16_hi v17, v0 offset:13088
	v_cvt_pk_bf16_f32 v0, 0, v5
	v_mfma_f32_16x16x32_bf16 v[8:11], v[48:51], v[112:115], v[80:83]
	ds_write_b16_d16_hi v17, v0 offset:13360
	v_cvt_pk_bf16_f32 v0, 0, v6
	ds_write_b16_d16_hi v17, v0 offset:13632
	v_cvt_pk_bf16_f32 v0, 0, v7
	ds_write_b16_d16_hi v17, v0 offset:13904
	s_nop 0
	s_nop 1
	v_cvt_pk_bf16_f32 v0, 0, v8
	ds_write_b16_d16_hi v17, v0 offset:13120
	v_cvt_pk_bf16_f32 v0, 0, v9
	v_mfma_f32_16x16x32_bf16 v[12:15], v[48:51], v[108:111], v[56:59]
	ds_write_b16_d16_hi v17, v0 offset:13392
	v_cvt_pk_bf16_f32 v0, 0, v10
	ds_write_b16_d16_hi v17, v0 offset:13664
	v_cvt_pk_bf16_f32 v0, 0, v11
	ds_write_b16_d16_hi v17, v0 offset:13936
	s_nop 0
	s_nop 1
	v_cvt_pk_bf16_f32 v0, 0, v12
	ds_write_b16_d16_hi v17, v0 offset:13152
	v_cvt_pk_bf16_f32 v0, 0, v13
	ds_write_b16_d16_hi v17, v0 offset:13424
	v_cvt_pk_bf16_f32 v0, 0, v14
	ds_write_b16_d16_hi v17, v0 offset:13696
	s_lshl_b64 s[8:9], s[8:9], 1
	v_cvt_pk_bf16_f32 v0, 0, v15
	s_add_u32 s8, s26, s8
	ds_write_b16_d16_hi v17, v0 offset:13968
	v_ashrrev_i32_e32 v0, 31, v16
	s_addc_u32 s9, s27, s9
	s_lshl_b32 s6, s6, 7
	v_lshrrev_b32_e32 v0, 28, v0
	s_ashr_i32 s7, s6, 31
	v_add_u32_e32 v0, v16, v0
	s_lshl_b64 s[6:7], s[6:7], 1
	v_ashrrev_i32_e32 v4, 4, v0
	v_and_b32_e32 v0, -16, v0
	s_add_u32 s6, s8, s6
	v_sub_u32_e32 v0, v16, v0
	v_ashrrev_i32_e32 v5, 31, v4
	s_addc_u32 s7, s9, s7
	v_mul_lo_u32 v1, v4, s42
	v_lshlrev_b32_e32 v6, 3, v0
	v_lshlrev_b64 v[4:5], 11, v[4:5]
	v_ashrrev_i32_e32 v7, 31, v6
	v_lshl_add_u64 v[4:5], s[6:7], 0, v[4:5]
	v_lshl_add_u64 v[8:9], v[6:7], 1, v[4:5]
	v_add_u32_e32 v4, 0x100, v16
	v_ashrrev_i32_e32 v5, 31, v4
	v_cvt_pk_bf16_f32 v19, 0, v100
	v_lshl_add_u32 v0, v0, 4, v1
	v_lshrrev_b32_e32 v5, 28, v5
	ds_write_b16_d16_hi v17, v19
	s_waitcnt lgkmcnt(0)
	s_barrier
; template <int WM, int WN>
; __device__ __forceinline__ void store_tile_bf16(const f32x4 (&acc)[WM][WN], u16* dst, int ld, char* smem) {
;     ...
;   constexpr int CPR = BN / 8;
; #pragma unroll
;   for (int i = 0; i < BM * CPR / 256; ++i) {
;     int q = tid + 256 * i, row = q / CPR, c = q % CPR;
;     uint4 v = *reinterpret_cast<const uint4*>(T + row * STR + c * 8);
;     *reinterpret_cast<uint4*>(dst + (size_t)row * ld + c * 8) = v;
;   }
; __device__ void phase_out(const Params& p, int layer, char* smem) {
;     ...
;   for (int t = li_; t < rbp_ * 8; t += nl_) {
;     const int rg_ = t / (8 * 8), v_ = t % (8 * 8);
;     const int rb = xg_ * rbp_ + rg_ * 8 + (v_ & 7), cb = v_ >> 3;
	ds_read_b128 v[0:3], v0
	v_add_u32_e32 v5, v4, v5
	v_ashrrev_i32_e32 v10, 4, v5
	v_and_b32_e32 v5, -16, v5
	v_sub_u32_e32 v11, v4, v5
	v_mul_lo_u32 v4, v10, s42
	v_lshl_add_u32 v4, v11, 4, v4
	ds_read_b128 v[4:7], v4
	s_waitcnt lgkmcnt(1)
	global_store_dwordx4 v[8:9], v[0:3], off
	s_add_i32 s43, s43, s61
	s_cmp_lt_i32 s43, s62
	v_lshlrev_b32_e32 v0, 3, v11
	v_ashrrev_i32_e32 v11, 31, v10
	v_lshlrev_b64 v[2:3], 11, v[10:11]
	v_ashrrev_i32_e32 v1, 31, v0
	v_lshl_add_u64 v[2:3], s[6:7], 0, v[2:3]
	v_lshl_add_u64 v[0:1], v[0:1], 1, v[2:3]
	s_waitcnt lgkmcnt(0)
	global_store_dwordx4 v[0:1], v[4:7], off
	v_add_u32_e32 v0, 0x200, v16
	v_ashrrev_i32_e32 v1, 31, v0
	v_lshrrev_b32_e32 v1, 28, v1
	v_add_u32_e32 v1, v0, v1
	v_ashrrev_i32_e32 v4, 4, v1
	v_and_b32_e32 v1, -16, v1
	v_sub_u32_e32 v0, v0, v1
	v_ashrrev_i32_e32 v5, 31, v4
	v_mul_lo_u32 v1, v4, s42
	v_lshlrev_b32_e32 v6, 3, v0
	v_lshlrev_b64 v[4:5], 11, v[4:5]
	v_ashrrev_i32_e32 v7, 31, v6
	v_lshl_add_u64 v[4:5], s[6:7], 0, v[4:5]
	v_lshl_add_u64 v[8:9], v[6:7], 1, v[4:5]
	v_add_u32_e32 v4, 0x300, v16
	v_ashrrev_i32_e32 v5, 31, v4
	v_lshl_add_u32 v0, v0, 4, v1
	v_lshrrev_b32_e32 v5, 28, v5
	ds_read_b128 v[0:3], v0
	v_add_u32_e32 v5, v4, v5
	v_ashrrev_i32_e32 v10, 4, v5
	v_and_b32_e32 v5, -16, v5
	v_sub_u32_e32 v11, v4, v5
	v_mul_lo_u32 v4, v10, s42
	v_lshl_add_u32 v4, v11, 4, v4
	ds_read_b128 v[4:7], v4
	s_waitcnt lgkmcnt(1)
	global_store_dwordx4 v[8:9], v[0:3], off
	s_nop 1
	v_lshlrev_b32_e32 v0, 3, v11
	v_ashrrev_i32_e32 v11, 31, v10
	v_lshlrev_b64 v[2:3], 11, v[10:11]
	v_ashrrev_i32_e32 v1, 31, v0
	v_lshl_add_u64 v[2:3], s[6:7], 0, v[2:3]
	v_lshl_add_u64 v[0:1], v[0:1], 1, v[2:3]
	s_waitcnt lgkmcnt(0)
	global_store_dwordx4 v[0:1], v[4:7], off
	v_add_u32_e32 v0, 0x400, v16
	v_ashrrev_i32_e32 v1, 31, v0
	v_lshrrev_b32_e32 v1, 28, v1
	v_add_u32_e32 v1, v0, v1
	v_ashrrev_i32_e32 v4, 4, v1
	v_and_b32_e32 v1, -16, v1
	v_sub_u32_e32 v0, v0, v1
	v_ashrrev_i32_e32 v5, 31, v4
	v_mul_lo_u32 v1, v4, s42
	v_lshlrev_b32_e32 v6, 3, v0
	v_lshlrev_b64 v[4:5], 11, v[4:5]
	v_ashrrev_i32_e32 v7, 31, v6
	v_lshl_add_u64 v[4:5], s[6:7], 0, v[4:5]
	v_lshl_add_u64 v[8:9], v[6:7], 1, v[4:5]
	v_add_u32_e32 v4, 0x500, v16
	v_ashrrev_i32_e32 v5, 31, v4
	v_lshl_add_u32 v0, v0, 4, v1
	v_lshrrev_b32_e32 v5, 28, v5
	ds_read_b128 v[0:3], v0
	v_add_u32_e32 v5, v4, v5
	v_ashrrev_i32_e32 v10, 4, v5
	v_and_b32_e32 v5, -16, v5
	v_sub_u32_e32 v11, v4, v5
	v_mul_lo_u32 v4, v10, s42
	v_lshl_add_u32 v4, v11, 4, v4
	ds_read_b128 v[4:7], v4
	s_waitcnt lgkmcnt(1)
	global_store_dwordx4 v[8:9], v[0:3], off
	s_nop 1
	v_lshlrev_b32_e32 v0, 3, v11
	v_ashrrev_i32_e32 v11, 31, v10
	v_lshlrev_b64 v[2:3], 11, v[10:11]
	v_ashrrev_i32_e32 v1, 31, v0
	v_lshl_add_u64 v[2:3], s[6:7], 0, v[2:3]
	v_lshl_add_u64 v[0:1], v[0:1], 1, v[2:3]
	s_waitcnt lgkmcnt(0)
	global_store_dwordx4 v[0:1], v[4:7], off
	v_add_u32_e32 v0, 0x600, v16
	v_ashrrev_i32_e32 v1, 31, v0
	v_lshrrev_b32_e32 v1, 28, v1
	v_add_u32_e32 v1, v0, v1
	v_ashrrev_i32_e32 v4, 4, v1
	v_and_b32_e32 v1, -16, v1
	v_sub_u32_e32 v0, v0, v1
	v_ashrrev_i32_e32 v5, 31, v4
	v_mul_lo_u32 v1, v4, s42
	v_lshlrev_b32_e32 v6, 3, v0
	v_lshlrev_b64 v[4:5], 11, v[4:5]
	v_ashrrev_i32_e32 v7, 31, v6
	v_lshl_add_u64 v[4:5], s[6:7], 0, v[4:5]
	v_lshl_add_u64 v[8:9], v[6:7], 1, v[4:5]
	v_add_u32_e32 v4, 0x700, v16
	v_ashrrev_i32_e32 v5, 31, v4
	v_lshl_add_u32 v0, v0, 4, v1
	v_lshrrev_b32_e32 v5, 28, v5
	ds_read_b128 v[0:3], v0
	v_add_u32_e32 v5, v4, v5
	v_ashrrev_i32_e32 v10, 4, v5
	v_and_b32_e32 v5, -16, v5
	v_sub_u32_e32 v11, v4, v5
	v_mul_lo_u32 v4, v10, s42
	v_lshl_add_u32 v4, v11, 4, v4
	ds_read_b128 v[4:7], v4
	s_waitcnt lgkmcnt(1)
	global_store_dwordx4 v[8:9], v[0:3], off
	s_nop 1
	v_lshlrev_b32_e32 v0, 3, v11
	v_ashrrev_i32_e32 v11, 31, v10
	v_lshlrev_b64 v[2:3], 11, v[10:11]
	v_ashrrev_i32_e32 v1, 31, v0
	v_lshl_add_u64 v[2:3], s[6:7], 0, v[2:3]
	v_lshl_add_u64 v[0:1], v[0:1], 1, v[2:3]
	s_waitcnt lgkmcnt(0)
	global_store_dwordx4 v[0:1], v[4:7], off
	s_cbranch_scc1 .LBB0_317

; template <int WM, int WN> ...
;     ...
; #pragma unroll
;   for (int n = 0; n < 4; ++n) fb0[n] = LDSF(cur + boff + n * 1024);
; #pragma unroll
;   for (int m = 0; m < 4; ++m) fa0[m] = LDSF(cur + aoff + m * 1024);
;   acc[3][0] = MFMA16(pa, pb0, acc[3][0]);
;   acc[3][1] = MFMA16(pa, pb1, acc[3][1]);
;   acc[3][2] = MFMA16(pa, pb2, acc[3][2]);
;   acc[3][3] = MFMA16(pa, pb3, acc[3][3]);
; #pragma unroll
;   for (int n = 0; n < 4; ++n) acc[0][n] = MFMA16(fa0[0], fb0[n], acc[0][n]);
; #pragma unroll
;   for (int m = 0; m < 4; ++m) fa1[m] = LDSF(cur + aoff + APAN + m * 1024);
; #pragma unroll
;   for (int n = 0; n < 4; ++n) acc[1][n] = MFMA16(fa0[1], fb0[n], acc[1][n]);
; #pragma unroll
;   for (int n = 0; n < 4; ++n) fb1[n] = LDSF(cur + boff + BPAN + n * 1024);
; #pragma unroll
;   for (int n = 0; n < 4; ++n) acc[2][n] = MFMA16(fa0[2], fb0[n], acc[2][n]);
;   *reinterpret_cast<uint4*>(nxt + wao) = a0;
;   *reinterpret_cast<uint4*>(nxt + wao + 32 * 64) = a1;
; #pragma unroll
;   for (int n = 0; n < 4; ++n) acc[3][n] = MFMA16(fa0[3], fb0[n], acc[3][n]);
;   *reinterpret_cast<uint4*>(nxt + wao + 64 * 64) = a2;
;   *reinterpret_cast<uint4*>(nxt + wao + 96 * 64) = a3;
; #pragma unroll
;   for (int n = 0; n < 4; ++n) acc[0][n] = MFMA16(fa1[0], fb1[n], acc[0][n]);
;   *reinterpret_cast<uint4*>(nxt + wbo) = b0;
;   *reinterpret_cast<uint4*>(nxt + wbo + 32 * 64) = b1;
; #pragma unroll
;   for (int n = 0; n < 4; ++n) acc[1][n] = MFMA16(fa1[1], fb1[n], acc[1][n]);
;   *reinterpret_cast<uint4*>(nxt + wbo + 64 * 64) = b2;
;   *reinterpret_cast<uint4*>(nxt + wbo + 96 * 64) = b3;
; #pragma unroll
;   for (int n = 0; n < 4; ++n) acc[2][n] = MFMA16(fa1[2], fb1[n], acc[2][n]);
;   pa = fa1[3];
;   pb0 = fb1[0]; pb1 = fb1[1]; pb2 = fb1[2]; pb3 = fb1[3];
;   SGB_(0x100, 5);
;   SGB_(0x008, 4);
; #pragma unroll
;   for (int i_ = 0; i_ < 11; ++i_) { SGB_(0x008, 1); SGB_(0x100, 1); }
; #pragma unroll
;   for (int i_ = 0; i_ < 8; ++i_) { SGB_(0x008, 2); SGB_(0x200, 1); SGB_(0x020, 1); }
;   SGB_(0x008, 1);
; }
; template <int WM, int WN, typename SrcF, typename PostF>
; __device__ __forceinline__ void gemm_stream(const int nsteps, SrcF src, PostF post, f32x4 (&acc)[WM][WN], char* smem) {
;     ...
;   for (int kt = 0; kt < nsteps; kt += 2) {
;     {
;       TileSrc s = src(min(kt + 2, nsteps - 1));
;       GLOAD_TILE(xa, s.a, s.lda, ACH);
;       GLOAD_TILE(xb, s.b, s.ldb, BCH);
;     }
.LBB0_425:
	s_add_i32 s17, s14, 2
	s_add_i32 s14, s14, 4
	s_min_u32 s14, s14, 15
	s_lshl_b32 s14, s14, 7
	s_add_u32 s92, s24, s14
	s_addc_u32 s93, s25, 0
	s_add_u32 s94, s26, s14
	s_addc_u32 s95, s27, 0
	ds_read_b128 v[148:151], v119
	ds_read_b128 v[132:135], v130 offset:16512
	ds_read_b128 v[136:139], v130 offset:17536
	ds_read_b128 v[140:143], v130 offset:18560
	ds_read_b128 v[144:147], v130 offset:19584
	v_mfma_f32_16x16x32_bf16 v[84:87], v[80:83], v[84:87], v[100:103]
	v_mfma_f32_16x16x32_bf16 v[96:99], v[80:83], v[104:107], v[96:99]
	s_waitcnt vmcnt(4)
	ds_write_b128 v131, v[76:79] offset:33024
	global_load_dwordx4 v[76:79], v116, s[92:93]
	s_add_u32 s64, s24, s14
	s_addc_u32 s65, s25, 0
	v_mfma_f32_16x16x32_bf16 v[92:95], v[80:83], v[108:111], v[92:95]
	v_mfma_f32_16x16x32_bf16 v[80:83], v[80:83], v[112:115], v[88:91]
	s_waitcnt lgkmcnt(4)
	v_mfma_f32_16x16x32_bf16 v[44:47], v[148:151], v[132:135], v[44:47]
	s_nop 0
	ds_read_b128 v[88:91], v119 offset:1024
	s_waitcnt lgkmcnt(4)
	v_mfma_f32_16x16x32_bf16 v[40:43], v[148:151], v[136:139], v[40:43]
	ds_write_b128 v131, v[68:71] offset:35072
	global_load_dwordx4 v[68:71], v120, s[92:93]
	ds_read_b128 v[100:103], v119 offset:2048
	s_waitcnt lgkmcnt(5)
	v_mfma_f32_16x16x32_bf16 v[36:39], v[148:151], v[140:143], v[36:39]
	ds_read_b128 v[104:107], v119 offset:3072
	s_waitcnt lgkmcnt(5)
	v_mfma_f32_16x16x32_bf16 v[32:35], v[148:151], v[144:147], v[32:35]
	ds_read_b128 v[108:111], v119 offset:8256
	s_waitcnt lgkmcnt(4)
	v_mfma_f32_16x16x32_bf16 v[28:31], v[88:91], v[132:135], v[28:31]
	ds_read_b128 v[112:115], v119 offset:9280
	v_mfma_f32_16x16x32_bf16 v[24:27], v[88:91], v[136:139], v[24:27]
	ds_read_b128 v[148:151], v119 offset:10304
	v_mfma_f32_16x16x32_bf16 v[20:23], v[88:91], v[140:143], v[20:23]
	ds_write_b128 v131, v[64:67] offset:37120
	global_load_dwordx4 v[64:67], v122, s[92:93]
	ds_read_b128 v[152:155], v119 offset:11328
	v_mfma_f32_16x16x32_bf16 v[16:19], v[88:91], v[144:147], v[16:19]
	ds_read_b128 v[88:91], v130 offset:24768
	s_waitcnt lgkmcnt(7)
	v_mfma_f32_16x16x32_bf16 v[12:15], v[100:103], v[132:135], v[12:15]
	ds_read_b128 v[156:159], v130 offset:25792
	v_mfma_f32_16x16x32_bf16 v[8:11], v[100:103], v[136:139], v[8:11]
	ds_read_b128 v[160:163], v130 offset:26816
	v_mfma_f32_16x16x32_bf16 v[4:7], v[100:103], v[140:143], v[4:7]
	ds_write_b128 v131, v[72:75] offset:39168
	global_load_dwordx4 v[72:75], v124, s[92:93]
	ds_read_b128 v[164:167], v130 offset:27840
	v_mfma_f32_16x16x32_bf16 v[0:3], v[100:103], v[144:147], v[0:3]
	s_waitcnt lgkmcnt(10)
	v_mfma_f32_16x16x32_bf16 v[84:87], v[104:107], v[132:135], v[84:87]
	v_mfma_f32_16x16x32_bf16 v[96:99], v[104:107], v[136:139], v[96:99]
	v_mfma_f32_16x16x32_bf16 v[92:95], v[104:107], v[140:143], v[92:95]
	v_mfma_f32_16x16x32_bf16 v[80:83], v[104:107], v[144:147], v[80:83]
	s_waitcnt vmcnt(4)
	ds_write_b128 v131, v[60:63] offset:49536
	global_load_dwordx4 v[60:63], v116, s[94:95]
	s_waitcnt lgkmcnt(5)
	v_mfma_f32_16x16x32_bf16 v[44:47], v[108:111], v[88:91], v[44:47]
	s_add_u32 s64, s26, s14
	s_addc_u32 s65, s27, 0
	s_waitcnt lgkmcnt(4)
	v_mfma_f32_16x16x32_bf16 v[40:43], v[108:111], v[156:159], v[40:43]
	s_min_u32 s14, s17, 12
	s_lshl_b32 s14, s14, 7
	s_waitcnt lgkmcnt(3)
	v_mfma_f32_16x16x32_bf16 v[36:39], v[108:111], v[160:163], v[36:39]
	s_waitcnt lgkmcnt(1)
	v_mfma_f32_16x16x32_bf16 v[32:35], v[108:111], v[164:167], v[32:35]
	ds_write_b128 v131, v[56:59] offset:51584
	global_load_dwordx4 v[56:59], v120, s[94:95]
	v_mfma_f32_16x16x32_bf16 v[28:31], v[112:115], v[88:91], v[28:31]
	v_mfma_f32_16x16x32_bf16 v[24:27], v[112:115], v[156:159], v[24:27]
	v_mfma_f32_16x16x32_bf16 v[20:23], v[112:115], v[160:163], v[20:23]
	v_mfma_f32_16x16x32_bf16 v[16:19], v[112:115], v[164:167], v[16:19]
	v_mfma_f32_16x16x32_bf16 v[12:15], v[148:151], v[88:91], v[12:15]
	ds_write_b128 v131, v[52:55] offset:53632
	global_load_dwordx4 v[52:55], v122, s[94:95]
	v_mfma_f32_16x16x32_bf16 v[8:11], v[148:151], v[156:159], v[8:11]
	s_add_u32 s64, s24, s14
	s_addc_u32 s65, s25, 0
	s_add_u32 s66, s26, s14
	v_mfma_f32_16x16x32_bf16 v[4:7], v[148:151], v[160:163], v[4:7]
	s_addc_u32 s67, s27, 0
	v_mfma_f32_16x16x32_bf16 v[0:3], v[148:151], v[164:167], v[0:3]
	v_mfma_f32_16x16x32_bf16 v[88:91], v[152:155], v[88:91], v[84:87]
	ds_write_b128 v131, v[48:51] offset:55680
	global_load_dwordx4 v[48:51], v124, s[94:95]
	v_mfma_f32_16x16x32_bf16 v[96:99], v[152:155], v[156:159], v[96:99]
	v_mfma_f32_16x16x32_bf16 v[92:95], v[152:155], v[160:163], v[92:95]
	v_mfma_f32_16x16x32_bf16 v[132:135], v[152:155], v[164:167], v[80:83]
	s_waitcnt lgkmcnt(0)
	s_barrier
; template <int WM, int WN> ...
;     ...
; #pragma unroll
;   for (int n = 0; n < 4; ++n) fb0[n] = LDSF(cur + boff + n * 1024);
; #pragma unroll
;   for (int m = 0; m < 4; ++m) fa0[m] = LDSF(cur + aoff + m * 1024);
;   acc[3][0] = MFMA16(pa, pb0, acc[3][0]);
;   acc[3][1] = MFMA16(pa, pb1, acc[3][1]);
;   acc[3][2] = MFMA16(pa, pb2, acc[3][2]);
;   acc[3][3] = MFMA16(pa, pb3, acc[3][3]);
; #pragma unroll
;   for (int n = 0; n < 4; ++n) acc[0][n] = MFMA16(fa0[0], fb0[n], acc[0][n]);
; #pragma unroll
;   for (int m = 0; m < 4; ++m) fa1[m] = LDSF(cur + aoff + APAN + m * 1024);
; #pragma unroll
;   for (int n = 0; n < 4; ++n) acc[1][n] = MFMA16(fa0[1], fb0[n], acc[1][n]);
; #pragma unroll
;   for (int n = 0; n < 4; ++n) fb1[n] = LDSF(cur + boff + BPAN + n * 1024);
; #pragma unroll
;   for (int n = 0; n < 4; ++n) acc[2][n] = MFMA16(fa0[2], fb0[n], acc[2][n]);
;   *reinterpret_cast<uint4*>(nxt + wao) = a0;
;   *reinterpret_cast<uint4*>(nxt + wao + 32 * 64) = a1;
; #pragma unroll
;   for (int n = 0; n < 4; ++n) acc[3][n] = MFMA16(fa0[3], fb0[n], acc[3][n]);
;   *reinterpret_cast<uint4*>(nxt + wao + 64 * 64) = a2;
;   *reinterpret_cast<uint4*>(nxt + wao + 96 * 64) = a3;
; #pragma unroll
;   for (int n = 0; n < 4; ++n) acc[0][n] = MFMA16(fa1[0], fb1[n], acc[0][n]);
;   *reinterpret_cast<uint4*>(nxt + wbo) = b0;
;   *reinterpret_cast<uint4*>(nxt + wbo + 32 * 64) = b1;
; #pragma unroll
;   for (int n = 0; n < 4; ++n) acc[1][n] = MFMA16(fa1[1], fb1[n], acc[1][n]);
;   *reinterpret_cast<uint4*>(nxt + wbo + 64 * 64) = b2;
;   *reinterpret_cast<uint4*>(nxt + wbo + 96 * 64) = b3;
; #pragma unroll
;   for (int n = 0; n < 4; ++n) acc[2][n] = MFMA16(fa1[2], fb1[n], acc[2][n]);
;   pa = fa1[3];
;   pb0 = fb1[0]; pb1 = fb1[1]; pb2 = fb1[2]; pb3 = fb1[3];
;   SGB_(0x100, 5);
;   SGB_(0x008, 4);
; #pragma unroll
;   for (int i_ = 0; i_ < 11; ++i_) { SGB_(0x008, 1); SGB_(0x100, 1); }
; #pragma unroll
;   for (int i_ = 0; i_ < 8; ++i_) { SGB_(0x008, 2); SGB_(0x200, 1); SGB_(0x020, 1); }
;   SGB_(0x008, 1);
; }
; template <int WM, int WN, typename SrcF, typename PostF>
; __device__ __forceinline__ void gemm_stream(const int nsteps, SrcF src, PostF post, f32x4 (&acc)[WM][WN], char* smem) {
;     ...
;       TileSrc s = src(min(kt + 3, nsteps - 1));
;       GLOAD_TILE(ya, s.a, s.lda, ACH);
;       GLOAD_TILE(yb, s.b, s.ldb, BCH);
;     }
	s_nop 0
	ds_read_b128 v[80:83], v119 offset:33024
	ds_read_b128 v[100:103], v130 offset:49536
	ds_read_b128 v[112:115], v130 offset:50560
	ds_read_b128 v[136:139], v130 offset:51584
	ds_read_b128 v[140:143], v130 offset:52608
	s_waitcnt lgkmcnt(3)
	v_mfma_f32_16x16x32_bf16 v[44:47], v[80:83], v[100:103], v[44:47]
	s_waitcnt lgkmcnt(2)
	v_mfma_f32_16x16x32_bf16 v[40:43], v[80:83], v[112:115], v[40:43]
	s_waitcnt vmcnt(4)
	ds_write_b128 v131, v[76:79]
	global_load_dwordx4 v[76:79], v116, s[64:65] offset:384
	s_waitcnt lgkmcnt(2)
	v_mfma_f32_16x16x32_bf16 v[36:39], v[80:83], v[136:139], v[36:39]
	s_waitcnt lgkmcnt(0)
	v_mfma_f32_16x16x32_bf16 v[32:35], v[80:83], v[140:143], v[32:35]
	ds_read_b128 v[80:83], v119 offset:34048
	s_waitcnt lgkmcnt(0)
	v_mfma_f32_16x16x32_bf16 v[28:31], v[80:83], v[100:103], v[28:31]
	ds_write_b128 v131, v[68:71] offset:2048
	global_load_dwordx4 v[68:71], v120, s[64:65] offset:384
	ds_read_b128 v[104:107], v119 offset:35072
	v_mfma_f32_16x16x32_bf16 v[24:27], v[80:83], v[112:115], v[24:27]
	ds_read_b128 v[144:147], v119 offset:36096
	v_mfma_f32_16x16x32_bf16 v[20:23], v[80:83], v[136:139], v[20:23]
	ds_read_b128 v[148:151], v119 offset:41280
	v_mfma_f32_16x16x32_bf16 v[16:19], v[80:83], v[140:143], v[16:19]
	ds_read_b128 v[152:155], v119 offset:42304
	s_waitcnt lgkmcnt(3)
	v_mfma_f32_16x16x32_bf16 v[12:15], v[104:107], v[100:103], v[12:15]
	ds_write_b128 v131, v[64:67] offset:4096
	global_load_dwordx4 v[64:67], v122, s[64:65] offset:384
	ds_read_b128 v[156:159], v119 offset:43328
	v_mfma_f32_16x16x32_bf16 v[8:11], v[104:107], v[112:115], v[8:11]
	ds_read_b128 v[80:83], v119 offset:44352
	v_mfma_f32_16x16x32_bf16 v[4:7], v[104:107], v[136:139], v[4:7]
	ds_read_b128 v[84:87], v130 offset:57792
	v_mfma_f32_16x16x32_bf16 v[0:3], v[104:107], v[140:143], v[0:3]
	ds_write_b128 v131, v[72:75] offset:6144
	global_load_dwordx4 v[72:75], v124, s[64:65] offset:384
	ds_read_b128 v[104:107], v130 offset:58816
	s_waitcnt lgkmcnt(8)
	v_mfma_f32_16x16x32_bf16 v[100:103], v[144:147], v[100:103], v[88:91]
	ds_read_b128 v[108:111], v130 offset:59840
	v_mfma_f32_16x16x32_bf16 v[96:99], v[144:147], v[112:115], v[96:99]
	ds_read_b128 v[112:115], v130 offset:60864
	v_mfma_f32_16x16x32_bf16 v[92:95], v[144:147], v[136:139], v[92:95]
	v_mfma_f32_16x16x32_bf16 v[88:91], v[144:147], v[140:143], v[132:135]
	s_waitcnt vmcnt(4)
	ds_write_b128 v131, v[60:63] offset:16512
	global_load_dwordx4 v[60:63], v116, s[66:67] offset:384
	s_waitcnt lgkmcnt(5)
	v_mfma_f32_16x16x32_bf16 v[44:47], v[148:151], v[84:87], v[44:47]
	s_waitcnt lgkmcnt(3)
	v_mfma_f32_16x16x32_bf16 v[40:43], v[148:151], v[104:107], v[40:43]
	s_waitcnt lgkmcnt(2)
	v_mfma_f32_16x16x32_bf16 v[36:39], v[148:151], v[108:111], v[36:39]
	ds_write_b128 v131, v[56:59] offset:18560
	global_load_dwordx4 v[56:59], v120, s[66:67] offset:384
	s_waitcnt lgkmcnt(2)
	v_mfma_f32_16x16x32_bf16 v[32:35], v[148:151], v[112:115], v[32:35]
	v_mfma_f32_16x16x32_bf16 v[28:31], v[152:155], v[84:87], v[28:31]
	v_mfma_f32_16x16x32_bf16 v[24:27], v[152:155], v[104:107], v[24:27]
	v_mfma_f32_16x16x32_bf16 v[20:23], v[152:155], v[108:111], v[20:23]
	ds_write_b128 v131, v[52:55] offset:20608
	global_load_dwordx4 v[52:55], v122, s[66:67] offset:384
	v_mfma_f32_16x16x32_bf16 v[16:19], v[152:155], v[112:115], v[16:19]
	v_mfma_f32_16x16x32_bf16 v[12:15], v[156:159], v[84:87], v[12:15]
	v_mfma_f32_16x16x32_bf16 v[8:11], v[156:159], v[104:107], v[8:11]
	ds_write_b128 v131, v[48:51] offset:22656
	global_load_dwordx4 v[48:51], v124, s[66:67] offset:384
	v_mfma_f32_16x16x32_bf16 v[4:7], v[156:159], v[108:111], v[4:7]
	v_mfma_f32_16x16x32_bf16 v[0:3], v[156:159], v[112:115], v[0:3]
	s_cmp_lt_u32 s17, 12
	s_mov_b32 s14, s17
	s_waitcnt lgkmcnt(0)
	s_barrier
	s_cbranch_scc1 .LBB0_425
	ds_read_b128 v[148:151], v119
	ds_read_b128 v[132:135], v130 offset:16512
	ds_read_b128 v[136:139], v130 offset:17536
	ds_read_b128 v[140:143], v130 offset:18560
	ds_read_b128 v[144:147], v130 offset:19584
	v_mfma_f32_16x16x32_bf16 v[84:87], v[80:83], v[84:87], v[100:103]
	s_add_i32 s17, s14, 2
	s_add_i32 s14, s14, 4
	s_min_u32 s14, s14, 15
	v_mfma_f32_16x16x32_bf16 v[96:99], v[80:83], v[104:107], v[96:99]
	s_lshl_b32 s14, s14, 7
	s_add_u32 s64, s24, s14
	s_addc_u32 s65, s25, 0
	v_mfma_f32_16x16x32_bf16 v[92:95], v[80:83], v[108:111], v[92:95]
	v_mfma_f32_16x16x32_bf16 v[80:83], v[80:83], v[112:115], v[88:91]
	s_waitcnt lgkmcnt(3)
	v_mfma_f32_16x16x32_bf16 v[44:47], v[148:151], v[132:135], v[44:47]
	s_nop 0
	ds_read_b128 v[88:91], v119 offset:1024
	s_waitcnt lgkmcnt(3)
	v_mfma_f32_16x16x32_bf16 v[40:43], v[148:151], v[136:139], v[40:43]
	ds_read_b128 v[100:103], v119 offset:2048
	s_waitcnt lgkmcnt(3)
	v_mfma_f32_16x16x32_bf16 v[36:39], v[148:151], v[140:143], v[36:39]
	ds_read_b128 v[104:107], v119 offset:3072
	s_waitcnt lgkmcnt(3)
	v_mfma_f32_16x16x32_bf16 v[32:35], v[148:151], v[144:147], v[32:35]
	ds_read_b128 v[108:111], v119 offset:8256
	s_waitcnt lgkmcnt(3)
	v_mfma_f32_16x16x32_bf16 v[28:31], v[88:91], v[132:135], v[28:31]
	ds_read_b128 v[112:115], v119 offset:9280
	v_mfma_f32_16x16x32_bf16 v[24:27], v[88:91], v[136:139], v[24:27]
	ds_read_b128 v[148:151], v119 offset:10304
	v_mfma_f32_16x16x32_bf16 v[20:23], v[88:91], v[140:143], v[20:23]
	ds_read_b128 v[152:155], v119 offset:11328
	v_mfma_f32_16x16x32_bf16 v[16:19], v[88:91], v[144:147], v[16:19]
	ds_read_b128 v[88:91], v130 offset:24768
	s_waitcnt lgkmcnt(6)
	v_mfma_f32_16x16x32_bf16 v[12:15], v[100:103], v[132:135], v[12:15]
	ds_read_b128 v[156:159], v130 offset:25792
	v_mfma_f32_16x16x32_bf16 v[8:11], v[100:103], v[136:139], v[8:11]
	ds_read_b128 v[160:163], v130 offset:26816
	v_mfma_f32_16x16x32_bf16 v[4:7], v[100:103], v[140:143], v[4:7]
	ds_read_b128 v[164:167], v130 offset:27840
	v_mfma_f32_16x16x32_bf16 v[0:3], v[100:103], v[144:147], v[0:3]
	s_waitcnt lgkmcnt(8)
; template <int WM, int WN> ...
;     ...
; #pragma unroll
;   for (int n = 0; n < 4; ++n) fb0[n] = LDSF(cur + boff + n * 1024);
; #pragma unroll
;   for (int m = 0; m < 4; ++m) fa0[m] = LDSF(cur + aoff + m * 1024);
;   acc[3][0] = MFMA16(pa, pb0, acc[3][0]);
;   acc[3][1] = MFMA16(pa, pb1, acc[3][1]);
;   acc[3][2] = MFMA16(pa, pb2, acc[3][2]);
;   acc[3][3] = MFMA16(pa, pb3, acc[3][3]);
; #pragma unroll
;   for (int n = 0; n < 4; ++n) acc[0][n] = MFMA16(fa0[0], fb0[n], acc[0][n]);
; #pragma unroll
;   for (int m = 0; m < 4; ++m) fa1[m] = LDSF(cur + aoff + APAN + m * 1024);
; #pragma unroll
;   for (int n = 0; n < 4; ++n) acc[1][n] = MFMA16(fa0[1], fb0[n], acc[1][n]);
; #pragma unroll
;   for (int n = 0; n < 4; ++n) fb1[n] = LDSF(cur + boff + BPAN + n * 1024);
; #pragma unroll
;   for (int n = 0; n < 4; ++n) acc[2][n] = MFMA16(fa0[2], fb0[n], acc[2][n]);
;   *reinterpret_cast<uint4*>(nxt + wao) = a0;
;   *reinterpret_cast<uint4*>(nxt + wao + 32 * 64) = a1;
; #pragma unroll
;   for (int n = 0; n < 4; ++n) acc[3][n] = MFMA16(fa0[3], fb0[n], acc[3][n]);
;   *reinterpret_cast<uint4*>(nxt + wao + 64 * 64) = a2;
;   *reinterpret_cast<uint4*>(nxt + wao + 96 * 64) = a3;
; #pragma unroll
;   for (int n = 0; n < 4; ++n) acc[0][n] = MFMA16(fa1[0], fb1[n], acc[0][n]);
;   *reinterpret_cast<uint4*>(nxt + wbo) = b0;
;   *reinterpret_cast<uint4*>(nxt + wbo + 32 * 64) = b1;
; #pragma unroll
;   for (int n = 0; n < 4; ++n) acc[1][n] = MFMA16(fa1[1], fb1[n], acc[1][n]);
;   *reinterpret_cast<uint4*>(nxt + wbo + 64 * 64) = b2;
;   *reinterpret_cast<uint4*>(nxt + wbo + 96 * 64) = b3;
; #pragma unroll
;   for (int n = 0; n < 4; ++n) acc[2][n] = MFMA16(fa1[2], fb1[n], acc[2][n]);
;   pa = fa1[3];
;   pb0 = fb1[0]; pb1 = fb1[1]; pb2 = fb1[2]; pb3 = fb1[3];
;   SGB_(0x100, 5);
;   SGB_(0x008, 4);
; #pragma unroll
;   for (int i_ = 0; i_ < 11; ++i_) { SGB_(0x008, 1); SGB_(0x100, 1); }
; #pragma unroll
;   for (int i_ = 0; i_ < 8; ++i_) { SGB_(0x008, 2); SGB_(0x200, 1); SGB_(0x020, 1); }
;   SGB_(0x008, 1);
; }
; template <int WM, int WN, typename SrcF, typename PostF>
; __device__ __forceinline__ void gemm_stream(const int nsteps, SrcF src, PostF post, f32x4 (&acc)[WM][WN], char* smem) {
;     ...
;   acc[3][0] = MFMA16(pa, pb0, acc[3][0]);
;   acc[3][1] = MFMA16(pa, pb1, acc[3][1]);
;   acc[3][2] = MFMA16(pa, pb2, acc[3][2]);
;   acc[3][3] = MFMA16(pa, pb3, acc[3][3]);
	v_mfma_f32_16x16x32_bf16 v[84:87], v[104:107], v[132:135], v[84:87]
	s_waitcnt vmcnt(7)
	ds_write_b128 v131, v[76:79] offset:33024
	v_mfma_f32_16x16x32_bf16 v[96:99], v[104:107], v[136:139], v[96:99]
	v_mfma_f32_16x16x32_bf16 v[92:95], v[104:107], v[140:143], v[92:95]
	s_waitcnt vmcnt(6)
	ds_write_b128 v131, v[68:71] offset:35072
	v_mfma_f32_16x16x32_bf16 v[80:83], v[104:107], v[144:147], v[80:83]
	s_waitcnt lgkmcnt(5)
	v_mfma_f32_16x16x32_bf16 v[44:47], v[108:111], v[88:91], v[44:47]
	s_waitcnt vmcnt(5)
	ds_write_b128 v131, v[64:67] offset:37120
	s_add_u32 s64, s26, s14
	s_addc_u32 s65, s27, 0
	s_waitcnt lgkmcnt(5)
	v_mfma_f32_16x16x32_bf16 v[40:43], v[108:111], v[156:159], v[40:43]
	s_min_u32 s14, s17, 12
	s_lshl_b32 s14, s14, 7
	s_waitcnt lgkmcnt(4)
	v_mfma_f32_16x16x32_bf16 v[36:39], v[108:111], v[160:163], v[36:39]
	s_waitcnt vmcnt(4)
	ds_write_b128 v131, v[72:75] offset:39168
	s_waitcnt lgkmcnt(4)
	v_mfma_f32_16x16x32_bf16 v[32:35], v[108:111], v[164:167], v[32:35]
	v_mfma_f32_16x16x32_bf16 v[28:31], v[112:115], v[88:91], v[28:31]
	s_waitcnt vmcnt(3)
	ds_write_b128 v131, v[60:63] offset:49536
	v_mfma_f32_16x16x32_bf16 v[24:27], v[112:115], v[156:159], v[24:27]
	v_mfma_f32_16x16x32_bf16 v[20:23], v[112:115], v[160:163], v[20:23]
	s_waitcnt vmcnt(2)
	ds_write_b128 v131, v[56:59] offset:51584
	v_mfma_f32_16x16x32_bf16 v[16:19], v[112:115], v[164:167], v[16:19]
	v_mfma_f32_16x16x32_bf16 v[12:15], v[148:151], v[88:91], v[12:15]
	s_waitcnt vmcnt(1)
	ds_write_b128 v131, v[52:55] offset:53632
	v_mfma_f32_16x16x32_bf16 v[8:11], v[148:151], v[156:159], v[8:11]
	s_add_u32 s64, s24, s14
	s_addc_u32 s65, s25, 0
	s_add_u32 s66, s26, s14
	v_mfma_f32_16x16x32_bf16 v[4:7], v[148:151], v[160:163], v[4:7]
	s_waitcnt vmcnt(0)
	ds_write_b128 v131, v[48:51] offset:55680
	s_addc_u32 s67, s27, 0
	v_mfma_f32_16x16x32_bf16 v[0:3], v[148:151], v[164:167], v[0:3]
	v_mfma_f32_16x16x32_bf16 v[88:91], v[152:155], v[88:91], v[84:87]
	v_mfma_f32_16x16x32_bf16 v[96:99], v[152:155], v[156:159], v[96:99]
	v_mfma_f32_16x16x32_bf16 v[92:95], v[152:155], v[160:163], v[92:95]
	v_mfma_f32_16x16x32_bf16 v[132:135], v[152:155], v[164:167], v[80:83]
	s_waitcnt lgkmcnt(0)
	s_barrier
	s_nop 0
	ds_read_b128 v[80:83], v119 offset:33024
	ds_read_b128 v[100:103], v130 offset:49536
	ds_read_b128 v[112:115], v130 offset:50560
	ds_read_b128 v[136:139], v130 offset:51584
	ds_read_b128 v[140:143], v130 offset:52608
	s_waitcnt lgkmcnt(3)
	v_mfma_f32_16x16x32_bf16 v[44:47], v[80:83], v[100:103], v[44:47]
	s_waitcnt lgkmcnt(2)
	v_mfma_f32_16x16x32_bf16 v[40:43], v[80:83], v[112:115], v[40:43]
	s_waitcnt lgkmcnt(1)
	v_mfma_f32_16x16x32_bf16 v[36:39], v[80:83], v[136:139], v[36:39]
	s_waitcnt lgkmcnt(0)
	v_mfma_f32_16x16x32_bf16 v[32:35], v[80:83], v[140:143], v[32:35]
	ds_read_b128 v[80:83], v119 offset:34048
	s_waitcnt lgkmcnt(0)
	v_mfma_f32_16x16x32_bf16 v[28:31], v[80:83], v[100:103], v[28:31]
	ds_read_b128 v[104:107], v119 offset:35072
	v_mfma_f32_16x16x32_bf16 v[24:27], v[80:83], v[112:115], v[24:27]
	ds_read_b128 v[144:147], v119 offset:36096
	v_mfma_f32_16x16x32_bf16 v[20:23], v[80:83], v[136:139], v[20:23]
	ds_read_b128 v[148:151], v119 offset:41280
	v_mfma_f32_16x16x32_bf16 v[16:19], v[80:83], v[140:143], v[16:19]
	ds_read_b128 v[152:155], v119 offset:42304
	s_waitcnt lgkmcnt(3)
	v_mfma_f32_16x16x32_bf16 v[12:15], v[104:107], v[100:103], v[12:15]
	ds_read_b128 v[156:159], v119 offset:43328
	v_mfma_f32_16x16x32_bf16 v[8:11], v[104:107], v[112:115], v[8:11]
	ds_read_b128 v[80:83], v119 offset:44352
	v_mfma_f32_16x16x32_bf16 v[4:7], v[104:107], v[136:139], v[4:7]
	ds_read_b128 v[84:87], v130 offset:57792
	v_mfma_f32_16x16x32_bf16 v[0:3], v[104:107], v[140:143], v[0:3]
	ds_read_b128 v[104:107], v130 offset:58816
	s_waitcnt lgkmcnt(6)
	v_mfma_f32_16x16x32_bf16 v[100:103], v[144:147], v[100:103], v[88:91]
	ds_read_b128 v[108:111], v130 offset:59840
	v_mfma_f32_16x16x32_bf16 v[96:99], v[144:147], v[112:115], v[96:99]
	ds_read_b128 v[112:115], v130 offset:60864
	v_mfma_f32_16x16x32_bf16 v[92:95], v[144:147], v[136:139], v[92:95]
	v_mfma_f32_16x16x32_bf16 v[88:91], v[144:147], v[140:143], v[132:135]
	ds_write_b128 v131, v[76:79]
	s_waitcnt lgkmcnt(4)
	v_mfma_f32_16x16x32_bf16 v[44:47], v[148:151], v[84:87], v[44:47]
	s_waitcnt lgkmcnt(3)
	v_mfma_f32_16x16x32_bf16 v[40:43], v[148:151], v[104:107], v[40:43]
	ds_write_b128 v131, v[68:71] offset:2048
	s_waitcnt lgkmcnt(3)
	v_mfma_f32_16x16x32_bf16 v[36:39], v[148:151], v[108:111], v[36:39]
	s_waitcnt lgkmcnt(2)
	v_mfma_f32_16x16x32_bf16 v[32:35], v[148:151], v[112:115], v[32:35]
	ds_write_b128 v131, v[64:67] offset:4096
	v_mfma_f32_16x16x32_bf16 v[28:31], v[152:155], v[84:87], v[28:31]
	v_mfma_f32_16x16x32_bf16 v[24:27], v[152:155], v[104:107], v[24:27]
	ds_write_b128 v131, v[72:75] offset:6144
	v_mfma_f32_16x16x32_bf16 v[20:23], v[152:155], v[108:111], v[20:23]
	v_mfma_f32_16x16x32_bf16 v[16:19], v[152:155], v[112:115], v[16:19]
	ds_write_b128 v131, v[60:63] offset:16512
	v_mfma_f32_16x16x32_bf16 v[12:15], v[156:159], v[84:87], v[12:15]
	v_mfma_f32_16x16x32_bf16 v[8:11], v[156:159], v[104:107], v[8:11]
	ds_write_b128 v131, v[56:59] offset:18560
	v_mfma_f32_16x16x32_bf16 v[4:7], v[156:159], v[108:111], v[4:7]
	v_mfma_f32_16x16x32_bf16 v[0:3], v[156:159], v[112:115], v[0:3]
	ds_write_b128 v131, v[52:55] offset:20608
	ds_write_b128 v131, v[48:51] offset:22656
	s_cmp_lt_u32 s17, 14
	s_mov_b32 s14, s17
	s_waitcnt lgkmcnt(0)
	s_barrier
	s_waitcnt vmcnt(3)
	v_mfma_f32_16x16x32_bf16 v[60:63], v[80:83], v[84:87], v[100:103]
	s_add_i32 s14, s22, -12
	s_cmp_gt_u32 s14, 4
	s_waitcnt vmcnt(2)
	v_mfma_f32_16x16x32_bf16 v[56:59], v[80:83], v[104:107], v[96:99]
	s_waitcnt vmcnt(1)
	v_mfma_f32_16x16x32_bf16 v[52:55], v[80:83], v[108:111], v[92:95]
	s_waitcnt vmcnt(0)
	v_mfma_f32_16x16x32_bf16 v[48:51], v[80:83], v[112:115], v[88:91]
	s_cbranch_scc1 .LBB0_428
; __device__ void phase_inproj(const Params& p, int layer, char* smem) {
;     ...
;     if (cb >= 12 && cb <= 16) {
; #pragma unroll
;       for (int m = 0; m < 4; ++m)
; #pragma unroll
;         for (int j = 0; j < 4; ++j) {
;           int row = row0 + m * 16 + fq * 4 + j;
;           int pos = row & (SEQ - 1);
; #pragma unroll
;           for (int n = 0; n < 2; ++n) {
;             float2 cs2 = RT[pos * 32 + n * 16 + fr];
;             float c = cs2.x, s = cs2.y;
;             float x1 = acc[m][n][j], x2 = acc[m][n + 2][j];
;             acc[m][n][j] = x1 * c - x2 * s;
;             acc[m][n + 2][j] = x2 * c + x1 * s;
;           }
;         }
;     }
	v_lshl_add_u32 v64, s16, 7, v126
	v_and_or_b32 v64, v64, s43, v127
	v_lshl_or_b32 v116, v64, 8, v128
	v_lshl_add_u64 v[92:93], s[12:13], 0, v[116:117]
	v_add_co_u32_e32 v94, vcc, s48, v92
	global_load_dwordx2 v[68:69], v116, s[12:13]
	global_load_dwordx2 v[64:65], v116, s[12:13] offset:256
	global_load_dwordx2 v[66:67], v116, s[12:13] offset:384
	global_load_dwordx2 v[72:73], v116, s[12:13] offset:512
	global_load_dwordx2 v[76:77], v116, s[12:13] offset:128
	global_load_dwordx2 v[74:75], v116, s[12:13] offset:640
	global_load_dwordx2 v[70:71], v116, s[12:13] offset:768
	global_load_dwordx2 v[78:79], v116, s[12:13] offset:896
	v_addc_co_u32_e32 v95, vcc, 0, v93, vcc
	v_add_co_u32_e32 v96, vcc, s49, v92
	s_waitcnt vmcnt(7)
	v_mov_b32_e32 v124, v68
	v_addc_co_u32_e32 v97, vcc, 0, v93, vcc
	global_load_dwordx2 v[82:83], v[96:97], off offset:-4096
	global_load_dwordx2 v[80:81], v[94:95], off offset:256
	global_load_dwordx2 v[84:85], v[94:95], off offset:384
	global_load_dwordx2 v[88:89], v[94:95], off offset:512
	global_load_dwordx2 v[98:99], v[94:95], off offset:128
	global_load_dwordx2 v[90:91], v[94:95], off offset:640
	global_load_dwordx2 v[86:87], v[94:95], off offset:768
	s_waitcnt vmcnt(13)
	v_mov_b32_e32 v125, v64
	v_mov_b32_e32 v64, v69
	s_waitcnt vmcnt(10)
	v_mov_b32_e32 v68, v76
	v_mul_f32_e32 v76, v46, v72
	v_mul_f32_e32 v130, v38, v73
	v_mul_f32_e32 v72, v38, v72
	v_mul_f32_e32 v132, v46, v73
	s_waitcnt vmcnt(9)
	v_mul_f32_e32 v134, v42, v74
	v_mul_f32_e32 v138, v42, v75
	v_mov_b32_e32 v38, v47
	v_mov_b32_e32 v46, v39
	v_mov_b32_e32 v42, v35
	v_add_co_u32_e32 v92, vcc, s50, v92
	v_mov_b32_e32 v69, v66
	v_mov_b32_e32 v66, v77
	v_mul_f32_e32 v136, v34, v75
	v_mul_f32_e32 v74, v34, v74
	v_mov_b32_e32 v34, v43
	v_pk_mul_f32 v[140:141], v[44:45], v[64:65]
	v_pk_mul_f32 v[64:65], v[36:37], v[64:65]
	s_waitcnt vmcnt(8)
	v_pk_mul_f32 v[38:39], v[38:39], v[70:71]
	v_pk_mul_f32 v[46:47], v[46:47], v[70:71]
	s_waitcnt vmcnt(7)
	v_pk_mul_f32 v[42:43], v[42:43], v[78:79]
	v_addc_co_u32_e32 v93, vcc, 0, v93, vcc
	v_pk_mul_f32 v[142:143], v[40:41], v[66:67]
	v_pk_mul_f32 v[66:67], v[32:33], v[66:67]
	v_pk_mul_f32 v[34:35], v[34:35], v[78:79]
	v_mov_b32_e32 v77, v38
	v_mov_b32_e32 v131, v39
	v_pk_fma_f32 v[44:45], v[44:45], v[124:125], v[64:65] neg_lo:[0,0,1] neg_hi:[0,0,1]
	v_mov_b32_e32 v73, v46
	v_mov_b32_e32 v133, v47
	v_mov_b32_e32 v75, v42
	v_mov_b32_e32 v139, v43
	global_load_dwordx2 v[94:95], v[94:95], off offset:896
	s_nop 0
	global_load_dwordx2 v[100:101], v[96:97], off
	global_load_dwordx2 v[102:103], v[96:97], off offset:256
	global_load_dwordx2 v[104:105], v[96:97], off offset:384
	global_load_dwordx2 v[106:107], v[96:97], off offset:128
	global_load_dwordx2 v[108:109], v[96:97], off offset:512
	global_load_dwordx2 v[110:111], v[96:97], off offset:640
	global_load_dwordx2 v[112:113], v[96:97], off offset:768
	s_nop 0
	global_load_dwordx2 v[96:97], v[96:97], off offset:896
	s_nop 0
	global_load_dwordx2 v[114:115], v[92:93], off offset:640
	global_load_dwordx2 v[120:121], v[92:93], off offset:768
	global_load_dwordx2 v[122:123], v[92:93], off offset:896
	v_mov_b32_e32 v135, v34
	v_mov_b32_e32 v137, v35
	v_pk_fma_f32 v[40:41], v[40:41], v[68:69], v[66:67] neg_lo:[0,0,1] neg_hi:[0,0,1]
	v_pk_fma_f32 v[32:33], v[32:33], v[68:69], v[142:143]
	v_pk_add_f32 v[46:47], v[76:77], v[130:131] neg_lo:[0,1] neg_hi:[0,1]
	v_pk_add_f32 v[38:39], v[72:73], v[132:133]
	v_pk_add_f32 v[34:35], v[74:75], v[138:139]
	global_load_dwordx2 v[74:75], v[92:93], off
	global_load_dwordx2 v[76:77], v[92:93], off offset:256
	v_pk_fma_f32 v[36:37], v[36:37], v[124:125], v[140:141]
	v_pk_add_f32 v[42:43], v[134:135], v[136:137] neg_lo:[0,1] neg_hi:[0,1]
	s_waitcnt vmcnt(20)
	v_mov_b32_e32 v64, v82
	s_waitcnt vmcnt(19)
	v_mov_b32_e32 v65, v80
	v_mov_b32_e32 v80, v83
	s_waitcnt vmcnt(18)
	v_mov_b32_e32 v71, v84
	s_waitcnt vmcnt(16)
	v_mov_b32_e32 v84, v99
	v_pk_mul_f32 v[66:67], v[28:29], v[80:81]
	v_pk_mul_f32 v[68:69], v[20:21], v[80:81]
	v_pk_mul_f32 v[72:73], v[24:25], v[84:85]
	v_pk_mul_f32 v[78:79], v[16:17], v[84:85]
	global_load_dwordx2 v[80:81], v[92:93], off offset:384
	global_load_dwordx2 v[82:83], v[92:93], off offset:512
	global_load_dwordx2 v[84:85], v[92:93], off offset:128
	v_mov_b32_e32 v70, v98
	v_mul_f32_e32 v92, v30, v88
	v_mul_f32_e32 v98, v22, v89
	v_mul_f32_e32 v88, v22, v88
	v_mul_f32_e32 v124, v30, v89
	s_waitcnt vmcnt(18)
	v_mul_f32_e32 v130, v26, v90
	v_mul_f32_e32 v132, v18, v91
	v_mul_f32_e32 v90, v18, v90
	v_mul_f32_e32 v134, v26, v91
	v_mov_b32_e32 v22, v31
	v_mov_b32_e32 v30, v23
	v_mov_b32_e32 v18, v27
	v_mov_b32_e32 v26, v19
	s_waitcnt vmcnt(17)
; __device__ void phase_inproj(const Params& p, int layer, char* smem) {
;     ...
;     if (cb >= 12 && cb <= 16) {
; #pragma unroll
;       for (int m = 0; m < 4; ++m)
; #pragma unroll
;         for (int j = 0; j < 4; ++j) {
;           int row = row0 + m * 16 + fq * 4 + j;
;           int pos = row & (SEQ - 1);
; #pragma unroll
;           for (int n = 0; n < 2; ++n) {
;             float2 cs2 = RT[pos * 32 + n * 16 + fr];
;             float c = cs2.x, s = cs2.y;
;             float x1 = acc[m][n][j], x2 = acc[m][n + 2][j];
;             acc[m][n][j] = x1 * c - x2 * s;
;             acc[m][n + 2][j] = x2 * c + x1 * s;
;           }
;         }
;     }
	v_pk_mul_f32 v[136:137], v[22:23], v[86:87]
	v_pk_mul_f32 v[22:23], v[30:31], v[86:87]
	v_mov_b32_e32 v93, v136
	v_mov_b32_e32 v89, v22
	v_mov_b32_e32 v125, v23
	v_mov_b32_e32 v99, v137
	v_pk_add_f32 v[22:23], v[88:89], v[124:125]
	v_pk_fma_f32 v[24:25], v[24:25], v[70:71], v[78:79] neg_lo:[0,0,1] neg_hi:[0,0,1]
	v_pk_fma_f32 v[16:17], v[16:17], v[70:71], v[72:73]
	s_waitcnt vmcnt(16)
	v_pk_mul_f32 v[30:31], v[18:19], v[94:95]
	v_pk_mul_f32 v[18:19], v[26:27], v[94:95]
	s_waitcnt vmcnt(14)
	v_mov_b32_e32 v27, v102
	v_mov_b32_e32 v91, v18
	v_mov_b32_e32 v135, v19
	v_pk_add_f32 v[18:19], v[90:91], v[134:135]
	v_mov_b32_e32 v102, v101
	s_waitcnt vmcnt(13)
	v_mov_b32_e32 v71, v104
	s_waitcnt vmcnt(12)
	v_mov_b32_e32 v104, v107
	s_waitcnt vmcnt(11)
	v_mul_f32_e32 v88, v6, v109
	v_mul_f32_e32 v90, v6, v108
	v_mov_b32_e32 v6, v15
	v_pk_fma_f32 v[28:29], v[28:29], v[64:65], v[68:69] neg_lo:[0,0,1] neg_hi:[0,0,1]
	v_pk_add_f32 v[68:69], v[92:93], v[98:99] neg_lo:[0,1] neg_hi:[0,1]
	v_pk_fma_f32 v[20:21], v[20:21], v[64:65], v[66:67]
	v_mov_b32_e32 v26, v100
	v_pk_mul_f32 v[64:65], v[12:13], v[102:103]
	v_pk_mul_f32 v[66:67], v[4:5], v[102:103]
	v_mov_b32_e32 v70, v106
	v_pk_mul_f32 v[72:73], v[8:9], v[104:105]
	v_pk_mul_f32 v[78:79], v[0:1], v[104:105]
	v_mul_f32_e32 v86, v14, v108
	v_mul_f32_e32 v92, v14, v109
	s_waitcnt vmcnt(10)
	v_mul_f32_e32 v94, v10, v110
	v_mul_f32_e32 v98, v2, v111
	v_mul_f32_e32 v100, v2, v110
	v_mul_f32_e32 v102, v10, v111
	s_waitcnt vmcnt(9)
	v_pk_mul_f32 v[104:105], v[6:7], v[112:113]
	v_mov_b32_e32 v14, v7
	v_mov_b32_e32 v2, v11
	v_mov_b32_e32 v10, v3
	v_mov_b32_e32 v87, v104
	v_mov_b32_e32 v89, v105
	v_pk_mul_f32 v[6:7], v[14:15], v[112:113]
	s_waitcnt vmcnt(8)
	v_pk_mul_f32 v[14:15], v[2:3], v[96:97]
	v_pk_fma_f32 v[8:9], v[8:9], v[70:71], v[78:79] neg_lo:[0,0,1] neg_hi:[0,0,1]
	v_pk_mul_f32 v[2:3], v[10:11], v[96:97]
	v_pk_fma_f32 v[0:1], v[0:1], v[70:71], v[72:73]
	s_waitcnt vmcnt(3)
	v_mov_b32_e32 v11, v76
	v_mov_b32_e32 v76, v75
	v_pk_fma_f32 v[12:13], v[12:13], v[26:27], v[66:67] neg_lo:[0,0,1] neg_hi:[0,0,1]
	v_pk_add_f32 v[66:67], v[86:87], v[88:89] neg_lo:[0,1] neg_hi:[0,1]
	v_mov_b32_e32 v91, v6
	v_mov_b32_e32 v93, v7
	v_pk_fma_f32 v[4:5], v[4:5], v[26:27], v[64:65]
	v_mov_b32_e32 v10, v74
	v_pk_mul_f32 v[26:27], v[60:61], v[76:77]
	v_pk_mul_f32 v[64:65], v[52:53], v[76:77]
	v_mul_f32_e32 v86, v50, v115
	v_mul_f32_e32 v88, v50, v114
	v_mov_b32_e32 v50, v59
	v_pk_add_f32 v[6:7], v[90:91], v[92:93]
	v_mul_f32_e32 v90, v58, v115
	v_pk_fma_f32 v[60:61], v[60:61], v[10:11], v[64:65] neg_lo:[0,0,1] neg_hi:[0,0,1]
	v_pk_fma_f32 v[52:53], v[52:53], v[10:11], v[26:27]
	s_waitcnt vmcnt(2)
	v_mov_b32_e32 v71, v80
	s_waitcnt vmcnt(1)
	v_mul_f32_e32 v78, v54, v83
	s_waitcnt vmcnt(0)
	v_mov_b32_e32 v80, v85
	v_pk_mul_f32 v[72:73], v[56:57], v[80:81]
	v_pk_mul_f32 v[74:75], v[48:49], v[80:81]
	v_mul_f32_e32 v80, v54, v82
	v_mov_b32_e32 v54, v63
	v_mov_b32_e32 v70, v84
	v_mul_f32_e32 v76, v62, v82
	v_mul_f32_e32 v82, v62, v83
	v_mul_f32_e32 v84, v58, v114
	v_pk_mul_f32 v[92:93], v[54:55], v[120:121]
	v_mov_b32_e32 v62, v55
	v_pk_mul_f32 v[10:11], v[50:51], v[122:123]
	v_mov_b32_e32 v58, v51
	v_mov_b32_e32 v131, v30
	v_mov_b32_e32 v133, v31
	v_mov_b32_e32 v95, v14
	v_mov_b32_e32 v99, v15
	v_mov_b32_e32 v77, v92
	v_mov_b32_e32 v79, v93
	v_pk_mul_f32 v[54:55], v[62:63], v[120:121]
	v_mov_b32_e32 v85, v10
	v_mov_b32_e32 v87, v11
	v_pk_mul_f32 v[26:27], v[58:59], v[122:123]
	v_pk_add_f32 v[30:31], v[130:131], v[132:133] neg_lo:[0,1] neg_hi:[0,1]
	v_pk_add_f32 v[14:15], v[94:95], v[98:99] neg_lo:[0,1] neg_hi:[0,1]
	v_mov_b32_e32 v101, v2
	v_mov_b32_e32 v103, v3
	v_pk_add_f32 v[64:65], v[76:77], v[78:79] neg_lo:[0,1] neg_hi:[0,1]
	v_mov_b32_e32 v81, v54
	v_mov_b32_e32 v83, v55
	v_pk_add_f32 v[10:11], v[84:85], v[86:87] neg_lo:[0,1] neg_hi:[0,1]
	v_mov_b32_e32 v89, v26
	v_mov_b32_e32 v91, v27
	v_pk_add_f32 v[2:3], v[100:101], v[102:103]
	v_pk_add_f32 v[54:55], v[80:81], v[82:83]
	v_pk_fma_f32 v[56:57], v[56:57], v[70:71], v[74:75] neg_lo:[0,0,1] neg_hi:[0,0,1]
	v_pk_fma_f32 v[48:49], v[48:49], v[70:71], v[72:73]
	v_pk_add_f32 v[50:51], v[88:89], v[90:91]
	v_mov_b32_e32 v58, v10
	v_mov_b32_e32 v59, v11
	v_mov_b32_e32 v62, v64
	v_mov_b32_e32 v63, v65
	v_mov_b32_e32 v10, v14
	v_mov_b32_e32 v11, v15
	v_mov_b32_e32 v14, v66
	v_mov_b32_e32 v15, v67
	v_mov_b32_e32 v26, v30
	v_mov_b32_e32 v27, v31
	v_mov_b32_e32 v30, v68
	v_mov_b32_e32 v31, v69

; template <int WM, int WN> ...
;     ...
; #pragma unroll
;   for (int n = 0; n < 4; ++n) fb0[n] = LDSF(cur + boff + n * 1024);
; #pragma unroll
;   for (int m = 0; m < 4; ++m) fa0[m] = LDSF(cur + aoff + m * 1024);
;   acc[3][0] = MFMA16(pa, pb0, acc[3][0]);
;   acc[3][1] = MFMA16(pa, pb1, acc[3][1]);
;   acc[3][2] = MFMA16(pa, pb2, acc[3][2]);
;   acc[3][3] = MFMA16(pa, pb3, acc[3][3]);
; #pragma unroll
;   for (int n = 0; n < 4; ++n) acc[0][n] = MFMA16(fa0[0], fb0[n], acc[0][n]);
; #pragma unroll
;   for (int m = 0; m < 4; ++m) fa1[m] = LDSF(cur + aoff + APAN + m * 1024);
; #pragma unroll
;   for (int n = 0; n < 4; ++n) acc[1][n] = MFMA16(fa0[1], fb0[n], acc[1][n]);
; #pragma unroll
;   for (int n = 0; n < 4; ++n) fb1[n] = LDSF(cur + boff + BPAN + n * 1024);
; #pragma unroll
;   for (int n = 0; n < 4; ++n) acc[2][n] = MFMA16(fa0[2], fb0[n], acc[2][n]);
;   *reinterpret_cast<uint4*>(nxt + wao) = a0;
;   *reinterpret_cast<uint4*>(nxt + wao + 32 * 64) = a1;
; #pragma unroll
;   for (int n = 0; n < 4; ++n) acc[3][n] = MFMA16(fa0[3], fb0[n], acc[3][n]);
;   *reinterpret_cast<uint4*>(nxt + wao + 64 * 64) = a2;
;   *reinterpret_cast<uint4*>(nxt + wao + 96 * 64) = a3;
; #pragma unroll
;   for (int n = 0; n < 4; ++n) acc[0][n] = MFMA16(fa1[0], fb1[n], acc[0][n]);
;   *reinterpret_cast<uint4*>(nxt + wbo) = b0;
;   *reinterpret_cast<uint4*>(nxt + wbo + 32 * 64) = b1;
; #pragma unroll
;   for (int n = 0; n < 4; ++n) acc[1][n] = MFMA16(fa1[1], fb1[n], acc[1][n]);
;   *reinterpret_cast<uint4*>(nxt + wbo + 64 * 64) = b2;
;   *reinterpret_cast<uint4*>(nxt + wbo + 96 * 64) = b3;
; #pragma unroll
;   for (int n = 0; n < 4; ++n) acc[2][n] = MFMA16(fa1[2], fb1[n], acc[2][n]);
;   pa = fa1[3];
;   pb0 = fb1[0]; pb1 = fb1[1]; pb2 = fb1[2]; pb3 = fb1[3];
;   SGB_(0x100, 5);
;   SGB_(0x008, 4);
; #pragma unroll
;   for (int i_ = 0; i_ < 11; ++i_) { SGB_(0x008, 1); SGB_(0x100, 1); }
; #pragma unroll
;   for (int i_ = 0; i_ < 8; ++i_) { SGB_(0x008, 2); SGB_(0x200, 1); SGB_(0x020, 1); }
;   SGB_(0x008, 1);
; }
; template <int WM, int WN, typename SrcF, typename PostF>
; __device__ __forceinline__ void gemm_stream(const int nsteps, SrcF src, PostF post, f32x4 (&acc)[WM][WN], char* smem) {
;     ...
;   for (int kt = 0; kt < nsteps; kt += 2) {
;     {
;       TileSrc s = src(min(kt + 2, nsteps - 1));
;       GLOAD_TILE(xa, s.a, s.lda, ACH);
;       GLOAD_TILE(xb, s.b, s.ldb, BCH);
;     }
.LBB0_639:
	s_add_i32 s44, s13, 2
	s_add_i32 s13, s13, 4
	s_min_u32 s13, s13, 15
	s_lshl_b32 s13, s13, 7
	s_add_u32 s92, s16, s13
	s_addc_u32 s93, s17, 0
	s_add_u32 s94, s20, s13
	s_addc_u32 s95, s21, 0
	ds_read_b128 v[144:147], v124
	ds_read_b128 v[128:131], v125 offset:16512
	ds_read_b128 v[132:135], v125 offset:17536
	ds_read_b128 v[136:139], v125 offset:18560
	ds_read_b128 v[140:143], v125 offset:19584
	v_mfma_f32_16x16x32_bf16 v[64:67], v[48:51], v[64:67], v[92:95]
	v_mfma_f32_16x16x32_bf16 v[88:91], v[48:51], v[104:107], v[88:91]
	s_waitcnt vmcnt(4)
	ds_write_b128 v126, v[32:35] offset:33024
	global_load_dwordx4 v[32:35], v116, s[92:93]
	s_add_u32 s48, s16, s13
	s_addc_u32 s49, s17, 0
	v_mfma_f32_16x16x32_bf16 v[80:83], v[48:51], v[112:115], v[80:83]
	v_mfma_f32_16x16x32_bf16 v[48:51], v[48:51], v[108:111], v[56:59]
	s_waitcnt lgkmcnt(4)
	v_mfma_f32_16x16x32_bf16 v[56:59], v[144:147], v[128:131], v[100:103]
	ds_read_b128 v[92:95], v124 offset:1024
	s_waitcnt lgkmcnt(4)
	v_mfma_f32_16x16x32_bf16 v[96:99], v[144:147], v[132:135], v[96:99]
	ds_write_b128 v126, v[20:23] offset:35072
	global_load_dwordx4 v[20:23], v118, s[92:93]
	ds_read_b128 v[100:103], v124 offset:2048
	s_waitcnt lgkmcnt(5)
	v_mfma_f32_16x16x32_bf16 v[84:87], v[144:147], v[136:139], v[84:87]
	ds_read_b128 v[104:107], v124 offset:3072
	s_waitcnt lgkmcnt(5)
	v_mfma_f32_16x16x32_bf16 v[76:79], v[144:147], v[140:143], v[76:79]
	ds_read_b128 v[108:111], v124 offset:8256
	s_waitcnt lgkmcnt(4)
	v_mfma_f32_16x16x32_bf16 v[72:75], v[92:95], v[128:131], v[72:75]
	ds_read_b128 v[112:115], v124 offset:9280
	v_mfma_f32_16x16x32_bf16 v[68:71], v[92:95], v[132:135], v[68:71]
	ds_read_b128 v[144:147], v124 offset:10304
	v_mfma_f32_16x16x32_bf16 v[60:63], v[92:95], v[136:139], v[60:63]
	ds_write_b128 v126, v[16:19] offset:37120
	global_load_dwordx4 v[16:19], v120, s[92:93]
	ds_read_b128 v[148:151], v124 offset:11328
	v_mfma_f32_16x16x32_bf16 v[52:55], v[92:95], v[140:143], v[52:55]
	ds_read_b128 v[92:95], v125 offset:24768
	s_waitcnt lgkmcnt(7)
	v_mfma_f32_16x16x32_bf16 v[44:47], v[100:103], v[128:131], v[44:47]
	ds_read_b128 v[152:155], v125 offset:25792
	v_mfma_f32_16x16x32_bf16 v[40:43], v[100:103], v[132:135], v[40:43]
	ds_read_b128 v[156:159], v125 offset:26816
	v_mfma_f32_16x16x32_bf16 v[36:39], v[100:103], v[136:139], v[36:39]
	ds_write_b128 v126, v[24:27] offset:39168
	global_load_dwordx4 v[24:27], v122, s[92:93]
	ds_read_b128 v[160:163], v125 offset:27840
	v_mfma_f32_16x16x32_bf16 v[28:31], v[100:103], v[140:143], v[28:31]
	s_waitcnt lgkmcnt(10)
	v_mfma_f32_16x16x32_bf16 v[64:67], v[104:107], v[128:131], v[64:67]
	v_mfma_f32_16x16x32_bf16 v[88:91], v[104:107], v[132:135], v[88:91]
	v_mfma_f32_16x16x32_bf16 v[80:83], v[104:107], v[136:139], v[80:83]
	v_mfma_f32_16x16x32_bf16 v[48:51], v[104:107], v[140:143], v[48:51]
	s_waitcnt vmcnt(4)
	ds_write_b128 v126, v[12:15] offset:49536
	global_load_dwordx4 v[12:15], v116, s[94:95]
	s_waitcnt lgkmcnt(5)
	v_mfma_f32_16x16x32_bf16 v[56:59], v[108:111], v[92:95], v[56:59]
	s_add_u32 s48, s20, s13
	s_addc_u32 s49, s21, 0
	s_waitcnt lgkmcnt(4)
	v_mfma_f32_16x16x32_bf16 v[96:99], v[108:111], v[152:155], v[96:99]
	s_min_u32 s13, s44, 12
	s_lshl_b32 s13, s13, 7
	s_waitcnt lgkmcnt(3)
	v_mfma_f32_16x16x32_bf16 v[84:87], v[108:111], v[156:159], v[84:87]
	s_waitcnt lgkmcnt(1)
	v_mfma_f32_16x16x32_bf16 v[76:79], v[108:111], v[160:163], v[76:79]
	ds_write_b128 v126, v[8:11] offset:51584
	global_load_dwordx4 v[8:11], v118, s[94:95]
	v_mfma_f32_16x16x32_bf16 v[72:75], v[112:115], v[92:95], v[72:75]
	v_mfma_f32_16x16x32_bf16 v[68:71], v[112:115], v[152:155], v[68:71]
	v_mfma_f32_16x16x32_bf16 v[60:63], v[112:115], v[156:159], v[60:63]
	v_mfma_f32_16x16x32_bf16 v[52:55], v[112:115], v[160:163], v[52:55]
	v_mfma_f32_16x16x32_bf16 v[44:47], v[144:147], v[92:95], v[44:47]
	ds_write_b128 v126, v[4:7] offset:53632
	global_load_dwordx4 v[4:7], v120, s[94:95]
	v_mfma_f32_16x16x32_bf16 v[40:43], v[144:147], v[152:155], v[40:43]
	s_add_u32 s48, s16, s13
	s_addc_u32 s49, s17, 0
	s_add_u32 s50, s20, s13
	v_mfma_f32_16x16x32_bf16 v[36:39], v[144:147], v[156:159], v[36:39]
	s_addc_u32 s51, s21, 0
	v_mfma_f32_16x16x32_bf16 v[28:31], v[144:147], v[160:163], v[28:31]
	v_mfma_f32_16x16x32_bf16 v[92:95], v[148:151], v[92:95], v[64:67]
	ds_write_b128 v126, v[0:3] offset:55680
	global_load_dwordx4 v[0:3], v122, s[94:95]
	v_mfma_f32_16x16x32_bf16 v[88:91], v[148:151], v[152:155], v[88:91]
	v_mfma_f32_16x16x32_bf16 v[80:83], v[148:151], v[156:159], v[80:83]
	v_mfma_f32_16x16x32_bf16 v[100:103], v[148:151], v[160:163], v[48:51]
	s_waitcnt lgkmcnt(0)
	s_barrier
; template <int WM, int WN> ...
;     ...
; #pragma unroll
;   for (int n = 0; n < 4; ++n) fb0[n] = LDSF(cur + boff + n * 1024);
; #pragma unroll
;   for (int m = 0; m < 4; ++m) fa0[m] = LDSF(cur + aoff + m * 1024);
;   acc[3][0] = MFMA16(pa, pb0, acc[3][0]);
;   acc[3][1] = MFMA16(pa, pb1, acc[3][1]);
;   acc[3][2] = MFMA16(pa, pb2, acc[3][2]);
;   acc[3][3] = MFMA16(pa, pb3, acc[3][3]);
; #pragma unroll
;   for (int n = 0; n < 4; ++n) acc[0][n] = MFMA16(fa0[0], fb0[n], acc[0][n]);
; #pragma unroll
;   for (int m = 0; m < 4; ++m) fa1[m] = LDSF(cur + aoff + APAN + m * 1024);
; #pragma unroll
;   for (int n = 0; n < 4; ++n) acc[1][n] = MFMA16(fa0[1], fb0[n], acc[1][n]);
; #pragma unroll
;   for (int n = 0; n < 4; ++n) fb1[n] = LDSF(cur + boff + BPAN + n * 1024);
; #pragma unroll
;   for (int n = 0; n < 4; ++n) acc[2][n] = MFMA16(fa0[2], fb0[n], acc[2][n]);
;   *reinterpret_cast<uint4*>(nxt + wao) = a0;
;   *reinterpret_cast<uint4*>(nxt + wao + 32 * 64) = a1;
; #pragma unroll
;   for (int n = 0; n < 4; ++n) acc[3][n] = MFMA16(fa0[3], fb0[n], acc[3][n]);
;   *reinterpret_cast<uint4*>(nxt + wao + 64 * 64) = a2;
;   *reinterpret_cast<uint4*>(nxt + wao + 96 * 64) = a3;
; #pragma unroll
;   for (int n = 0; n < 4; ++n) acc[0][n] = MFMA16(fa1[0], fb1[n], acc[0][n]);
;   *reinterpret_cast<uint4*>(nxt + wbo) = b0;
;   *reinterpret_cast<uint4*>(nxt + wbo + 32 * 64) = b1;
; #pragma unroll
;   for (int n = 0; n < 4; ++n) acc[1][n] = MFMA16(fa1[1], fb1[n], acc[1][n]);
;   *reinterpret_cast<uint4*>(nxt + wbo + 64 * 64) = b2;
;   *reinterpret_cast<uint4*>(nxt + wbo + 96 * 64) = b3;
; #pragma unroll
;   for (int n = 0; n < 4; ++n) acc[2][n] = MFMA16(fa1[2], fb1[n], acc[2][n]);
;   pa = fa1[3];
;   pb0 = fb1[0]; pb1 = fb1[1]; pb2 = fb1[2]; pb3 = fb1[3];
;   SGB_(0x100, 5);
;   SGB_(0x008, 4);
; #pragma unroll
;   for (int i_ = 0; i_ < 11; ++i_) { SGB_(0x008, 1); SGB_(0x100, 1); }
; #pragma unroll
;   for (int i_ = 0; i_ < 8; ++i_) { SGB_(0x008, 2); SGB_(0x200, 1); SGB_(0x020, 1); }
;   SGB_(0x008, 1);
; }
; template <int WM, int WN, typename SrcF, typename PostF>
; __device__ __forceinline__ void gemm_stream(const int nsteps, SrcF src, PostF post, f32x4 (&acc)[WM][WN], char* smem) {
;     ...
;       TileSrc s = src(min(kt + 3, nsteps - 1));
;       GLOAD_TILE(ya, s.a, s.lda, ACH);
;       GLOAD_TILE(yb, s.b, s.ldb, BCH);
;     }
	s_nop 0
	ds_read_b128 v[48:51], v124 offset:33024
	ds_read_b128 v[108:111], v125 offset:49536
	ds_read_b128 v[128:131], v125 offset:50560
	ds_read_b128 v[132:135], v125 offset:51584
	ds_read_b128 v[136:139], v125 offset:52608
	s_waitcnt lgkmcnt(3)
	v_mfma_f32_16x16x32_bf16 v[140:143], v[48:51], v[108:111], v[56:59]
	s_waitcnt lgkmcnt(2)
	v_mfma_f32_16x16x32_bf16 v[96:99], v[48:51], v[128:131], v[96:99]
	s_waitcnt vmcnt(4)
	ds_write_b128 v126, v[32:35]
	global_load_dwordx4 v[32:35], v116, s[48:49] offset:384
	s_waitcnt lgkmcnt(2)
	v_mfma_f32_16x16x32_bf16 v[84:87], v[48:51], v[132:135], v[84:87]
	s_waitcnt lgkmcnt(0)
	v_mfma_f32_16x16x32_bf16 v[76:79], v[48:51], v[136:139], v[76:79]
	ds_read_b128 v[48:51], v124 offset:34048
	s_waitcnt lgkmcnt(0)
	v_mfma_f32_16x16x32_bf16 v[72:75], v[48:51], v[108:111], v[72:75]
	ds_write_b128 v126, v[20:23] offset:2048
	global_load_dwordx4 v[20:23], v118, s[48:49] offset:384
	ds_read_b128 v[56:59], v124 offset:35072
	v_mfma_f32_16x16x32_bf16 v[68:71], v[48:51], v[128:131], v[68:71]
	ds_read_b128 v[144:147], v124 offset:36096
	v_mfma_f32_16x16x32_bf16 v[60:63], v[48:51], v[132:135], v[60:63]
	ds_read_b128 v[148:151], v124 offset:41280
	v_mfma_f32_16x16x32_bf16 v[52:55], v[48:51], v[136:139], v[52:55]
	ds_read_b128 v[152:155], v124 offset:42304
	s_waitcnt lgkmcnt(3)
	v_mfma_f32_16x16x32_bf16 v[44:47], v[56:59], v[108:111], v[44:47]
	ds_write_b128 v126, v[16:19] offset:4096
	global_load_dwordx4 v[16:19], v120, s[48:49] offset:384
	ds_read_b128 v[156:159], v124 offset:43328
	v_mfma_f32_16x16x32_bf16 v[40:43], v[56:59], v[128:131], v[40:43]
	ds_read_b128 v[48:51], v124 offset:44352
	v_mfma_f32_16x16x32_bf16 v[36:39], v[56:59], v[132:135], v[36:39]
	ds_read_b128 v[64:67], v125 offset:57792
	v_mfma_f32_16x16x32_bf16 v[28:31], v[56:59], v[136:139], v[28:31]
	ds_write_b128 v126, v[24:27] offset:6144
	global_load_dwordx4 v[24:27], v122, s[48:49] offset:384
	ds_read_b128 v[104:107], v125 offset:58816
	s_waitcnt lgkmcnt(8)
	v_mfma_f32_16x16x32_bf16 v[92:95], v[144:147], v[108:111], v[92:95]
	ds_read_b128 v[112:115], v125 offset:59840
	v_mfma_f32_16x16x32_bf16 v[88:91], v[144:147], v[128:131], v[88:91]
	ds_read_b128 v[108:111], v125 offset:60864
	v_mfma_f32_16x16x32_bf16 v[80:83], v[144:147], v[132:135], v[80:83]
	v_mfma_f32_16x16x32_bf16 v[56:59], v[144:147], v[136:139], v[100:103]
	s_waitcnt vmcnt(4)
	ds_write_b128 v126, v[12:15] offset:16512
	global_load_dwordx4 v[12:15], v116, s[50:51] offset:384
	s_waitcnt lgkmcnt(5)
	v_mfma_f32_16x16x32_bf16 v[100:103], v[148:151], v[64:67], v[140:143]
	s_waitcnt lgkmcnt(3)
	v_mfma_f32_16x16x32_bf16 v[96:99], v[148:151], v[104:107], v[96:99]
	s_waitcnt lgkmcnt(2)
	v_mfma_f32_16x16x32_bf16 v[84:87], v[148:151], v[112:115], v[84:87]
	ds_write_b128 v126, v[8:11] offset:18560
	global_load_dwordx4 v[8:11], v118, s[50:51] offset:384
	s_waitcnt lgkmcnt(2)
	v_mfma_f32_16x16x32_bf16 v[76:79], v[148:151], v[108:111], v[76:79]
	v_mfma_f32_16x16x32_bf16 v[72:75], v[152:155], v[64:67], v[72:75]
	v_mfma_f32_16x16x32_bf16 v[68:71], v[152:155], v[104:107], v[68:71]
	v_mfma_f32_16x16x32_bf16 v[60:63], v[152:155], v[112:115], v[60:63]
	ds_write_b128 v126, v[4:7] offset:20608
	global_load_dwordx4 v[4:7], v120, s[50:51] offset:384
	v_mfma_f32_16x16x32_bf16 v[52:55], v[152:155], v[108:111], v[52:55]
	v_mfma_f32_16x16x32_bf16 v[44:47], v[156:159], v[64:67], v[44:47]
	v_mfma_f32_16x16x32_bf16 v[40:43], v[156:159], v[104:107], v[40:43]
	ds_write_b128 v126, v[0:3] offset:22656
	global_load_dwordx4 v[0:3], v122, s[50:51] offset:384
	v_mfma_f32_16x16x32_bf16 v[36:39], v[156:159], v[112:115], v[36:39]
	v_mfma_f32_16x16x32_bf16 v[28:31], v[156:159], v[108:111], v[28:31]
	s_cmp_lt_u32 s44, 12
	s_mov_b32 s13, s44
	s_waitcnt lgkmcnt(0)
	s_barrier
	s_cbranch_scc1 .LBB0_639
	ds_read_b128 v[144:147], v124
	ds_read_b128 v[128:131], v125 offset:16512
	ds_read_b128 v[132:135], v125 offset:17536
	ds_read_b128 v[136:139], v125 offset:18560
	ds_read_b128 v[140:143], v125 offset:19584
	v_mfma_f32_16x16x32_bf16 v[64:67], v[48:51], v[64:67], v[92:95]
	s_add_i32 s44, s13, 2
	s_add_i32 s13, s13, 4
	s_min_u32 s13, s13, 15
	v_mfma_f32_16x16x32_bf16 v[88:91], v[48:51], v[104:107], v[88:91]
	s_lshl_b32 s13, s13, 7
	s_add_u32 s48, s16, s13
	s_addc_u32 s49, s17, 0
	v_mfma_f32_16x16x32_bf16 v[80:83], v[48:51], v[112:115], v[80:83]
	v_mfma_f32_16x16x32_bf16 v[48:51], v[48:51], v[108:111], v[56:59]
	s_waitcnt lgkmcnt(3)
	v_mfma_f32_16x16x32_bf16 v[56:59], v[144:147], v[128:131], v[100:103]
	ds_read_b128 v[92:95], v124 offset:1024
	s_waitcnt lgkmcnt(3)
	v_mfma_f32_16x16x32_bf16 v[96:99], v[144:147], v[132:135], v[96:99]
	ds_read_b128 v[100:103], v124 offset:2048
	s_waitcnt lgkmcnt(3)
	v_mfma_f32_16x16x32_bf16 v[84:87], v[144:147], v[136:139], v[84:87]
	ds_read_b128 v[104:107], v124 offset:3072
	s_waitcnt lgkmcnt(3)
	v_mfma_f32_16x16x32_bf16 v[76:79], v[144:147], v[140:143], v[76:79]
	ds_read_b128 v[108:111], v124 offset:8256
	s_waitcnt lgkmcnt(3)
	v_mfma_f32_16x16x32_bf16 v[72:75], v[92:95], v[128:131], v[72:75]
	ds_read_b128 v[112:115], v124 offset:9280
	v_mfma_f32_16x16x32_bf16 v[68:71], v[92:95], v[132:135], v[68:71]
	ds_read_b128 v[144:147], v124 offset:10304
	v_mfma_f32_16x16x32_bf16 v[60:63], v[92:95], v[136:139], v[60:63]
	ds_read_b128 v[148:151], v124 offset:11328
	v_mfma_f32_16x16x32_bf16 v[52:55], v[92:95], v[140:143], v[52:55]
	ds_read_b128 v[92:95], v125 offset:24768
	s_waitcnt lgkmcnt(6)
	v_mfma_f32_16x16x32_bf16 v[44:47], v[100:103], v[128:131], v[44:47]
	ds_read_b128 v[152:155], v125 offset:25792
	v_mfma_f32_16x16x32_bf16 v[40:43], v[100:103], v[132:135], v[40:43]
	ds_read_b128 v[156:159], v125 offset:26816
	v_mfma_f32_16x16x32_bf16 v[36:39], v[100:103], v[136:139], v[36:39]
	ds_read_b128 v[160:163], v125 offset:27840
	v_mfma_f32_16x16x32_bf16 v[28:31], v[100:103], v[140:143], v[28:31]
	s_waitcnt lgkmcnt(8)
; template <int WM, int WN> ...
;     ...
; #pragma unroll
;   for (int n = 0; n < 4; ++n) fb0[n] = LDSF(cur + boff + n * 1024);
; #pragma unroll
;   for (int m = 0; m < 4; ++m) fa0[m] = LDSF(cur + aoff + m * 1024);
;   acc[3][0] = MFMA16(pa, pb0, acc[3][0]);
;   acc[3][1] = MFMA16(pa, pb1, acc[3][1]);
;   acc[3][2] = MFMA16(pa, pb2, acc[3][2]);
;   acc[3][3] = MFMA16(pa, pb3, acc[3][3]);
; #pragma unroll
;   for (int n = 0; n < 4; ++n) acc[0][n] = MFMA16(fa0[0], fb0[n], acc[0][n]);
; #pragma unroll
;   for (int m = 0; m < 4; ++m) fa1[m] = LDSF(cur + aoff + APAN + m * 1024);
; #pragma unroll
;   for (int n = 0; n < 4; ++n) acc[1][n] = MFMA16(fa0[1], fb0[n], acc[1][n]);
; #pragma unroll
;   for (int n = 0; n < 4; ++n) fb1[n] = LDSF(cur + boff + BPAN + n * 1024);
; #pragma unroll
;   for (int n = 0; n < 4; ++n) acc[2][n] = MFMA16(fa0[2], fb0[n], acc[2][n]);
;   *reinterpret_cast<uint4*>(nxt + wao) = a0;
;   *reinterpret_cast<uint4*>(nxt + wao + 32 * 64) = a1;
; #pragma unroll
;   for (int n = 0; n < 4; ++n) acc[3][n] = MFMA16(fa0[3], fb0[n], acc[3][n]);
;   *reinterpret_cast<uint4*>(nxt + wao + 64 * 64) = a2;
;   *reinterpret_cast<uint4*>(nxt + wao + 96 * 64) = a3;
; #pragma unroll
;   for (int n = 0; n < 4; ++n) acc[0][n] = MFMA16(fa1[0], fb1[n], acc[0][n]);
;   *reinterpret_cast<uint4*>(nxt + wbo) = b0;
;   *reinterpret_cast<uint4*>(nxt + wbo + 32 * 64) = b1;
; #pragma unroll
;   for (int n = 0; n < 4; ++n) acc[1][n] = MFMA16(fa1[1], fb1[n], acc[1][n]);
;   *reinterpret_cast<uint4*>(nxt + wbo + 64 * 64) = b2;
;   *reinterpret_cast<uint4*>(nxt + wbo + 96 * 64) = b3;
; #pragma unroll
;   for (int n = 0; n < 4; ++n) acc[2][n] = MFMA16(fa1[2], fb1[n], acc[2][n]);
;   pa = fa1[3];
;   pb0 = fb1[0]; pb1 = fb1[1]; pb2 = fb1[2]; pb3 = fb1[3];
;   SGB_(0x100, 5);
;   SGB_(0x008, 4);
; #pragma unroll
;   for (int i_ = 0; i_ < 11; ++i_) { SGB_(0x008, 1); SGB_(0x100, 1); }
; #pragma unroll
;   for (int i_ = 0; i_ < 8; ++i_) { SGB_(0x008, 2); SGB_(0x200, 1); SGB_(0x020, 1); }
;   SGB_(0x008, 1);
; }
; template <int WM, int WN, typename SrcF, typename PostF>
; __device__ __forceinline__ void gemm_stream(const int nsteps, SrcF src, PostF post, f32x4 (&acc)[WM][WN], char* smem) {
;     ...
;       TileSrc s = src(min(kt + 3, nsteps - 1));
;       GLOAD_TILE(ya, s.a, s.lda, ACH);
;       GLOAD_TILE(yb, s.b, s.ldb, BCH);
;     }
	v_mfma_f32_16x16x32_bf16 v[64:67], v[104:107], v[128:131], v[64:67]
	s_waitcnt vmcnt(7)
	ds_write_b128 v126, v[32:35] offset:33024
	v_mfma_f32_16x16x32_bf16 v[88:91], v[104:107], v[132:135], v[88:91]
	v_mfma_f32_16x16x32_bf16 v[80:83], v[104:107], v[136:139], v[80:83]
	s_waitcnt vmcnt(6)
	ds_write_b128 v126, v[20:23] offset:35072
	v_mfma_f32_16x16x32_bf16 v[48:51], v[104:107], v[140:143], v[48:51]
	s_waitcnt lgkmcnt(5)
	v_mfma_f32_16x16x32_bf16 v[56:59], v[108:111], v[92:95], v[56:59]
	s_waitcnt vmcnt(5)
	ds_write_b128 v126, v[16:19] offset:37120
	s_add_u32 s48, s20, s13
	s_addc_u32 s49, s21, 0
	s_waitcnt lgkmcnt(5)
	v_mfma_f32_16x16x32_bf16 v[96:99], v[108:111], v[152:155], v[96:99]
	s_min_u32 s13, s44, 12
	s_lshl_b32 s13, s13, 7
	s_waitcnt lgkmcnt(4)
	v_mfma_f32_16x16x32_bf16 v[84:87], v[108:111], v[156:159], v[84:87]
	s_waitcnt vmcnt(4)
	ds_write_b128 v126, v[24:27] offset:39168
	s_waitcnt lgkmcnt(4)
	v_mfma_f32_16x16x32_bf16 v[76:79], v[108:111], v[160:163], v[76:79]
	v_mfma_f32_16x16x32_bf16 v[72:75], v[112:115], v[92:95], v[72:75]
	s_waitcnt vmcnt(3)
	ds_write_b128 v126, v[12:15] offset:49536
	v_mfma_f32_16x16x32_bf16 v[68:71], v[112:115], v[152:155], v[68:71]
	v_mfma_f32_16x16x32_bf16 v[60:63], v[112:115], v[156:159], v[60:63]
	s_waitcnt vmcnt(2)
	ds_write_b128 v126, v[8:11] offset:51584
	v_mfma_f32_16x16x32_bf16 v[52:55], v[112:115], v[160:163], v[52:55]
	v_mfma_f32_16x16x32_bf16 v[44:47], v[144:147], v[92:95], v[44:47]
	s_waitcnt vmcnt(1)
	ds_write_b128 v126, v[4:7] offset:53632
	v_mfma_f32_16x16x32_bf16 v[40:43], v[144:147], v[152:155], v[40:43]
	s_add_u32 s48, s16, s13
	s_addc_u32 s49, s17, 0
	s_add_u32 s50, s20, s13
	v_mfma_f32_16x16x32_bf16 v[36:39], v[144:147], v[156:159], v[36:39]
	s_waitcnt vmcnt(0)
	ds_write_b128 v126, v[0:3] offset:55680
	s_addc_u32 s51, s21, 0
	v_mfma_f32_16x16x32_bf16 v[28:31], v[144:147], v[160:163], v[28:31]
	v_mfma_f32_16x16x32_bf16 v[92:95], v[148:151], v[92:95], v[64:67]
	v_mfma_f32_16x16x32_bf16 v[88:91], v[148:151], v[152:155], v[88:91]
	v_mfma_f32_16x16x32_bf16 v[80:83], v[148:151], v[156:159], v[80:83]
	v_mfma_f32_16x16x32_bf16 v[100:103], v[148:151], v[160:163], v[48:51]
	s_waitcnt lgkmcnt(0)
	s_barrier
	s_nop 0
	ds_read_b128 v[48:51], v124 offset:33024
	ds_read_b128 v[108:111], v125 offset:49536
	ds_read_b128 v[128:131], v125 offset:50560
	ds_read_b128 v[132:135], v125 offset:51584
	ds_read_b128 v[136:139], v125 offset:52608
	s_waitcnt lgkmcnt(3)
	v_mfma_f32_16x16x32_bf16 v[140:143], v[48:51], v[108:111], v[56:59]
	s_waitcnt lgkmcnt(2)
	v_mfma_f32_16x16x32_bf16 v[96:99], v[48:51], v[128:131], v[96:99]
	s_waitcnt lgkmcnt(1)
	v_mfma_f32_16x16x32_bf16 v[84:87], v[48:51], v[132:135], v[84:87]
	s_waitcnt lgkmcnt(0)
	v_mfma_f32_16x16x32_bf16 v[76:79], v[48:51], v[136:139], v[76:79]
	ds_read_b128 v[48:51], v124 offset:34048
	s_waitcnt lgkmcnt(0)
	v_mfma_f32_16x16x32_bf16 v[72:75], v[48:51], v[108:111], v[72:75]
	ds_read_b128 v[56:59], v124 offset:35072
	v_mfma_f32_16x16x32_bf16 v[68:71], v[48:51], v[128:131], v[68:71]
	ds_read_b128 v[144:147], v124 offset:36096
	v_mfma_f32_16x16x32_bf16 v[60:63], v[48:51], v[132:135], v[60:63]
	ds_read_b128 v[148:151], v124 offset:41280
	v_mfma_f32_16x16x32_bf16 v[52:55], v[48:51], v[136:139], v[52:55]
	ds_read_b128 v[152:155], v124 offset:42304
	s_waitcnt lgkmcnt(3)
	v_mfma_f32_16x16x32_bf16 v[44:47], v[56:59], v[108:111], v[44:47]
	ds_read_b128 v[156:159], v124 offset:43328
	v_mfma_f32_16x16x32_bf16 v[40:43], v[56:59], v[128:131], v[40:43]
	ds_read_b128 v[48:51], v124 offset:44352
	v_mfma_f32_16x16x32_bf16 v[36:39], v[56:59], v[132:135], v[36:39]
	ds_read_b128 v[64:67], v125 offset:57792
	v_mfma_f32_16x16x32_bf16 v[28:31], v[56:59], v[136:139], v[28:31]
	ds_read_b128 v[104:107], v125 offset:58816
	s_waitcnt lgkmcnt(6)
	v_mfma_f32_16x16x32_bf16 v[92:95], v[144:147], v[108:111], v[92:95]
	ds_read_b128 v[112:115], v125 offset:59840
	v_mfma_f32_16x16x32_bf16 v[88:91], v[144:147], v[128:131], v[88:91]
	ds_read_b128 v[108:111], v125 offset:60864
	v_mfma_f32_16x16x32_bf16 v[80:83], v[144:147], v[132:135], v[80:83]
	v_mfma_f32_16x16x32_bf16 v[56:59], v[144:147], v[136:139], v[100:103]
	ds_write_b128 v126, v[32:35]
	s_waitcnt lgkmcnt(4)
	v_mfma_f32_16x16x32_bf16 v[100:103], v[148:151], v[64:67], v[140:143]
	s_waitcnt lgkmcnt(3)
	v_mfma_f32_16x16x32_bf16 v[96:99], v[148:151], v[104:107], v[96:99]
	ds_write_b128 v126, v[20:23] offset:2048
	s_waitcnt lgkmcnt(3)
	v_mfma_f32_16x16x32_bf16 v[84:87], v[148:151], v[112:115], v[84:87]
	s_waitcnt lgkmcnt(2)
	v_mfma_f32_16x16x32_bf16 v[76:79], v[148:151], v[108:111], v[76:79]
	ds_write_b128 v126, v[16:19] offset:4096
	v_mfma_f32_16x16x32_bf16 v[72:75], v[152:155], v[64:67], v[72:75]
	v_mfma_f32_16x16x32_bf16 v[68:71], v[152:155], v[104:107], v[68:71]
	ds_write_b128 v126, v[24:27] offset:6144
	v_mfma_f32_16x16x32_bf16 v[60:63], v[152:155], v[112:115], v[60:63]
	v_mfma_f32_16x16x32_bf16 v[52:55], v[152:155], v[108:111], v[52:55]
	ds_write_b128 v126, v[12:15] offset:16512
	v_mfma_f32_16x16x32_bf16 v[44:47], v[156:159], v[64:67], v[44:47]
	v_mfma_f32_16x16x32_bf16 v[40:43], v[156:159], v[104:107], v[40:43]
	ds_write_b128 v126, v[8:11] offset:18560
	v_mfma_f32_16x16x32_bf16 v[36:39], v[156:159], v[112:115], v[36:39]
	v_mfma_f32_16x16x32_bf16 v[28:31], v[156:159], v[108:111], v[28:31]
	ds_write_b128 v126, v[4:7] offset:20608
	ds_write_b128 v126, v[0:3] offset:22656
	s_cmp_lt_u32 s44, 14
	s_mov_b32 s13, s44
	s_waitcnt lgkmcnt(0)
	s_barrier
; #define MFMA16(a, b, c) __builtin_amdgcn_mfma_f32_16x16x32_bf16(a, b, c, 0, 0, 0)
; template <int WM, int WN, typename SrcF, typename PostF>
; __device__ __forceinline__ void gemm_stream(const int nsteps, SrcF src, PostF post, f32x4 (&acc)[WM][WN], char* smem) {
;     ...
;   acc[3][0] = MFMA16(pa, pb0, acc[3][0]);
;   acc[3][1] = MFMA16(pa, pb1, acc[3][1]);
;   acc[3][2] = MFMA16(pa, pb2, acc[3][2]);
;   acc[3][3] = MFMA16(pa, pb3, acc[3][3]);
; template <int WM, int WN>
; __device__ __forceinline__ void store_tile_bf16(const f32x4 (&acc)[WM][WN], u16* dst, int ld, char* smem) {
;   constexpr int BM = 32 * WM, BN = 32 * WN, STR = BN + 8;
;   const int tid = opaque_tid(), lane = tid & 63, wid = tid >> 6;
;   const int wr = wid >> 1, wc = wid & 1, fr = lane & 15, fq = lane >> 4;
;   u16* T = reinterpret_cast<u16*>(smem);
; #pragma unroll
;   for (int m = 0; m < WM; ++m)
; #pragma unroll
;     for (int n = 0; n < WN; ++n)
; #pragma unroll
;       for (int j = 0; j < 4; ++j)
;         T[(wr * 16 * WM + m * 16 + fq * 4 + j) * STR + wc * 16 * WN + n * 16 + fr] = f2bf(acc[m][n][j]);
;   __syncthreads();
	s_waitcnt vmcnt(5)
	v_mov_b32_e32 v16, v232
	s_waitcnt vmcnt(0)
	v_mfma_f32_16x16x32_bf16 v[0:3], v[48:51], v[64:67], v[92:95]
	v_lshrrev_b32_e32 v18, 2, v16
	v_lshrrev_b32_e32 v17, 1, v16
	v_and_b32_e32 v18, 12, v18
	v_and_or_b32 v17, v17, s40, v18
	v_and_b32_e32 v18, 0x4f, v16
	v_mul_lo_u32 v17, v17, s42
	v_lshl_add_u32 v17, v18, 1, v17
	v_cvt_pk_bf16_f32 v18, 0, v101
	ds_write_b16_d16_hi v17, v18 offset:272
	v_cvt_pk_bf16_f32 v18, 0, v102
	ds_write_b16_d16_hi v17, v18 offset:544
	v_cvt_pk_bf16_f32 v18, 0, v103
	ds_write_b16_d16_hi v17, v18 offset:816
	v_cvt_pk_bf16_f32 v18, 0, v96
	ds_write_b16_d16_hi v17, v18 offset:32
	v_cvt_pk_bf16_f32 v18, 0, v97
	ds_write_b16_d16_hi v17, v18 offset:304
	v_cvt_pk_bf16_f32 v18, 0, v98
	ds_write_b16_d16_hi v17, v18 offset:576
	v_cvt_pk_bf16_f32 v18, 0, v99
	ds_write_b16_d16_hi v17, v18 offset:848
	v_cvt_pk_bf16_f32 v18, 0, v84
	ds_write_b16_d16_hi v17, v18 offset:64
	v_cvt_pk_bf16_f32 v18, 0, v85
	ds_write_b16_d16_hi v17, v18 offset:336
	v_cvt_pk_bf16_f32 v18, 0, v86
	ds_write_b16_d16_hi v17, v18 offset:608
	v_cvt_pk_bf16_f32 v18, 0, v87
	ds_write_b16_d16_hi v17, v18 offset:880
	v_cvt_pk_bf16_f32 v18, 0, v76
	ds_write_b16_d16_hi v17, v18 offset:96
	v_cvt_pk_bf16_f32 v18, 0, v77
	ds_write_b16_d16_hi v17, v18 offset:368
	v_cvt_pk_bf16_f32 v18, 0, v78
	ds_write_b16_d16_hi v17, v18 offset:640
	v_cvt_pk_bf16_f32 v18, 0, v79
	ds_write_b16_d16_hi v17, v18 offset:912
	v_cvt_pk_bf16_f32 v18, 0, v72
	ds_write_b16_d16_hi v17, v18 offset:4352
	v_cvt_pk_bf16_f32 v18, 0, v73
	ds_write_b16_d16_hi v17, v18 offset:4624
	v_cvt_pk_bf16_f32 v18, 0, v74
	ds_write_b16_d16_hi v17, v18 offset:4896
	v_cvt_pk_bf16_f32 v18, 0, v75
	ds_write_b16_d16_hi v17, v18 offset:5168
	v_cvt_pk_bf16_f32 v18, 0, v68
	ds_write_b16_d16_hi v17, v18 offset:4384
	v_cvt_pk_bf16_f32 v18, 0, v69
	ds_write_b16_d16_hi v17, v18 offset:4656
	v_cvt_pk_bf16_f32 v18, 0, v70
	ds_write_b16_d16_hi v17, v18 offset:4928
	v_cvt_pk_bf16_f32 v18, 0, v71
	ds_write_b16_d16_hi v17, v18 offset:5200
	v_cvt_pk_bf16_f32 v18, 0, v60
	ds_write_b16_d16_hi v17, v18 offset:4416
	v_cvt_pk_bf16_f32 v18, 0, v61
	ds_write_b16_d16_hi v17, v18 offset:4688
	v_cvt_pk_bf16_f32 v18, 0, v62
	ds_write_b16_d16_hi v17, v18 offset:4960
	v_cvt_pk_bf16_f32 v18, 0, v63
	ds_write_b16_d16_hi v17, v18 offset:5232
	v_cvt_pk_bf16_f32 v18, 0, v52
	ds_write_b16_d16_hi v17, v18 offset:4448
	v_cvt_pk_bf16_f32 v18, 0, v53
	ds_write_b16_d16_hi v17, v18 offset:4720
	v_cvt_pk_bf16_f32 v18, 0, v54
	ds_write_b16_d16_hi v17, v18 offset:4992
	v_cvt_pk_bf16_f32 v18, 0, v55
	ds_write_b16_d16_hi v17, v18 offset:5264
	v_cvt_pk_bf16_f32 v18, 0, v44
	ds_write_b16_d16_hi v17, v18 offset:8704
	v_cvt_pk_bf16_f32 v18, 0, v45
	ds_write_b16_d16_hi v17, v18 offset:8976
	v_cvt_pk_bf16_f32 v18, 0, v46
	ds_write_b16_d16_hi v17, v18 offset:9248
	v_cvt_pk_bf16_f32 v18, 0, v47
	ds_write_b16_d16_hi v17, v18 offset:9520
	v_cvt_pk_bf16_f32 v18, 0, v40
	ds_write_b16_d16_hi v17, v18 offset:8736
	v_cvt_pk_bf16_f32 v18, 0, v41
	ds_write_b16_d16_hi v17, v18 offset:9008
	v_cvt_pk_bf16_f32 v18, 0, v42
	ds_write_b16_d16_hi v17, v18 offset:9280
	v_cvt_pk_bf16_f32 v18, 0, v43
	ds_write_b16_d16_hi v17, v18 offset:9552
	v_cvt_pk_bf16_f32 v18, 0, v36
	ds_write_b16_d16_hi v17, v18 offset:8768
	v_cvt_pk_bf16_f32 v18, 0, v37
	ds_write_b16_d16_hi v17, v18 offset:9040
	v_cvt_pk_bf16_f32 v18, 0, v38
	ds_write_b16_d16_hi v17, v18 offset:9312
	v_cvt_pk_bf16_f32 v18, 0, v39
	ds_write_b16_d16_hi v17, v18 offset:9584
	v_cvt_pk_bf16_f32 v18, 0, v28
	ds_write_b16_d16_hi v17, v18 offset:8800
	v_cvt_pk_bf16_f32 v18, 0, v29
	ds_write_b16_d16_hi v17, v18 offset:9072
	v_cvt_pk_bf16_f32 v18, 0, v30
	ds_write_b16_d16_hi v17, v18 offset:9344
	v_cvt_pk_bf16_f32 v18, 0, v31
	ds_write_b16_d16_hi v17, v18 offset:9616
	v_cvt_pk_bf16_f32 v0, 0, v0
	ds_write_b16_d16_hi v17, v0 offset:13056
	v_cvt_pk_bf16_f32 v0, 0, v1
	v_mfma_f32_16x16x32_bf16 v[4:7], v[48:51], v[104:107], v[88:91]
	ds_write_b16_d16_hi v17, v0 offset:13328
	v_cvt_pk_bf16_f32 v0, 0, v2
	ds_write_b16_d16_hi v17, v0 offset:13600
	v_cvt_pk_bf16_f32 v0, 0, v3
	ds_write_b16_d16_hi v17, v0 offset:13872
	s_nop 0
	s_nop 1
	v_cvt_pk_bf16_f32 v0, 0, v4
	ds_write_b16_d16_hi v17, v0 offset:13088
	v_cvt_pk_bf16_f32 v0, 0, v5
	v_mfma_f32_16x16x32_bf16 v[8:11], v[48:51], v[112:115], v[80:83]
	ds_write_b16_d16_hi v17, v0 offset:13360
	v_cvt_pk_bf16_f32 v0, 0, v6
	ds_write_b16_d16_hi v17, v0 offset:13632
	v_cvt_pk_bf16_f32 v0, 0, v7
	ds_write_b16_d16_hi v17, v0 offset:13904
	s_nop 0
	s_nop 1
	v_cvt_pk_bf16_f32 v0, 0, v8
	ds_write_b16_d16_hi v17, v0 offset:13120
	v_cvt_pk_bf16_f32 v0, 0, v9
	v_mfma_f32_16x16x32_bf16 v[12:15], v[48:51], v[108:111], v[56:59]
	ds_write_b16_d16_hi v17, v0 offset:13392
	v_cvt_pk_bf16_f32 v0, 0, v10
	ds_write_b16_d16_hi v17, v0 offset:13664
	v_cvt_pk_bf16_f32 v0, 0, v11
	ds_write_b16_d16_hi v17, v0 offset:13936
	s_nop 0
	s_nop 1
	v_cvt_pk_bf16_f32 v0, 0, v12
	ds_write_b16_d16_hi v17, v0 offset:13152
	v_cvt_pk_bf16_f32 v0, 0, v13
	ds_write_b16_d16_hi v17, v0 offset:13424
	v_cvt_pk_bf16_f32 v0, 0, v14
	ds_write_b16_d16_hi v17, v0 offset:13696
	s_lshl_b64 s[14:15], s[14:15], 1
	v_cvt_pk_bf16_f32 v0, 0, v15
	s_add_u32 s14, s26, s14
	ds_write_b16_d16_hi v17, v0 offset:13968
	v_ashrrev_i32_e32 v0, 31, v16
	s_addc_u32 s15, s27, s15
	s_lshl_b32 s12, s12, 7
	v_lshrrev_b32_e32 v0, 28, v0
	s_ashr_i32 s13, s12, 31
	v_add_u32_e32 v0, v16, v0
	s_lshl_b64 s[12:13], s[12:13], 1
	v_ashrrev_i32_e32 v4, 4, v0
	v_and_b32_e32 v0, -16, v0
	s_add_u32 s12, s14, s12
	v_sub_u32_e32 v0, v16, v0
	v_ashrrev_i32_e32 v5, 31, v4
	s_addc_u32 s13, s15, s13
	v_mul_lo_u32 v1, v4, s42
	v_lshlrev_b32_e32 v6, 3, v0
	v_lshlrev_b64 v[4:5], 11, v[4:5]
	v_ashrrev_i32_e32 v7, 31, v6
	v_lshl_add_u64 v[4:5], s[12:13], 0, v[4:5]
	v_lshl_add_u64 v[8:9], v[6:7], 1, v[4:5]
	v_add_u32_e32 v4, 0x100, v16
	v_ashrrev_i32_e32 v5, 31, v4
	v_cvt_pk_bf16_f32 v19, 0, v100
	v_lshl_add_u32 v0, v0, 4, v1
	v_lshrrev_b32_e32 v5, 28, v5
	ds_write_b16_d16_hi v17, v19
	s_waitcnt lgkmcnt(0)
	s_barrier
; template <int WM, int WN>
; __device__ __forceinline__ void store_tile_bf16(const f32x4 (&acc)[WM][WN], u16* dst, int ld, char* smem) {
;     ...
;   constexpr int CPR = BN / 8;
; #pragma unroll
;   for (int i = 0; i < BM * CPR / 256; ++i) {
;     int q = tid + 256 * i, row = q / CPR, c = q % CPR;
;     uint4 v = *reinterpret_cast<const uint4*>(T + row * STR + c * 8);
;     *reinterpret_cast<uint4*>(dst + (size_t)row * ld + c * 8) = v;
;   }
; __device__ void phase_out(const Params& p, int layer, char* smem) {
;     ...
;   for (int t = li_; t < rbp_ * 8; t += nl_) {
;     const int rg_ = t / (8 * 8), v_ = t % (8 * 8);
;     const int rb = xg_ * rbp_ + rg_ * 8 + (v_ & 7), cb = v_ >> 3;
	ds_read_b128 v[0:3], v0
	v_add_u32_e32 v5, v4, v5
	v_ashrrev_i32_e32 v10, 4, v5
	v_and_b32_e32 v5, -16, v5
	v_sub_u32_e32 v11, v4, v5
	v_mul_lo_u32 v4, v10, s42
	v_lshl_add_u32 v4, v11, 4, v4
	ds_read_b128 v[4:7], v4
	s_waitcnt lgkmcnt(1)
	global_store_dwordx4 v[8:9], v[0:3], off
	s_add_i32 s43, s43, s61
	s_cmp_lt_i32 s43, s62
	v_lshlrev_b32_e32 v0, 3, v11
	v_ashrrev_i32_e32 v11, 31, v10
	v_lshlrev_b64 v[2:3], 11, v[10:11]
	v_ashrrev_i32_e32 v1, 31, v0
	v_lshl_add_u64 v[2:3], s[12:13], 0, v[2:3]
	v_lshl_add_u64 v[0:1], v[0:1], 1, v[2:3]
	s_waitcnt lgkmcnt(0)
	global_store_dwordx4 v[0:1], v[4:7], off
	v_add_u32_e32 v0, 0x200, v16
	v_ashrrev_i32_e32 v1, 31, v0
	v_lshrrev_b32_e32 v1, 28, v1
	v_add_u32_e32 v1, v0, v1
	v_ashrrev_i32_e32 v4, 4, v1
	v_and_b32_e32 v1, -16, v1
	v_sub_u32_e32 v0, v0, v1
	v_ashrrev_i32_e32 v5, 31, v4
	v_mul_lo_u32 v1, v4, s42
	v_lshlrev_b32_e32 v6, 3, v0
	v_lshlrev_b64 v[4:5], 11, v[4:5]
	v_ashrrev_i32_e32 v7, 31, v6
	v_lshl_add_u64 v[4:5], s[12:13], 0, v[4:5]
	v_lshl_add_u64 v[8:9], v[6:7], 1, v[4:5]
	v_add_u32_e32 v4, 0x300, v16
	v_ashrrev_i32_e32 v5, 31, v4
	v_lshl_add_u32 v0, v0, 4, v1
	v_lshrrev_b32_e32 v5, 28, v5
	ds_read_b128 v[0:3], v0
	v_add_u32_e32 v5, v4, v5
	v_ashrrev_i32_e32 v10, 4, v5
	v_and_b32_e32 v5, -16, v5
	v_sub_u32_e32 v11, v4, v5
	v_mul_lo_u32 v4, v10, s42
	v_lshl_add_u32 v4, v11, 4, v4
	ds_read_b128 v[4:7], v4
	s_waitcnt lgkmcnt(1)
	global_store_dwordx4 v[8:9], v[0:3], off
	s_nop 1
	v_lshlrev_b32_e32 v0, 3, v11
	v_ashrrev_i32_e32 v11, 31, v10
	v_lshlrev_b64 v[2:3], 11, v[10:11]
	v_ashrrev_i32_e32 v1, 31, v0
	v_lshl_add_u64 v[2:3], s[12:13], 0, v[2:3]
	v_lshl_add_u64 v[0:1], v[0:1], 1, v[2:3]
	s_waitcnt lgkmcnt(0)
	global_store_dwordx4 v[0:1], v[4:7], off
	v_add_u32_e32 v0, 0x400, v16
	v_ashrrev_i32_e32 v1, 31, v0
	v_lshrrev_b32_e32 v1, 28, v1
	v_add_u32_e32 v1, v0, v1
	v_ashrrev_i32_e32 v4, 4, v1
	v_and_b32_e32 v1, -16, v1
	v_sub_u32_e32 v0, v0, v1
	v_ashrrev_i32_e32 v5, 31, v4
	v_mul_lo_u32 v1, v4, s42
	v_lshlrev_b32_e32 v6, 3, v0
	v_lshlrev_b64 v[4:5], 11, v[4:5]
	v_ashrrev_i32_e32 v7, 31, v6
	v_lshl_add_u64 v[4:5], s[12:13], 0, v[4:5]
	v_lshl_add_u64 v[8:9], v[6:7], 1, v[4:5]
	v_add_u32_e32 v4, 0x500, v16
	v_ashrrev_i32_e32 v5, 31, v4
	v_lshl_add_u32 v0, v0, 4, v1
	v_lshrrev_b32_e32 v5, 28, v5
	ds_read_b128 v[0:3], v0
	v_add_u32_e32 v5, v4, v5
	v_ashrrev_i32_e32 v10, 4, v5
	v_and_b32_e32 v5, -16, v5
	v_sub_u32_e32 v11, v4, v5
	v_mul_lo_u32 v4, v10, s42
	v_lshl_add_u32 v4, v11, 4, v4
	ds_read_b128 v[4:7], v4
	s_waitcnt lgkmcnt(1)
	global_store_dwordx4 v[8:9], v[0:3], off
	s_nop 1
	v_lshlrev_b32_e32 v0, 3, v11
	v_ashrrev_i32_e32 v11, 31, v10
	v_lshlrev_b64 v[2:3], 11, v[10:11]
	v_ashrrev_i32_e32 v1, 31, v0
	v_lshl_add_u64 v[2:3], s[12:13], 0, v[2:3]
	v_lshl_add_u64 v[0:1], v[0:1], 1, v[2:3]
	s_waitcnt lgkmcnt(0)
	global_store_dwordx4 v[0:1], v[4:7], off
	v_add_u32_e32 v0, 0x600, v16
	v_ashrrev_i32_e32 v1, 31, v0
	v_lshrrev_b32_e32 v1, 28, v1
	v_add_u32_e32 v1, v0, v1
	v_ashrrev_i32_e32 v4, 4, v1
	v_and_b32_e32 v1, -16, v1
	v_sub_u32_e32 v0, v0, v1
	v_ashrrev_i32_e32 v5, 31, v4
	v_mul_lo_u32 v1, v4, s42
	v_lshlrev_b32_e32 v6, 3, v0
	v_lshlrev_b64 v[4:5], 11, v[4:5]
	v_ashrrev_i32_e32 v7, 31, v6
	v_lshl_add_u64 v[4:5], s[12:13], 0, v[4:5]
	v_lshl_add_u64 v[8:9], v[6:7], 1, v[4:5]
	v_add_u32_e32 v4, 0x700, v16
	v_ashrrev_i32_e32 v5, 31, v4
	v_lshl_add_u32 v0, v0, 4, v1
	v_lshrrev_b32_e32 v5, 28, v5
	ds_read_b128 v[0:3], v0
	v_add_u32_e32 v5, v4, v5
	v_ashrrev_i32_e32 v10, 4, v5
	v_and_b32_e32 v5, -16, v5
	v_sub_u32_e32 v11, v4, v5
	v_mul_lo_u32 v4, v10, s42
	v_lshl_add_u32 v4, v11, 4, v4
	ds_read_b128 v[4:7], v4
	s_waitcnt lgkmcnt(1)
	global_store_dwordx4 v[8:9], v[0:3], off
	s_nop 1
	v_lshlrev_b32_e32 v0, 3, v11
	v_ashrrev_i32_e32 v11, 31, v10
	v_lshlrev_b64 v[2:3], 11, v[10:11]
	v_ashrrev_i32_e32 v1, 31, v0
	v_lshl_add_u64 v[2:3], s[12:13], 0, v[2:3]
	v_lshl_add_u64 v[0:1], v[0:1], 1, v[2:3]
	s_waitcnt lgkmcnt(0)
	global_store_dwordx4 v[0:1], v[4:7], off
	s_cbranch_scc1 .LBB0_638

; template <int WM, int WN> ...
;     ...
; #pragma unroll
;   for (int n = 0; n < 4; ++n) fb0[n] = LDSF(cur + boff + n * 1024);
; #pragma unroll
;   for (int m = 0; m < 4; ++m) fa0[m] = LDSF(cur + aoff + m * 1024);
;   acc[3][0] = MFMA16(pa, pb0, acc[3][0]);
;   acc[3][1] = MFMA16(pa, pb1, acc[3][1]);
;   acc[3][2] = MFMA16(pa, pb2, acc[3][2]);
;   acc[3][3] = MFMA16(pa, pb3, acc[3][3]);
; #pragma unroll
;   for (int n = 0; n < 4; ++n) acc[0][n] = MFMA16(fa0[0], fb0[n], acc[0][n]);
; #pragma unroll
;   for (int m = 0; m < 4; ++m) fa1[m] = LDSF(cur + aoff + APAN + m * 1024);
; #pragma unroll
;   for (int n = 0; n < 4; ++n) acc[1][n] = MFMA16(fa0[1], fb0[n], acc[1][n]);
; #pragma unroll
;   for (int n = 0; n < 4; ++n) fb1[n] = LDSF(cur + boff + BPAN + n * 1024);
; #pragma unroll
;   for (int n = 0; n < 4; ++n) acc[2][n] = MFMA16(fa0[2], fb0[n], acc[2][n]);
;   *reinterpret_cast<uint4*>(nxt + wao) = a0;
;   *reinterpret_cast<uint4*>(nxt + wao + 32 * 64) = a1;
; #pragma unroll
;   for (int n = 0; n < 4; ++n) acc[3][n] = MFMA16(fa0[3], fb0[n], acc[3][n]);
;   *reinterpret_cast<uint4*>(nxt + wao + 64 * 64) = a2;
;   *reinterpret_cast<uint4*>(nxt + wao + 96 * 64) = a3;
; #pragma unroll
;   for (int n = 0; n < 4; ++n) acc[0][n] = MFMA16(fa1[0], fb1[n], acc[0][n]);
;   *reinterpret_cast<uint4*>(nxt + wbo) = b0;
;   *reinterpret_cast<uint4*>(nxt + wbo + 32 * 64) = b1;
; #pragma unroll
;   for (int n = 0; n < 4; ++n) acc[1][n] = MFMA16(fa1[1], fb1[n], acc[1][n]);
;   *reinterpret_cast<uint4*>(nxt + wbo + 64 * 64) = b2;
;   *reinterpret_cast<uint4*>(nxt + wbo + 96 * 64) = b3;
; #pragma unroll
;   for (int n = 0; n < 4; ++n) acc[2][n] = MFMA16(fa1[2], fb1[n], acc[2][n]);
;   pa = fa1[3];
;   pb0 = fb1[0]; pb1 = fb1[1]; pb2 = fb1[2]; pb3 = fb1[3];
;   SGB_(0x100, 5);
;   SGB_(0x008, 4);
; #pragma unroll
;   for (int i_ = 0; i_ < 11; ++i_) { SGB_(0x008, 1); SGB_(0x100, 1); }
; #pragma unroll
;   for (int i_ = 0; i_ < 8; ++i_) { SGB_(0x008, 2); SGB_(0x200, 1); SGB_(0x020, 1); }
;   SGB_(0x008, 1);
; }
; template <int WM, int WN, typename SrcF, typename PostF>
; __device__ __forceinline__ void gemm_stream(const int nsteps, SrcF src, PostF post, f32x4 (&acc)[WM][WN], char* smem) {
;     ...
;   for (int kt = 0; kt < nsteps; kt += 2) {
;     {
;       TileSrc s = src(min(kt + 2, nsteps - 1));
;       GLOAD_TILE(xa, s.a, s.lda, ACH);
;       GLOAD_TILE(xb, s.b, s.ldb, BCH);
;     }
.LBB0_746:
	s_add_i32 s21, s16, 2
	s_add_i32 s16, s16, 4
	s_min_u32 s16, s16, 15
	s_lshl_b32 s16, s16, 7
	s_add_u32 s92, s24, s16
	s_addc_u32 s93, s25, 0
	s_add_u32 s94, s26, s16
	s_addc_u32 s95, s27, 0
	ds_read_b128 v[148:151], v119
	ds_read_b128 v[132:135], v130 offset:16512
	ds_read_b128 v[136:139], v130 offset:17536
	ds_read_b128 v[140:143], v130 offset:18560
	ds_read_b128 v[144:147], v130 offset:19584
	v_mfma_f32_16x16x32_bf16 v[84:87], v[80:83], v[84:87], v[100:103]
	v_mfma_f32_16x16x32_bf16 v[96:99], v[80:83], v[104:107], v[96:99]
	s_waitcnt vmcnt(4)
	ds_write_b128 v131, v[76:79] offset:33024
	global_load_dwordx4 v[76:79], v116, s[92:93]
	s_add_u32 s64, s24, s16
	s_addc_u32 s65, s25, 0
	v_mfma_f32_16x16x32_bf16 v[92:95], v[80:83], v[108:111], v[92:95]
	v_mfma_f32_16x16x32_bf16 v[80:83], v[80:83], v[112:115], v[88:91]
	s_waitcnt lgkmcnt(4)
	v_mfma_f32_16x16x32_bf16 v[44:47], v[148:151], v[132:135], v[44:47]
	s_nop 0
	ds_read_b128 v[88:91], v119 offset:1024
	s_waitcnt lgkmcnt(4)
	v_mfma_f32_16x16x32_bf16 v[40:43], v[148:151], v[136:139], v[40:43]
	ds_write_b128 v131, v[68:71] offset:35072
	global_load_dwordx4 v[68:71], v120, s[92:93]
	ds_read_b128 v[100:103], v119 offset:2048
	s_waitcnt lgkmcnt(5)
	v_mfma_f32_16x16x32_bf16 v[36:39], v[148:151], v[140:143], v[36:39]
	ds_read_b128 v[104:107], v119 offset:3072
	s_waitcnt lgkmcnt(5)
	v_mfma_f32_16x16x32_bf16 v[32:35], v[148:151], v[144:147], v[32:35]
	ds_read_b128 v[108:111], v119 offset:8256
	s_waitcnt lgkmcnt(4)
	v_mfma_f32_16x16x32_bf16 v[28:31], v[88:91], v[132:135], v[28:31]
	ds_read_b128 v[112:115], v119 offset:9280
	v_mfma_f32_16x16x32_bf16 v[24:27], v[88:91], v[136:139], v[24:27]
	ds_read_b128 v[148:151], v119 offset:10304
	v_mfma_f32_16x16x32_bf16 v[20:23], v[88:91], v[140:143], v[20:23]
	ds_write_b128 v131, v[64:67] offset:37120
	global_load_dwordx4 v[64:67], v122, s[92:93]
	ds_read_b128 v[152:155], v119 offset:11328
	v_mfma_f32_16x16x32_bf16 v[16:19], v[88:91], v[144:147], v[16:19]
	ds_read_b128 v[88:91], v130 offset:24768
	s_waitcnt lgkmcnt(7)
	v_mfma_f32_16x16x32_bf16 v[12:15], v[100:103], v[132:135], v[12:15]
	ds_read_b128 v[156:159], v130 offset:25792
	v_mfma_f32_16x16x32_bf16 v[8:11], v[100:103], v[136:139], v[8:11]
	ds_read_b128 v[160:163], v130 offset:26816
	v_mfma_f32_16x16x32_bf16 v[4:7], v[100:103], v[140:143], v[4:7]
	ds_write_b128 v131, v[72:75] offset:39168
	global_load_dwordx4 v[72:75], v124, s[92:93]
	ds_read_b128 v[164:167], v130 offset:27840
	v_mfma_f32_16x16x32_bf16 v[0:3], v[100:103], v[144:147], v[0:3]
	s_waitcnt lgkmcnt(10)
	v_mfma_f32_16x16x32_bf16 v[84:87], v[104:107], v[132:135], v[84:87]
	v_mfma_f32_16x16x32_bf16 v[96:99], v[104:107], v[136:139], v[96:99]
	v_mfma_f32_16x16x32_bf16 v[92:95], v[104:107], v[140:143], v[92:95]
	v_mfma_f32_16x16x32_bf16 v[80:83], v[104:107], v[144:147], v[80:83]
	s_waitcnt vmcnt(4)
	ds_write_b128 v131, v[60:63] offset:49536
	global_load_dwordx4 v[60:63], v116, s[94:95]
	s_waitcnt lgkmcnt(5)
	v_mfma_f32_16x16x32_bf16 v[44:47], v[108:111], v[88:91], v[44:47]
	s_add_u32 s64, s26, s16
	s_addc_u32 s65, s27, 0
	s_waitcnt lgkmcnt(4)
	v_mfma_f32_16x16x32_bf16 v[40:43], v[108:111], v[156:159], v[40:43]
	s_min_u32 s16, s21, 12
	s_lshl_b32 s16, s16, 7
	s_waitcnt lgkmcnt(3)
	v_mfma_f32_16x16x32_bf16 v[36:39], v[108:111], v[160:163], v[36:39]
	s_waitcnt lgkmcnt(1)
	v_mfma_f32_16x16x32_bf16 v[32:35], v[108:111], v[164:167], v[32:35]
	ds_write_b128 v131, v[56:59] offset:51584
	global_load_dwordx4 v[56:59], v120, s[94:95]
	v_mfma_f32_16x16x32_bf16 v[28:31], v[112:115], v[88:91], v[28:31]
	v_mfma_f32_16x16x32_bf16 v[24:27], v[112:115], v[156:159], v[24:27]
	v_mfma_f32_16x16x32_bf16 v[20:23], v[112:115], v[160:163], v[20:23]
	v_mfma_f32_16x16x32_bf16 v[16:19], v[112:115], v[164:167], v[16:19]
	v_mfma_f32_16x16x32_bf16 v[12:15], v[148:151], v[88:91], v[12:15]
	ds_write_b128 v131, v[52:55] offset:53632
	global_load_dwordx4 v[52:55], v122, s[94:95]
	v_mfma_f32_16x16x32_bf16 v[8:11], v[148:151], v[156:159], v[8:11]
	s_add_u32 s64, s24, s16
	s_addc_u32 s65, s25, 0
	s_add_u32 s66, s26, s16
	v_mfma_f32_16x16x32_bf16 v[4:7], v[148:151], v[160:163], v[4:7]
	s_addc_u32 s67, s27, 0
	v_mfma_f32_16x16x32_bf16 v[0:3], v[148:151], v[164:167], v[0:3]
	v_mfma_f32_16x16x32_bf16 v[88:91], v[152:155], v[88:91], v[84:87]
	ds_write_b128 v131, v[48:51] offset:55680
	global_load_dwordx4 v[48:51], v124, s[94:95]
	v_mfma_f32_16x16x32_bf16 v[96:99], v[152:155], v[156:159], v[96:99]
	v_mfma_f32_16x16x32_bf16 v[92:95], v[152:155], v[160:163], v[92:95]
	v_mfma_f32_16x16x32_bf16 v[132:135], v[152:155], v[164:167], v[80:83]
	s_waitcnt lgkmcnt(0)
	s_barrier
; template <int WM, int WN> ...
;     ...
; #pragma unroll
;   for (int n = 0; n < 4; ++n) fb0[n] = LDSF(cur + boff + n * 1024);
; #pragma unroll
;   for (int m = 0; m < 4; ++m) fa0[m] = LDSF(cur + aoff + m * 1024);
;   acc[3][0] = MFMA16(pa, pb0, acc[3][0]);
;   acc[3][1] = MFMA16(pa, pb1, acc[3][1]);
;   acc[3][2] = MFMA16(pa, pb2, acc[3][2]);
;   acc[3][3] = MFMA16(pa, pb3, acc[3][3]);
; #pragma unroll
;   for (int n = 0; n < 4; ++n) acc[0][n] = MFMA16(fa0[0], fb0[n], acc[0][n]);
; #pragma unroll
;   for (int m = 0; m < 4; ++m) fa1[m] = LDSF(cur + aoff + APAN + m * 1024);
; #pragma unroll
;   for (int n = 0; n < 4; ++n) acc[1][n] = MFMA16(fa0[1], fb0[n], acc[1][n]);
; #pragma unroll
;   for (int n = 0; n < 4; ++n) fb1[n] = LDSF(cur + boff + BPAN + n * 1024);
; #pragma unroll
;   for (int n = 0; n < 4; ++n) acc[2][n] = MFMA16(fa0[2], fb0[n], acc[2][n]);
;   *reinterpret_cast<uint4*>(nxt + wao) = a0;
;   *reinterpret_cast<uint4*>(nxt + wao + 32 * 64) = a1;
; #pragma unroll
;   for (int n = 0; n < 4; ++n) acc[3][n] = MFMA16(fa0[3], fb0[n], acc[3][n]);
;   *reinterpret_cast<uint4*>(nxt + wao + 64 * 64) = a2;
;   *reinterpret_cast<uint4*>(nxt + wao + 96 * 64) = a3;
; #pragma unroll
;   for (int n = 0; n < 4; ++n) acc[0][n] = MFMA16(fa1[0], fb1[n], acc[0][n]);
;   *reinterpret_cast<uint4*>(nxt + wbo) = b0;
;   *reinterpret_cast<uint4*>(nxt + wbo + 32 * 64) = b1;
; #pragma unroll
;   for (int n = 0; n < 4; ++n) acc[1][n] = MFMA16(fa1[1], fb1[n], acc[1][n]);
;   *reinterpret_cast<uint4*>(nxt + wbo + 64 * 64) = b2;
;   *reinterpret_cast<uint4*>(nxt + wbo + 96 * 64) = b3;
; #pragma unroll
;   for (int n = 0; n < 4; ++n) acc[2][n] = MFMA16(fa1[2], fb1[n], acc[2][n]);
;   pa = fa1[3];
;   pb0 = fb1[0]; pb1 = fb1[1]; pb2 = fb1[2]; pb3 = fb1[3];
;   SGB_(0x100, 5);
;   SGB_(0x008, 4);
; #pragma unroll
;   for (int i_ = 0; i_ < 11; ++i_) { SGB_(0x008, 1); SGB_(0x100, 1); }
; #pragma unroll
;   for (int i_ = 0; i_ < 8; ++i_) { SGB_(0x008, 2); SGB_(0x200, 1); SGB_(0x020, 1); }
;   SGB_(0x008, 1);
; }
; template <int WM, int WN, typename SrcF, typename PostF>
; __device__ __forceinline__ void gemm_stream(const int nsteps, SrcF src, PostF post, f32x4 (&acc)[WM][WN], char* smem) {
;     ...
;       TileSrc s = src(min(kt + 3, nsteps - 1));
;       GLOAD_TILE(ya, s.a, s.lda, ACH);
;       GLOAD_TILE(yb, s.b, s.ldb, BCH);
;     }
	s_nop 0
	ds_read_b128 v[80:83], v119 offset:33024
	ds_read_b128 v[100:103], v130 offset:49536
	ds_read_b128 v[112:115], v130 offset:50560
	ds_read_b128 v[136:139], v130 offset:51584
	ds_read_b128 v[140:143], v130 offset:52608
	s_waitcnt lgkmcnt(3)
	v_mfma_f32_16x16x32_bf16 v[44:47], v[80:83], v[100:103], v[44:47]
	s_waitcnt lgkmcnt(2)
	v_mfma_f32_16x16x32_bf16 v[40:43], v[80:83], v[112:115], v[40:43]
	s_waitcnt vmcnt(4)
	ds_write_b128 v131, v[76:79]
	global_load_dwordx4 v[76:79], v116, s[64:65] offset:384
	s_waitcnt lgkmcnt(2)
	v_mfma_f32_16x16x32_bf16 v[36:39], v[80:83], v[136:139], v[36:39]
	s_waitcnt lgkmcnt(0)
	v_mfma_f32_16x16x32_bf16 v[32:35], v[80:83], v[140:143], v[32:35]
	ds_read_b128 v[80:83], v119 offset:34048
	s_waitcnt lgkmcnt(0)
	v_mfma_f32_16x16x32_bf16 v[28:31], v[80:83], v[100:103], v[28:31]
	ds_write_b128 v131, v[68:71] offset:2048
	global_load_dwordx4 v[68:71], v120, s[64:65] offset:384
	ds_read_b128 v[104:107], v119 offset:35072
	v_mfma_f32_16x16x32_bf16 v[24:27], v[80:83], v[112:115], v[24:27]
	ds_read_b128 v[144:147], v119 offset:36096
	v_mfma_f32_16x16x32_bf16 v[20:23], v[80:83], v[136:139], v[20:23]
	ds_read_b128 v[148:151], v119 offset:41280
	v_mfma_f32_16x16x32_bf16 v[16:19], v[80:83], v[140:143], v[16:19]
	ds_read_b128 v[152:155], v119 offset:42304
	s_waitcnt lgkmcnt(3)
	v_mfma_f32_16x16x32_bf16 v[12:15], v[104:107], v[100:103], v[12:15]
	ds_write_b128 v131, v[64:67] offset:4096
	global_load_dwordx4 v[64:67], v122, s[64:65] offset:384
	ds_read_b128 v[156:159], v119 offset:43328
	v_mfma_f32_16x16x32_bf16 v[8:11], v[104:107], v[112:115], v[8:11]
	ds_read_b128 v[80:83], v119 offset:44352
	v_mfma_f32_16x16x32_bf16 v[4:7], v[104:107], v[136:139], v[4:7]
	ds_read_b128 v[84:87], v130 offset:57792
	v_mfma_f32_16x16x32_bf16 v[0:3], v[104:107], v[140:143], v[0:3]
	ds_write_b128 v131, v[72:75] offset:6144
	global_load_dwordx4 v[72:75], v124, s[64:65] offset:384
	ds_read_b128 v[104:107], v130 offset:58816
	s_waitcnt lgkmcnt(8)
	v_mfma_f32_16x16x32_bf16 v[100:103], v[144:147], v[100:103], v[88:91]
	ds_read_b128 v[108:111], v130 offset:59840
	v_mfma_f32_16x16x32_bf16 v[96:99], v[144:147], v[112:115], v[96:99]
	ds_read_b128 v[112:115], v130 offset:60864
	v_mfma_f32_16x16x32_bf16 v[92:95], v[144:147], v[136:139], v[92:95]
	v_mfma_f32_16x16x32_bf16 v[88:91], v[144:147], v[140:143], v[132:135]
	s_waitcnt vmcnt(4)
	ds_write_b128 v131, v[60:63] offset:16512
	global_load_dwordx4 v[60:63], v116, s[66:67] offset:384
	s_waitcnt lgkmcnt(5)
	v_mfma_f32_16x16x32_bf16 v[44:47], v[148:151], v[84:87], v[44:47]
	s_waitcnt lgkmcnt(3)
	v_mfma_f32_16x16x32_bf16 v[40:43], v[148:151], v[104:107], v[40:43]
	s_waitcnt lgkmcnt(2)
	v_mfma_f32_16x16x32_bf16 v[36:39], v[148:151], v[108:111], v[36:39]
	ds_write_b128 v131, v[56:59] offset:18560
	global_load_dwordx4 v[56:59], v120, s[66:67] offset:384
	s_waitcnt lgkmcnt(2)
	v_mfma_f32_16x16x32_bf16 v[32:35], v[148:151], v[112:115], v[32:35]
	v_mfma_f32_16x16x32_bf16 v[28:31], v[152:155], v[84:87], v[28:31]
	v_mfma_f32_16x16x32_bf16 v[24:27], v[152:155], v[104:107], v[24:27]
	v_mfma_f32_16x16x32_bf16 v[20:23], v[152:155], v[108:111], v[20:23]
	ds_write_b128 v131, v[52:55] offset:20608
	global_load_dwordx4 v[52:55], v122, s[66:67] offset:384
	v_mfma_f32_16x16x32_bf16 v[16:19], v[152:155], v[112:115], v[16:19]
	v_mfma_f32_16x16x32_bf16 v[12:15], v[156:159], v[84:87], v[12:15]
	v_mfma_f32_16x16x32_bf16 v[8:11], v[156:159], v[104:107], v[8:11]
	ds_write_b128 v131, v[48:51] offset:22656
	global_load_dwordx4 v[48:51], v124, s[66:67] offset:384
	v_mfma_f32_16x16x32_bf16 v[4:7], v[156:159], v[108:111], v[4:7]
	v_mfma_f32_16x16x32_bf16 v[0:3], v[156:159], v[112:115], v[0:3]
	s_cmp_lt_u32 s21, 12
	s_mov_b32 s16, s21
	s_waitcnt lgkmcnt(0)
	s_barrier
	s_cbranch_scc1 .LBB0_746
	ds_read_b128 v[148:151], v119
	ds_read_b128 v[132:135], v130 offset:16512
	ds_read_b128 v[136:139], v130 offset:17536
	ds_read_b128 v[140:143], v130 offset:18560
	ds_read_b128 v[144:147], v130 offset:19584
	v_mfma_f32_16x16x32_bf16 v[84:87], v[80:83], v[84:87], v[100:103]
	s_add_i32 s21, s16, 2
	s_add_i32 s16, s16, 4
	s_min_u32 s16, s16, 15
	v_mfma_f32_16x16x32_bf16 v[96:99], v[80:83], v[104:107], v[96:99]
	s_lshl_b32 s16, s16, 7
	s_add_u32 s64, s24, s16
	s_addc_u32 s65, s25, 0
	v_mfma_f32_16x16x32_bf16 v[92:95], v[80:83], v[108:111], v[92:95]
	v_mfma_f32_16x16x32_bf16 v[80:83], v[80:83], v[112:115], v[88:91]
	s_waitcnt lgkmcnt(3)
	v_mfma_f32_16x16x32_bf16 v[44:47], v[148:151], v[132:135], v[44:47]
	s_nop 0
	ds_read_b128 v[88:91], v119 offset:1024
	s_waitcnt lgkmcnt(3)
	v_mfma_f32_16x16x32_bf16 v[40:43], v[148:151], v[136:139], v[40:43]
	ds_read_b128 v[100:103], v119 offset:2048
	s_waitcnt lgkmcnt(3)
	v_mfma_f32_16x16x32_bf16 v[36:39], v[148:151], v[140:143], v[36:39]
	ds_read_b128 v[104:107], v119 offset:3072
	s_waitcnt lgkmcnt(3)
	v_mfma_f32_16x16x32_bf16 v[32:35], v[148:151], v[144:147], v[32:35]
	ds_read_b128 v[108:111], v119 offset:8256
	s_waitcnt lgkmcnt(3)
	v_mfma_f32_16x16x32_bf16 v[28:31], v[88:91], v[132:135], v[28:31]
	ds_read_b128 v[112:115], v119 offset:9280
	v_mfma_f32_16x16x32_bf16 v[24:27], v[88:91], v[136:139], v[24:27]
	ds_read_b128 v[148:151], v119 offset:10304
	v_mfma_f32_16x16x32_bf16 v[20:23], v[88:91], v[140:143], v[20:23]
	ds_read_b128 v[152:155], v119 offset:11328
	v_mfma_f32_16x16x32_bf16 v[16:19], v[88:91], v[144:147], v[16:19]
	ds_read_b128 v[88:91], v130 offset:24768
	s_waitcnt lgkmcnt(6)
	v_mfma_f32_16x16x32_bf16 v[12:15], v[100:103], v[132:135], v[12:15]
	ds_read_b128 v[156:159], v130 offset:25792
	v_mfma_f32_16x16x32_bf16 v[8:11], v[100:103], v[136:139], v[8:11]
	ds_read_b128 v[160:163], v130 offset:26816
	v_mfma_f32_16x16x32_bf16 v[4:7], v[100:103], v[140:143], v[4:7]
	ds_read_b128 v[164:167], v130 offset:27840
	v_mfma_f32_16x16x32_bf16 v[0:3], v[100:103], v[144:147], v[0:3]
	s_waitcnt lgkmcnt(8)
; template <int WM, int WN> ...
;     ...
; #pragma unroll
;   for (int n = 0; n < 4; ++n) fb0[n] = LDSF(cur + boff + n * 1024);
; #pragma unroll
;   for (int m = 0; m < 4; ++m) fa0[m] = LDSF(cur + aoff + m * 1024);
;   acc[3][0] = MFMA16(pa, pb0, acc[3][0]);
;   acc[3][1] = MFMA16(pa, pb1, acc[3][1]);
;   acc[3][2] = MFMA16(pa, pb2, acc[3][2]);
;   acc[3][3] = MFMA16(pa, pb3, acc[3][3]);
; #pragma unroll
;   for (int n = 0; n < 4; ++n) acc[0][n] = MFMA16(fa0[0], fb0[n], acc[0][n]);
; #pragma unroll
;   for (int m = 0; m < 4; ++m) fa1[m] = LDSF(cur + aoff + APAN + m * 1024);
; #pragma unroll
;   for (int n = 0; n < 4; ++n) acc[1][n] = MFMA16(fa0[1], fb0[n], acc[1][n]);
; #pragma unroll
;   for (int n = 0; n < 4; ++n) fb1[n] = LDSF(cur + boff + BPAN + n * 1024);
; #pragma unroll
;   for (int n = 0; n < 4; ++n) acc[2][n] = MFMA16(fa0[2], fb0[n], acc[2][n]);
;   *reinterpret_cast<uint4*>(nxt + wao) = a0;
;   *reinterpret_cast<uint4*>(nxt + wao + 32 * 64) = a1;
; #pragma unroll
;   for (int n = 0; n < 4; ++n) acc[3][n] = MFMA16(fa0[3], fb0[n], acc[3][n]);
;   *reinterpret_cast<uint4*>(nxt + wao + 64 * 64) = a2;
;   *reinterpret_cast<uint4*>(nxt + wao + 96 * 64) = a3;
; #pragma unroll
;   for (int n = 0; n < 4; ++n) acc[0][n] = MFMA16(fa1[0], fb1[n], acc[0][n]);
;   *reinterpret_cast<uint4*>(nxt + wbo) = b0;
;   *reinterpret_cast<uint4*>(nxt + wbo + 32 * 64) = b1;
; #pragma unroll
;   for (int n = 0; n < 4; ++n) acc[1][n] = MFMA16(fa1[1], fb1[n], acc[1][n]);
;   *reinterpret_cast<uint4*>(nxt + wbo + 64 * 64) = b2;
;   *reinterpret_cast<uint4*>(nxt + wbo + 96 * 64) = b3;
; #pragma unroll
;   for (int n = 0; n < 4; ++n) acc[2][n] = MFMA16(fa1[2], fb1[n], acc[2][n]);
;   pa = fa1[3];
;   pb0 = fb1[0]; pb1 = fb1[1]; pb2 = fb1[2]; pb3 = fb1[3];
;   SGB_(0x100, 5);
;   SGB_(0x008, 4);
; #pragma unroll
;   for (int i_ = 0; i_ < 11; ++i_) { SGB_(0x008, 1); SGB_(0x100, 1); }
; #pragma unroll
;   for (int i_ = 0; i_ < 8; ++i_) { SGB_(0x008, 2); SGB_(0x200, 1); SGB_(0x020, 1); }
;   SGB_(0x008, 1);
; }
; template <int WM, int WN, typename SrcF, typename PostF>
; __device__ __forceinline__ void gemm_stream(const int nsteps, SrcF src, PostF post, f32x4 (&acc)[WM][WN], char* smem) {
;     ...
;   acc[3][0] = MFMA16(pa, pb0, acc[3][0]);
;   acc[3][1] = MFMA16(pa, pb1, acc[3][1]);
;   acc[3][2] = MFMA16(pa, pb2, acc[3][2]);
;   acc[3][3] = MFMA16(pa, pb3, acc[3][3]);
	v_mfma_f32_16x16x32_bf16 v[84:87], v[104:107], v[132:135], v[84:87]
	s_waitcnt vmcnt(7)
	ds_write_b128 v131, v[76:79] offset:33024
	v_mfma_f32_16x16x32_bf16 v[96:99], v[104:107], v[136:139], v[96:99]
	v_mfma_f32_16x16x32_bf16 v[92:95], v[104:107], v[140:143], v[92:95]
	s_waitcnt vmcnt(6)
	ds_write_b128 v131, v[68:71] offset:35072
	v_mfma_f32_16x16x32_bf16 v[80:83], v[104:107], v[144:147], v[80:83]
	s_waitcnt lgkmcnt(5)
	v_mfma_f32_16x16x32_bf16 v[44:47], v[108:111], v[88:91], v[44:47]
	s_waitcnt vmcnt(5)
	ds_write_b128 v131, v[64:67] offset:37120
	s_add_u32 s64, s26, s16
	s_addc_u32 s65, s27, 0
	s_waitcnt lgkmcnt(5)
	v_mfma_f32_16x16x32_bf16 v[40:43], v[108:111], v[156:159], v[40:43]
	s_min_u32 s16, s21, 12
	s_lshl_b32 s16, s16, 7
	s_waitcnt lgkmcnt(4)
	v_mfma_f32_16x16x32_bf16 v[36:39], v[108:111], v[160:163], v[36:39]
	s_waitcnt vmcnt(4)
	ds_write_b128 v131, v[72:75] offset:39168
	s_waitcnt lgkmcnt(4)
	v_mfma_f32_16x16x32_bf16 v[32:35], v[108:111], v[164:167], v[32:35]
	v_mfma_f32_16x16x32_bf16 v[28:31], v[112:115], v[88:91], v[28:31]
	s_waitcnt vmcnt(3)
	ds_write_b128 v131, v[60:63] offset:49536
	v_mfma_f32_16x16x32_bf16 v[24:27], v[112:115], v[156:159], v[24:27]
	v_mfma_f32_16x16x32_bf16 v[20:23], v[112:115], v[160:163], v[20:23]
	s_waitcnt vmcnt(2)
	ds_write_b128 v131, v[56:59] offset:51584
	v_mfma_f32_16x16x32_bf16 v[16:19], v[112:115], v[164:167], v[16:19]
	v_mfma_f32_16x16x32_bf16 v[12:15], v[148:151], v[88:91], v[12:15]
	s_waitcnt vmcnt(1)
	ds_write_b128 v131, v[52:55] offset:53632
	v_mfma_f32_16x16x32_bf16 v[8:11], v[148:151], v[156:159], v[8:11]
	s_add_u32 s64, s24, s16
	s_addc_u32 s65, s25, 0
	s_add_u32 s66, s26, s16
	v_mfma_f32_16x16x32_bf16 v[4:7], v[148:151], v[160:163], v[4:7]
	s_waitcnt vmcnt(0)
	ds_write_b128 v131, v[48:51] offset:55680
	s_addc_u32 s67, s27, 0
	v_mfma_f32_16x16x32_bf16 v[0:3], v[148:151], v[164:167], v[0:3]
	v_mfma_f32_16x16x32_bf16 v[88:91], v[152:155], v[88:91], v[84:87]
	v_mfma_f32_16x16x32_bf16 v[96:99], v[152:155], v[156:159], v[96:99]
	v_mfma_f32_16x16x32_bf16 v[92:95], v[152:155], v[160:163], v[92:95]
	v_mfma_f32_16x16x32_bf16 v[132:135], v[152:155], v[164:167], v[80:83]
	s_waitcnt lgkmcnt(0)
	s_barrier
	s_nop 0
	ds_read_b128 v[80:83], v119 offset:33024
	ds_read_b128 v[100:103], v130 offset:49536
	ds_read_b128 v[112:115], v130 offset:50560
	ds_read_b128 v[136:139], v130 offset:51584
	ds_read_b128 v[140:143], v130 offset:52608
	s_waitcnt lgkmcnt(3)
	v_mfma_f32_16x16x32_bf16 v[44:47], v[80:83], v[100:103], v[44:47]
	s_waitcnt lgkmcnt(2)
	v_mfma_f32_16x16x32_bf16 v[40:43], v[80:83], v[112:115], v[40:43]
	s_waitcnt lgkmcnt(1)
	v_mfma_f32_16x16x32_bf16 v[36:39], v[80:83], v[136:139], v[36:39]
	s_waitcnt lgkmcnt(0)
	v_mfma_f32_16x16x32_bf16 v[32:35], v[80:83], v[140:143], v[32:35]
	ds_read_b128 v[80:83], v119 offset:34048
	s_waitcnt lgkmcnt(0)
	v_mfma_f32_16x16x32_bf16 v[28:31], v[80:83], v[100:103], v[28:31]
	ds_read_b128 v[104:107], v119 offset:35072
	v_mfma_f32_16x16x32_bf16 v[24:27], v[80:83], v[112:115], v[24:27]
	ds_read_b128 v[144:147], v119 offset:36096
	v_mfma_f32_16x16x32_bf16 v[20:23], v[80:83], v[136:139], v[20:23]
	ds_read_b128 v[148:151], v119 offset:41280
	v_mfma_f32_16x16x32_bf16 v[16:19], v[80:83], v[140:143], v[16:19]
	ds_read_b128 v[152:155], v119 offset:42304
	s_waitcnt lgkmcnt(3)
	v_mfma_f32_16x16x32_bf16 v[12:15], v[104:107], v[100:103], v[12:15]
	ds_read_b128 v[156:159], v119 offset:43328
	v_mfma_f32_16x16x32_bf16 v[8:11], v[104:107], v[112:115], v[8:11]
	ds_read_b128 v[80:83], v119 offset:44352
	v_mfma_f32_16x16x32_bf16 v[4:7], v[104:107], v[136:139], v[4:7]
	ds_read_b128 v[84:87], v130 offset:57792
	v_mfma_f32_16x16x32_bf16 v[0:3], v[104:107], v[140:143], v[0:3]
	ds_read_b128 v[104:107], v130 offset:58816
	s_waitcnt lgkmcnt(6)
	v_mfma_f32_16x16x32_bf16 v[100:103], v[144:147], v[100:103], v[88:91]
	ds_read_b128 v[108:111], v130 offset:59840
	v_mfma_f32_16x16x32_bf16 v[96:99], v[144:147], v[112:115], v[96:99]
	ds_read_b128 v[112:115], v130 offset:60864
	v_mfma_f32_16x16x32_bf16 v[92:95], v[144:147], v[136:139], v[92:95]
	v_mfma_f32_16x16x32_bf16 v[88:91], v[144:147], v[140:143], v[132:135]
	ds_write_b128 v131, v[76:79]
	s_waitcnt lgkmcnt(4)
	v_mfma_f32_16x16x32_bf16 v[44:47], v[148:151], v[84:87], v[44:47]
	s_waitcnt lgkmcnt(3)
	v_mfma_f32_16x16x32_bf16 v[40:43], v[148:151], v[104:107], v[40:43]
	ds_write_b128 v131, v[68:71] offset:2048
	s_waitcnt lgkmcnt(3)
	v_mfma_f32_16x16x32_bf16 v[36:39], v[148:151], v[108:111], v[36:39]
	s_waitcnt lgkmcnt(2)
	v_mfma_f32_16x16x32_bf16 v[32:35], v[148:151], v[112:115], v[32:35]
	ds_write_b128 v131, v[64:67] offset:4096
	v_mfma_f32_16x16x32_bf16 v[28:31], v[152:155], v[84:87], v[28:31]
	v_mfma_f32_16x16x32_bf16 v[24:27], v[152:155], v[104:107], v[24:27]
	ds_write_b128 v131, v[72:75] offset:6144
	v_mfma_f32_16x16x32_bf16 v[20:23], v[152:155], v[108:111], v[20:23]
	v_mfma_f32_16x16x32_bf16 v[16:19], v[152:155], v[112:115], v[16:19]
	ds_write_b128 v131, v[60:63] offset:16512
	v_mfma_f32_16x16x32_bf16 v[12:15], v[156:159], v[84:87], v[12:15]
	v_mfma_f32_16x16x32_bf16 v[8:11], v[156:159], v[104:107], v[8:11]
	ds_write_b128 v131, v[56:59] offset:18560
	v_mfma_f32_16x16x32_bf16 v[4:7], v[156:159], v[108:111], v[4:7]
	v_mfma_f32_16x16x32_bf16 v[0:3], v[156:159], v[112:115], v[0:3]
	ds_write_b128 v131, v[52:55] offset:20608
	ds_write_b128 v131, v[48:51] offset:22656
	s_cmp_lt_u32 s21, 14
	s_mov_b32 s16, s21
	s_waitcnt lgkmcnt(0)
	s_barrier
	s_waitcnt vmcnt(3)
	v_mfma_f32_16x16x32_bf16 v[60:63], v[80:83], v[84:87], v[100:103]
	s_add_i32 s16, s22, -12
	s_cmp_gt_u32 s16, 4
	s_waitcnt vmcnt(2)
	v_mfma_f32_16x16x32_bf16 v[56:59], v[80:83], v[104:107], v[96:99]
	s_waitcnt vmcnt(1)
	v_mfma_f32_16x16x32_bf16 v[52:55], v[80:83], v[108:111], v[92:95]
	s_waitcnt vmcnt(0)
	v_mfma_f32_16x16x32_bf16 v[48:51], v[80:83], v[112:115], v[88:91]
	s_cbranch_scc1 .LBB0_749
; __device__ void phase_inproj(const Params& p, int layer, char* smem) {
;     ...
;     if (cb >= 12 && cb <= 16) {
; #pragma unroll
;       for (int m = 0; m < 4; ++m)
; #pragma unroll
;         for (int j = 0; j < 4; ++j) {
;           int row = row0 + m * 16 + fq * 4 + j;
;           int pos = row & (SEQ - 1);
; #pragma unroll
;           for (int n = 0; n < 2; ++n) {
;             float2 cs2 = RT[pos * 32 + n * 16 + fr];
;             float c = cs2.x, s = cs2.y;
;             float x1 = acc[m][n][j], x2 = acc[m][n + 2][j];
;             acc[m][n][j] = x1 * c - x2 * s;
;             acc[m][n + 2][j] = x2 * c + x1 * s;
;           }
;         }
;     }
	v_lshl_add_u32 v64, s20, 7, v126
	v_and_or_b32 v64, v64, s43, v127
	v_lshl_or_b32 v116, v64, 8, v128
	v_lshl_add_u64 v[92:93], s[14:15], 0, v[116:117]
	v_add_co_u32_e32 v94, vcc, s48, v92
	global_load_dwordx2 v[68:69], v116, s[14:15]
	global_load_dwordx2 v[64:65], v116, s[14:15] offset:256
	global_load_dwordx2 v[66:67], v116, s[14:15] offset:384
	global_load_dwordx2 v[72:73], v116, s[14:15] offset:512
	global_load_dwordx2 v[76:77], v116, s[14:15] offset:128
	global_load_dwordx2 v[74:75], v116, s[14:15] offset:640
	global_load_dwordx2 v[70:71], v116, s[14:15] offset:768
	global_load_dwordx2 v[78:79], v116, s[14:15] offset:896
	v_addc_co_u32_e32 v95, vcc, 0, v93, vcc
	v_add_co_u32_e32 v96, vcc, s49, v92
	s_waitcnt vmcnt(7)
	v_mov_b32_e32 v124, v68
	v_addc_co_u32_e32 v97, vcc, 0, v93, vcc
	global_load_dwordx2 v[82:83], v[96:97], off offset:-4096
	global_load_dwordx2 v[80:81], v[94:95], off offset:256
	global_load_dwordx2 v[84:85], v[94:95], off offset:384
	global_load_dwordx2 v[88:89], v[94:95], off offset:512
	global_load_dwordx2 v[98:99], v[94:95], off offset:128
	global_load_dwordx2 v[90:91], v[94:95], off offset:640
	global_load_dwordx2 v[86:87], v[94:95], off offset:768
	s_waitcnt vmcnt(13)
	v_mov_b32_e32 v125, v64
	v_mov_b32_e32 v64, v69
	s_waitcnt vmcnt(10)
	v_mov_b32_e32 v68, v76
	v_mul_f32_e32 v76, v46, v72
	v_mul_f32_e32 v130, v38, v73
	v_mul_f32_e32 v72, v38, v72
	v_mul_f32_e32 v132, v46, v73
	s_waitcnt vmcnt(9)
	v_mul_f32_e32 v134, v42, v74
	v_mul_f32_e32 v138, v42, v75
	v_mov_b32_e32 v38, v47
	v_mov_b32_e32 v46, v39
	v_mov_b32_e32 v42, v35
	v_add_co_u32_e32 v92, vcc, s50, v92
	v_mov_b32_e32 v69, v66
	v_mov_b32_e32 v66, v77
	v_mul_f32_e32 v136, v34, v75
	v_mul_f32_e32 v74, v34, v74
	v_mov_b32_e32 v34, v43
	v_pk_mul_f32 v[140:141], v[44:45], v[64:65]
	v_pk_mul_f32 v[64:65], v[36:37], v[64:65]
	s_waitcnt vmcnt(8)
	v_pk_mul_f32 v[38:39], v[38:39], v[70:71]
	v_pk_mul_f32 v[46:47], v[46:47], v[70:71]
	s_waitcnt vmcnt(7)
	v_pk_mul_f32 v[42:43], v[42:43], v[78:79]
	v_addc_co_u32_e32 v93, vcc, 0, v93, vcc
	v_pk_mul_f32 v[142:143], v[40:41], v[66:67]
	v_pk_mul_f32 v[66:67], v[32:33], v[66:67]
	v_pk_mul_f32 v[34:35], v[34:35], v[78:79]
	v_mov_b32_e32 v77, v38
	v_mov_b32_e32 v131, v39
	v_pk_fma_f32 v[44:45], v[44:45], v[124:125], v[64:65] neg_lo:[0,0,1] neg_hi:[0,0,1]
	v_mov_b32_e32 v73, v46
	v_mov_b32_e32 v133, v47
	v_mov_b32_e32 v75, v42
	v_mov_b32_e32 v139, v43
	global_load_dwordx2 v[94:95], v[94:95], off offset:896
	s_nop 0
	global_load_dwordx2 v[100:101], v[96:97], off
	global_load_dwordx2 v[102:103], v[96:97], off offset:256
	global_load_dwordx2 v[104:105], v[96:97], off offset:384
	global_load_dwordx2 v[106:107], v[96:97], off offset:128
	global_load_dwordx2 v[108:109], v[96:97], off offset:512
	global_load_dwordx2 v[110:111], v[96:97], off offset:640
	global_load_dwordx2 v[112:113], v[96:97], off offset:768
	s_nop 0
	global_load_dwordx2 v[96:97], v[96:97], off offset:896
	s_nop 0
	global_load_dwordx2 v[114:115], v[92:93], off offset:640
	global_load_dwordx2 v[120:121], v[92:93], off offset:768
	global_load_dwordx2 v[122:123], v[92:93], off offset:896
	v_mov_b32_e32 v135, v34
	v_mov_b32_e32 v137, v35
	v_pk_fma_f32 v[40:41], v[40:41], v[68:69], v[66:67] neg_lo:[0,0,1] neg_hi:[0,0,1]
	v_pk_fma_f32 v[32:33], v[32:33], v[68:69], v[142:143]
	v_pk_add_f32 v[46:47], v[76:77], v[130:131] neg_lo:[0,1] neg_hi:[0,1]
	v_pk_add_f32 v[38:39], v[72:73], v[132:133]
	v_pk_add_f32 v[34:35], v[74:75], v[138:139]
	global_load_dwordx2 v[74:75], v[92:93], off
	global_load_dwordx2 v[76:77], v[92:93], off offset:256
	v_pk_fma_f32 v[36:37], v[36:37], v[124:125], v[140:141]
	v_pk_add_f32 v[42:43], v[134:135], v[136:137] neg_lo:[0,1] neg_hi:[0,1]
	s_waitcnt vmcnt(20)
	v_mov_b32_e32 v64, v82
	s_waitcnt vmcnt(19)
	v_mov_b32_e32 v65, v80
	v_mov_b32_e32 v80, v83
	s_waitcnt vmcnt(18)
	v_mov_b32_e32 v71, v84
	s_waitcnt vmcnt(16)
	v_mov_b32_e32 v84, v99
	v_pk_mul_f32 v[66:67], v[28:29], v[80:81]
	v_pk_mul_f32 v[68:69], v[20:21], v[80:81]
	v_pk_mul_f32 v[72:73], v[24:25], v[84:85]
	v_pk_mul_f32 v[78:79], v[16:17], v[84:85]
	global_load_dwordx2 v[80:81], v[92:93], off offset:384
	global_load_dwordx2 v[82:83], v[92:93], off offset:512
	global_load_dwordx2 v[84:85], v[92:93], off offset:128
	v_mov_b32_e32 v70, v98
	v_mul_f32_e32 v92, v30, v88
	v_mul_f32_e32 v98, v22, v89
	v_mul_f32_e32 v88, v22, v88
	v_mul_f32_e32 v124, v30, v89
	s_waitcnt vmcnt(18)
	v_mul_f32_e32 v130, v26, v90
	v_mul_f32_e32 v132, v18, v91
	v_mul_f32_e32 v90, v18, v90
	v_mul_f32_e32 v134, v26, v91
	v_mov_b32_e32 v22, v31
	v_mov_b32_e32 v30, v23
	v_mov_b32_e32 v18, v27
	v_mov_b32_e32 v26, v19
	s_waitcnt vmcnt(17)
; __device__ void phase_inproj(const Params& p, int layer, char* smem) {
;     ...
;     if (cb >= 12 && cb <= 16) {
; #pragma unroll
;       for (int m = 0; m < 4; ++m)
; #pragma unroll
;         for (int j = 0; j < 4; ++j) {
;           int row = row0 + m * 16 + fq * 4 + j;
;           int pos = row & (SEQ - 1);
; #pragma unroll
;           for (int n = 0; n < 2; ++n) {
;             float2 cs2 = RT[pos * 32 + n * 16 + fr];
;             float c = cs2.x, s = cs2.y;
;             float x1 = acc[m][n][j], x2 = acc[m][n + 2][j];
;             acc[m][n][j] = x1 * c - x2 * s;
;             acc[m][n + 2][j] = x2 * c + x1 * s;
;           }
;         }
;     }
	v_pk_mul_f32 v[136:137], v[22:23], v[86:87]
	v_pk_mul_f32 v[22:23], v[30:31], v[86:87]
	v_mov_b32_e32 v93, v136
	v_mov_b32_e32 v89, v22
	v_mov_b32_e32 v125, v23
	v_mov_b32_e32 v99, v137
	v_pk_add_f32 v[22:23], v[88:89], v[124:125]
	v_pk_fma_f32 v[24:25], v[24:25], v[70:71], v[78:79] neg_lo:[0,0,1] neg_hi:[0,0,1]
	v_pk_fma_f32 v[16:17], v[16:17], v[70:71], v[72:73]
	s_waitcnt vmcnt(16)
	v_pk_mul_f32 v[30:31], v[18:19], v[94:95]
	v_pk_mul_f32 v[18:19], v[26:27], v[94:95]
	s_waitcnt vmcnt(14)
	v_mov_b32_e32 v27, v102
	v_mov_b32_e32 v91, v18
	v_mov_b32_e32 v135, v19
	v_pk_add_f32 v[18:19], v[90:91], v[134:135]
	v_mov_b32_e32 v102, v101
	s_waitcnt vmcnt(13)
	v_mov_b32_e32 v71, v104
	s_waitcnt vmcnt(12)
	v_mov_b32_e32 v104, v107
	s_waitcnt vmcnt(11)
	v_mul_f32_e32 v88, v6, v109
	v_mul_f32_e32 v90, v6, v108
	v_mov_b32_e32 v6, v15
	v_pk_fma_f32 v[28:29], v[28:29], v[64:65], v[68:69] neg_lo:[0,0,1] neg_hi:[0,0,1]
	v_pk_add_f32 v[68:69], v[92:93], v[98:99] neg_lo:[0,1] neg_hi:[0,1]
	v_pk_fma_f32 v[20:21], v[20:21], v[64:65], v[66:67]
	v_mov_b32_e32 v26, v100
	v_pk_mul_f32 v[64:65], v[12:13], v[102:103]
	v_pk_mul_f32 v[66:67], v[4:5], v[102:103]
	v_mov_b32_e32 v70, v106
	v_pk_mul_f32 v[72:73], v[8:9], v[104:105]
	v_pk_mul_f32 v[78:79], v[0:1], v[104:105]
	v_mul_f32_e32 v86, v14, v108
	v_mul_f32_e32 v92, v14, v109
	s_waitcnt vmcnt(10)
	v_mul_f32_e32 v94, v10, v110
	v_mul_f32_e32 v98, v2, v111
	v_mul_f32_e32 v100, v2, v110
	v_mul_f32_e32 v102, v10, v111
	s_waitcnt vmcnt(9)
	v_pk_mul_f32 v[104:105], v[6:7], v[112:113]
	v_mov_b32_e32 v14, v7
	v_mov_b32_e32 v2, v11
	v_mov_b32_e32 v10, v3
	v_mov_b32_e32 v87, v104
	v_mov_b32_e32 v89, v105
	v_pk_mul_f32 v[6:7], v[14:15], v[112:113]
	s_waitcnt vmcnt(8)
	v_pk_mul_f32 v[14:15], v[2:3], v[96:97]
	v_pk_fma_f32 v[8:9], v[8:9], v[70:71], v[78:79] neg_lo:[0,0,1] neg_hi:[0,0,1]
	v_pk_mul_f32 v[2:3], v[10:11], v[96:97]
	v_pk_fma_f32 v[0:1], v[0:1], v[70:71], v[72:73]
	s_waitcnt vmcnt(3)
	v_mov_b32_e32 v11, v76
	v_mov_b32_e32 v76, v75
	v_pk_fma_f32 v[12:13], v[12:13], v[26:27], v[66:67] neg_lo:[0,0,1] neg_hi:[0,0,1]
	v_pk_add_f32 v[66:67], v[86:87], v[88:89] neg_lo:[0,1] neg_hi:[0,1]
	v_mov_b32_e32 v91, v6
	v_mov_b32_e32 v93, v7
	v_pk_fma_f32 v[4:5], v[4:5], v[26:27], v[64:65]
	v_mov_b32_e32 v10, v74
	v_pk_mul_f32 v[26:27], v[60:61], v[76:77]
	v_pk_mul_f32 v[64:65], v[52:53], v[76:77]
	v_mul_f32_e32 v86, v50, v115
	v_mul_f32_e32 v88, v50, v114
	v_mov_b32_e32 v50, v59
	v_pk_add_f32 v[6:7], v[90:91], v[92:93]
	v_mul_f32_e32 v90, v58, v115
	v_pk_fma_f32 v[60:61], v[60:61], v[10:11], v[64:65] neg_lo:[0,0,1] neg_hi:[0,0,1]
	v_pk_fma_f32 v[52:53], v[52:53], v[10:11], v[26:27]
	s_waitcnt vmcnt(2)
	v_mov_b32_e32 v71, v80
	s_waitcnt vmcnt(1)
	v_mul_f32_e32 v78, v54, v83
	s_waitcnt vmcnt(0)
	v_mov_b32_e32 v80, v85
	v_pk_mul_f32 v[72:73], v[56:57], v[80:81]
	v_pk_mul_f32 v[74:75], v[48:49], v[80:81]
	v_mul_f32_e32 v80, v54, v82
	v_mov_b32_e32 v54, v63
	v_mov_b32_e32 v70, v84
	v_mul_f32_e32 v76, v62, v82
	v_mul_f32_e32 v82, v62, v83
	v_mul_f32_e32 v84, v58, v114
	v_pk_mul_f32 v[92:93], v[54:55], v[120:121]
	v_mov_b32_e32 v62, v55
	v_pk_mul_f32 v[10:11], v[50:51], v[122:123]
	v_mov_b32_e32 v58, v51
	v_mov_b32_e32 v131, v30
	v_mov_b32_e32 v133, v31
	v_mov_b32_e32 v95, v14
	v_mov_b32_e32 v99, v15
	v_mov_b32_e32 v77, v92
	v_mov_b32_e32 v79, v93
	v_pk_mul_f32 v[54:55], v[62:63], v[120:121]
	v_mov_b32_e32 v85, v10
	v_mov_b32_e32 v87, v11
	v_pk_mul_f32 v[26:27], v[58:59], v[122:123]
	v_pk_add_f32 v[30:31], v[130:131], v[132:133] neg_lo:[0,1] neg_hi:[0,1]
	v_pk_add_f32 v[14:15], v[94:95], v[98:99] neg_lo:[0,1] neg_hi:[0,1]
	v_mov_b32_e32 v101, v2
	v_mov_b32_e32 v103, v3
	v_pk_add_f32 v[64:65], v[76:77], v[78:79] neg_lo:[0,1] neg_hi:[0,1]
	v_mov_b32_e32 v81, v54
	v_mov_b32_e32 v83, v55
	v_pk_add_f32 v[10:11], v[84:85], v[86:87] neg_lo:[0,1] neg_hi:[0,1]
	v_mov_b32_e32 v89, v26
	v_mov_b32_e32 v91, v27
	v_pk_add_f32 v[2:3], v[100:101], v[102:103]
	v_pk_add_f32 v[54:55], v[80:81], v[82:83]
	v_pk_fma_f32 v[56:57], v[56:57], v[70:71], v[74:75] neg_lo:[0,0,1] neg_hi:[0,0,1]
	v_pk_fma_f32 v[48:49], v[48:49], v[70:71], v[72:73]
	v_pk_add_f32 v[50:51], v[88:89], v[90:91]
	v_mov_b32_e32 v58, v10
	v_mov_b32_e32 v59, v11
	v_mov_b32_e32 v62, v64
	v_mov_b32_e32 v63, v65
	v_mov_b32_e32 v10, v14
	v_mov_b32_e32 v11, v15
	v_mov_b32_e32 v14, v66
	v_mov_b32_e32 v15, v67
	v_mov_b32_e32 v26, v30
	v_mov_b32_e32 v27, v31
	v_mov_b32_e32 v30, v68
	v_mov_b32_e32 v31, v69

; template <int WM, int WN> ...
;     ...
; #pragma unroll
;   for (int n = 0; n < 4; ++n) fb0[n] = LDSF(cur + boff + n * 1024);
; #pragma unroll
;   for (int m = 0; m < 4; ++m) fa0[m] = LDSF(cur + aoff + m * 1024);
;   acc[3][0] = MFMA16(pa, pb0, acc[3][0]);
;   acc[3][1] = MFMA16(pa, pb1, acc[3][1]);
;   acc[3][2] = MFMA16(pa, pb2, acc[3][2]);
;   acc[3][3] = MFMA16(pa, pb3, acc[3][3]);
; #pragma unroll
;   for (int n = 0; n < 4; ++n) acc[0][n] = MFMA16(fa0[0], fb0[n], acc[0][n]);
; #pragma unroll
;   for (int m = 0; m < 4; ++m) fa1[m] = LDSF(cur + aoff + APAN + m * 1024);
; #pragma unroll
;   for (int n = 0; n < 4; ++n) acc[1][n] = MFMA16(fa0[1], fb0[n], acc[1][n]);
; #pragma unroll
;   for (int n = 0; n < 4; ++n) fb1[n] = LDSF(cur + boff + BPAN + n * 1024);
; #pragma unroll
;   for (int n = 0; n < 4; ++n) acc[2][n] = MFMA16(fa0[2], fb0[n], acc[2][n]);
;   *reinterpret_cast<uint4*>(nxt + wao) = a0;
;   *reinterpret_cast<uint4*>(nxt + wao + 32 * 64) = a1;
; #pragma unroll
;   for (int n = 0; n < 4; ++n) acc[3][n] = MFMA16(fa0[3], fb0[n], acc[3][n]);
;   *reinterpret_cast<uint4*>(nxt + wao + 64 * 64) = a2;
;   *reinterpret_cast<uint4*>(nxt + wao + 96 * 64) = a3;
; #pragma unroll
;   for (int n = 0; n < 4; ++n) acc[0][n] = MFMA16(fa1[0], fb1[n], acc[0][n]);
;   *reinterpret_cast<uint4*>(nxt + wbo) = b0;
;   *reinterpret_cast<uint4*>(nxt + wbo + 32 * 64) = b1;
; #pragma unroll
;   for (int n = 0; n < 4; ++n) acc[1][n] = MFMA16(fa1[1], fb1[n], acc[1][n]);
;   *reinterpret_cast<uint4*>(nxt + wbo + 64 * 64) = b2;
;   *reinterpret_cast<uint4*>(nxt + wbo + 96 * 64) = b3;
; #pragma unroll
;   for (int n = 0; n < 4; ++n) acc[2][n] = MFMA16(fa1[2], fb1[n], acc[2][n]);
;   pa = fa1[3];
;   pb0 = fb1[0]; pb1 = fb1[1]; pb2 = fb1[2]; pb3 = fb1[3];
;   SGB_(0x100, 5);
;   SGB_(0x008, 4);
; #pragma unroll
;   for (int i_ = 0; i_ < 11; ++i_) { SGB_(0x008, 1); SGB_(0x100, 1); }
; #pragma unroll
;   for (int i_ = 0; i_ < 8; ++i_) { SGB_(0x008, 2); SGB_(0x200, 1); SGB_(0x020, 1); }
;   SGB_(0x008, 1);
; }
; template <int WM, int WN, typename SrcF, typename PostF>
; __device__ __forceinline__ void gemm_stream(const int nsteps, SrcF src, PostF post, f32x4 (&acc)[WM][WN], char* smem) {
;     ...
;   for (int kt = 0; kt < nsteps; kt += 2) {
;     {
;       TileSrc s = src(min(kt + 2, nsteps - 1));
;       GLOAD_TILE(xa, s.a, s.lda, ACH);
;       GLOAD_TILE(xb, s.b, s.ldb, BCH);
;     }
.LBB0_1067:
	s_add_i32 s15, s12, 2
	s_add_i32 s12, s12, 4
	s_min_u32 s12, s12, 15
	s_lshl_b32 s12, s12, 7
	s_add_u32 s92, s20, s12
	s_addc_u32 s93, s21, 0
	s_add_u32 s94, s22, s12
	s_addc_u32 s95, s23, 0
	ds_read_b128 v[148:151], v119
	ds_read_b128 v[132:135], v130 offset:16512
	ds_read_b128 v[136:139], v130 offset:17536
	ds_read_b128 v[140:143], v130 offset:18560
	ds_read_b128 v[144:147], v130 offset:19584
	v_mfma_f32_16x16x32_bf16 v[84:87], v[80:83], v[84:87], v[100:103]
	v_mfma_f32_16x16x32_bf16 v[96:99], v[80:83], v[104:107], v[96:99]
	s_waitcnt vmcnt(4)
	ds_write_b128 v131, v[76:79] offset:33024
	global_load_dwordx4 v[76:79], v116, s[92:93]
	s_add_u32 s52, s20, s12
	s_addc_u32 s53, s21, 0
	v_mfma_f32_16x16x32_bf16 v[92:95], v[80:83], v[108:111], v[92:95]
	v_mfma_f32_16x16x32_bf16 v[80:83], v[80:83], v[112:115], v[88:91]
	s_waitcnt lgkmcnt(4)
	v_mfma_f32_16x16x32_bf16 v[44:47], v[148:151], v[132:135], v[44:47]
	s_nop 0
	ds_read_b128 v[88:91], v119 offset:1024
	s_waitcnt lgkmcnt(4)
	v_mfma_f32_16x16x32_bf16 v[40:43], v[148:151], v[136:139], v[40:43]
	ds_write_b128 v131, v[68:71] offset:35072
	global_load_dwordx4 v[68:71], v120, s[92:93]
	ds_read_b128 v[100:103], v119 offset:2048
	s_waitcnt lgkmcnt(5)
	v_mfma_f32_16x16x32_bf16 v[36:39], v[148:151], v[140:143], v[36:39]
	ds_read_b128 v[104:107], v119 offset:3072
	s_waitcnt lgkmcnt(5)
	v_mfma_f32_16x16x32_bf16 v[32:35], v[148:151], v[144:147], v[32:35]
	ds_read_b128 v[108:111], v119 offset:8256
	s_waitcnt lgkmcnt(4)
	v_mfma_f32_16x16x32_bf16 v[28:31], v[88:91], v[132:135], v[28:31]
	ds_read_b128 v[112:115], v119 offset:9280
	v_mfma_f32_16x16x32_bf16 v[24:27], v[88:91], v[136:139], v[24:27]
	ds_read_b128 v[148:151], v119 offset:10304
	v_mfma_f32_16x16x32_bf16 v[20:23], v[88:91], v[140:143], v[20:23]
	ds_write_b128 v131, v[64:67] offset:37120
	global_load_dwordx4 v[64:67], v122, s[92:93]
	ds_read_b128 v[152:155], v119 offset:11328
	v_mfma_f32_16x16x32_bf16 v[16:19], v[88:91], v[144:147], v[16:19]
	ds_read_b128 v[88:91], v130 offset:24768
	s_waitcnt lgkmcnt(7)
	v_mfma_f32_16x16x32_bf16 v[12:15], v[100:103], v[132:135], v[12:15]
	ds_read_b128 v[156:159], v130 offset:25792
	v_mfma_f32_16x16x32_bf16 v[8:11], v[100:103], v[136:139], v[8:11]
	ds_read_b128 v[160:163], v130 offset:26816
	v_mfma_f32_16x16x32_bf16 v[4:7], v[100:103], v[140:143], v[4:7]
	ds_write_b128 v131, v[72:75] offset:39168
	global_load_dwordx4 v[72:75], v124, s[92:93]
	ds_read_b128 v[164:167], v130 offset:27840
	v_mfma_f32_16x16x32_bf16 v[0:3], v[100:103], v[144:147], v[0:3]
	s_waitcnt lgkmcnt(10)
	v_mfma_f32_16x16x32_bf16 v[84:87], v[104:107], v[132:135], v[84:87]
	v_mfma_f32_16x16x32_bf16 v[96:99], v[104:107], v[136:139], v[96:99]
	v_mfma_f32_16x16x32_bf16 v[92:95], v[104:107], v[140:143], v[92:95]
	v_mfma_f32_16x16x32_bf16 v[80:83], v[104:107], v[144:147], v[80:83]
	s_waitcnt vmcnt(4)
	ds_write_b128 v131, v[60:63] offset:49536
	global_load_dwordx4 v[60:63], v116, s[94:95]
	s_waitcnt lgkmcnt(5)
	v_mfma_f32_16x16x32_bf16 v[44:47], v[108:111], v[88:91], v[44:47]
	s_add_u32 s52, s22, s12
	s_addc_u32 s53, s23, 0
	s_waitcnt lgkmcnt(4)
	v_mfma_f32_16x16x32_bf16 v[40:43], v[108:111], v[156:159], v[40:43]
	s_min_u32 s12, s15, 12
	s_lshl_b32 s12, s12, 7
	s_waitcnt lgkmcnt(3)
	v_mfma_f32_16x16x32_bf16 v[36:39], v[108:111], v[160:163], v[36:39]
	s_waitcnt lgkmcnt(1)
	v_mfma_f32_16x16x32_bf16 v[32:35], v[108:111], v[164:167], v[32:35]
	ds_write_b128 v131, v[56:59] offset:51584
	global_load_dwordx4 v[56:59], v120, s[94:95]
	v_mfma_f32_16x16x32_bf16 v[28:31], v[112:115], v[88:91], v[28:31]
	v_mfma_f32_16x16x32_bf16 v[24:27], v[112:115], v[156:159], v[24:27]
	v_mfma_f32_16x16x32_bf16 v[20:23], v[112:115], v[160:163], v[20:23]
	v_mfma_f32_16x16x32_bf16 v[16:19], v[112:115], v[164:167], v[16:19]
	v_mfma_f32_16x16x32_bf16 v[12:15], v[148:151], v[88:91], v[12:15]
	ds_write_b128 v131, v[52:55] offset:53632
	global_load_dwordx4 v[52:55], v122, s[94:95]
	v_mfma_f32_16x16x32_bf16 v[8:11], v[148:151], v[156:159], v[8:11]
	s_add_u32 s52, s20, s12
	s_addc_u32 s53, s21, 0
	s_add_u32 s54, s22, s12
	v_mfma_f32_16x16x32_bf16 v[4:7], v[148:151], v[160:163], v[4:7]
	s_addc_u32 s55, s23, 0
	v_mfma_f32_16x16x32_bf16 v[0:3], v[148:151], v[164:167], v[0:3]
	v_mfma_f32_16x16x32_bf16 v[88:91], v[152:155], v[88:91], v[84:87]
	ds_write_b128 v131, v[48:51] offset:55680
	global_load_dwordx4 v[48:51], v124, s[94:95]
	v_mfma_f32_16x16x32_bf16 v[96:99], v[152:155], v[156:159], v[96:99]
	v_mfma_f32_16x16x32_bf16 v[92:95], v[152:155], v[160:163], v[92:95]
	v_mfma_f32_16x16x32_bf16 v[132:135], v[152:155], v[164:167], v[80:83]
	s_waitcnt lgkmcnt(0)
	s_barrier
; template <int WM, int WN> ...
;     ...
; #pragma unroll
;   for (int n = 0; n < 4; ++n) fb0[n] = LDSF(cur + boff + n * 1024);
; #pragma unroll
;   for (int m = 0; m < 4; ++m) fa0[m] = LDSF(cur + aoff + m * 1024);
;   acc[3][0] = MFMA16(pa, pb0, acc[3][0]);
;   acc[3][1] = MFMA16(pa, pb1, acc[3][1]);
;   acc[3][2] = MFMA16(pa, pb2, acc[3][2]);
;   acc[3][3] = MFMA16(pa, pb3, acc[3][3]);
; #pragma unroll
;   for (int n = 0; n < 4; ++n) acc[0][n] = MFMA16(fa0[0], fb0[n], acc[0][n]);
; #pragma unroll
;   for (int m = 0; m < 4; ++m) fa1[m] = LDSF(cur + aoff + APAN + m * 1024);
; #pragma unroll
;   for (int n = 0; n < 4; ++n) acc[1][n] = MFMA16(fa0[1], fb0[n], acc[1][n]);
; #pragma unroll
;   for (int n = 0; n < 4; ++n) fb1[n] = LDSF(cur + boff + BPAN + n * 1024);
; #pragma unroll
;   for (int n = 0; n < 4; ++n) acc[2][n] = MFMA16(fa0[2], fb0[n], acc[2][n]);
;   *reinterpret_cast<uint4*>(nxt + wao) = a0;
;   *reinterpret_cast<uint4*>(nxt + wao + 32 * 64) = a1;
; #pragma unroll
;   for (int n = 0; n < 4; ++n) acc[3][n] = MFMA16(fa0[3], fb0[n], acc[3][n]);
;   *reinterpret_cast<uint4*>(nxt + wao + 64 * 64) = a2;
;   *reinterpret_cast<uint4*>(nxt + wao + 96 * 64) = a3;
; #pragma unroll
;   for (int n = 0; n < 4; ++n) acc[0][n] = MFMA16(fa1[0], fb1[n], acc[0][n]);
;   *reinterpret_cast<uint4*>(nxt + wbo) = b0;
;   *reinterpret_cast<uint4*>(nxt + wbo + 32 * 64) = b1;
; #pragma unroll
;   for (int n = 0; n < 4; ++n) acc[1][n] = MFMA16(fa1[1], fb1[n], acc[1][n]);
;   *reinterpret_cast<uint4*>(nxt + wbo + 64 * 64) = b2;
;   *reinterpret_cast<uint4*>(nxt + wbo + 96 * 64) = b3;
; #pragma unroll
;   for (int n = 0; n < 4; ++n) acc[2][n] = MFMA16(fa1[2], fb1[n], acc[2][n]);
;   pa = fa1[3];
;   pb0 = fb1[0]; pb1 = fb1[1]; pb2 = fb1[2]; pb3 = fb1[3];
;   SGB_(0x100, 5);
;   SGB_(0x008, 4);
; #pragma unroll
;   for (int i_ = 0; i_ < 11; ++i_) { SGB_(0x008, 1); SGB_(0x100, 1); }
; #pragma unroll
;   for (int i_ = 0; i_ < 8; ++i_) { SGB_(0x008, 2); SGB_(0x200, 1); SGB_(0x020, 1); }
;   SGB_(0x008, 1);
; }
; template <int WM, int WN, typename SrcF, typename PostF>
; __device__ __forceinline__ void gemm_stream(const int nsteps, SrcF src, PostF post, f32x4 (&acc)[WM][WN], char* smem) {
;     ...
;       TileSrc s = src(min(kt + 3, nsteps - 1));
;       GLOAD_TILE(ya, s.a, s.lda, ACH);
;       GLOAD_TILE(yb, s.b, s.ldb, BCH);
;     }
	s_nop 0
	ds_read_b128 v[80:83], v119 offset:33024
	ds_read_b128 v[100:103], v130 offset:49536
	ds_read_b128 v[112:115], v130 offset:50560
	ds_read_b128 v[136:139], v130 offset:51584
	ds_read_b128 v[140:143], v130 offset:52608
	s_waitcnt lgkmcnt(3)
	v_mfma_f32_16x16x32_bf16 v[44:47], v[80:83], v[100:103], v[44:47]
	s_waitcnt lgkmcnt(2)
	v_mfma_f32_16x16x32_bf16 v[40:43], v[80:83], v[112:115], v[40:43]
	s_waitcnt vmcnt(4)
	ds_write_b128 v131, v[76:79]
	global_load_dwordx4 v[76:79], v116, s[52:53] offset:384
	s_waitcnt lgkmcnt(2)
	v_mfma_f32_16x16x32_bf16 v[36:39], v[80:83], v[136:139], v[36:39]
	s_waitcnt lgkmcnt(0)
	v_mfma_f32_16x16x32_bf16 v[32:35], v[80:83], v[140:143], v[32:35]
	ds_read_b128 v[80:83], v119 offset:34048
	s_waitcnt lgkmcnt(0)
	v_mfma_f32_16x16x32_bf16 v[28:31], v[80:83], v[100:103], v[28:31]
	ds_write_b128 v131, v[68:71] offset:2048
	global_load_dwordx4 v[68:71], v120, s[52:53] offset:384
	ds_read_b128 v[104:107], v119 offset:35072
	v_mfma_f32_16x16x32_bf16 v[24:27], v[80:83], v[112:115], v[24:27]
	ds_read_b128 v[144:147], v119 offset:36096
	v_mfma_f32_16x16x32_bf16 v[20:23], v[80:83], v[136:139], v[20:23]
	ds_read_b128 v[148:151], v119 offset:41280
	v_mfma_f32_16x16x32_bf16 v[16:19], v[80:83], v[140:143], v[16:19]
	ds_read_b128 v[152:155], v119 offset:42304
	s_waitcnt lgkmcnt(3)
	v_mfma_f32_16x16x32_bf16 v[12:15], v[104:107], v[100:103], v[12:15]
	ds_write_b128 v131, v[64:67] offset:4096
	global_load_dwordx4 v[64:67], v122, s[52:53] offset:384
	ds_read_b128 v[156:159], v119 offset:43328
	v_mfma_f32_16x16x32_bf16 v[8:11], v[104:107], v[112:115], v[8:11]
	ds_read_b128 v[80:83], v119 offset:44352
	v_mfma_f32_16x16x32_bf16 v[4:7], v[104:107], v[136:139], v[4:7]
	ds_read_b128 v[84:87], v130 offset:57792
	v_mfma_f32_16x16x32_bf16 v[0:3], v[104:107], v[140:143], v[0:3]
	ds_write_b128 v131, v[72:75] offset:6144
	global_load_dwordx4 v[72:75], v124, s[52:53] offset:384
	ds_read_b128 v[104:107], v130 offset:58816
	s_waitcnt lgkmcnt(8)
	v_mfma_f32_16x16x32_bf16 v[100:103], v[144:147], v[100:103], v[88:91]
	ds_read_b128 v[108:111], v130 offset:59840
	v_mfma_f32_16x16x32_bf16 v[96:99], v[144:147], v[112:115], v[96:99]
	ds_read_b128 v[112:115], v130 offset:60864
	v_mfma_f32_16x16x32_bf16 v[92:95], v[144:147], v[136:139], v[92:95]
	v_mfma_f32_16x16x32_bf16 v[88:91], v[144:147], v[140:143], v[132:135]
	s_waitcnt vmcnt(4)
	ds_write_b128 v131, v[60:63] offset:16512
	global_load_dwordx4 v[60:63], v116, s[54:55] offset:384
	s_waitcnt lgkmcnt(5)
	v_mfma_f32_16x16x32_bf16 v[44:47], v[148:151], v[84:87], v[44:47]
	s_waitcnt lgkmcnt(3)
	v_mfma_f32_16x16x32_bf16 v[40:43], v[148:151], v[104:107], v[40:43]
	s_waitcnt lgkmcnt(2)
	v_mfma_f32_16x16x32_bf16 v[36:39], v[148:151], v[108:111], v[36:39]
	ds_write_b128 v131, v[56:59] offset:18560
	global_load_dwordx4 v[56:59], v120, s[54:55] offset:384
	s_waitcnt lgkmcnt(2)
	v_mfma_f32_16x16x32_bf16 v[32:35], v[148:151], v[112:115], v[32:35]
	v_mfma_f32_16x16x32_bf16 v[28:31], v[152:155], v[84:87], v[28:31]
	v_mfma_f32_16x16x32_bf16 v[24:27], v[152:155], v[104:107], v[24:27]
	v_mfma_f32_16x16x32_bf16 v[20:23], v[152:155], v[108:111], v[20:23]
	ds_write_b128 v131, v[52:55] offset:20608
	global_load_dwordx4 v[52:55], v122, s[54:55] offset:384
	v_mfma_f32_16x16x32_bf16 v[16:19], v[152:155], v[112:115], v[16:19]
	v_mfma_f32_16x16x32_bf16 v[12:15], v[156:159], v[84:87], v[12:15]
	v_mfma_f32_16x16x32_bf16 v[8:11], v[156:159], v[104:107], v[8:11]
	ds_write_b128 v131, v[48:51] offset:22656
	global_load_dwordx4 v[48:51], v124, s[54:55] offset:384
	v_mfma_f32_16x16x32_bf16 v[4:7], v[156:159], v[108:111], v[4:7]
	v_mfma_f32_16x16x32_bf16 v[0:3], v[156:159], v[112:115], v[0:3]
	s_cmp_lt_u32 s15, 12
	s_mov_b32 s12, s15
	s_waitcnt lgkmcnt(0)
	s_barrier
	s_cbranch_scc1 .LBB0_1067
	ds_read_b128 v[148:151], v119
	ds_read_b128 v[132:135], v130 offset:16512
	ds_read_b128 v[136:139], v130 offset:17536
	ds_read_b128 v[140:143], v130 offset:18560
	ds_read_b128 v[144:147], v130 offset:19584
	v_mfma_f32_16x16x32_bf16 v[84:87], v[80:83], v[84:87], v[100:103]
	s_add_i32 s15, s12, 2
	s_add_i32 s12, s12, 4
	s_min_u32 s12, s12, 15
	v_mfma_f32_16x16x32_bf16 v[96:99], v[80:83], v[104:107], v[96:99]
	s_lshl_b32 s12, s12, 7
	s_add_u32 s52, s20, s12
	s_addc_u32 s53, s21, 0
	v_mfma_f32_16x16x32_bf16 v[92:95], v[80:83], v[108:111], v[92:95]
	v_mfma_f32_16x16x32_bf16 v[80:83], v[80:83], v[112:115], v[88:91]
	s_waitcnt lgkmcnt(3)
	v_mfma_f32_16x16x32_bf16 v[44:47], v[148:151], v[132:135], v[44:47]
	s_nop 0
	ds_read_b128 v[88:91], v119 offset:1024
	s_waitcnt lgkmcnt(3)
	v_mfma_f32_16x16x32_bf16 v[40:43], v[148:151], v[136:139], v[40:43]
	ds_read_b128 v[100:103], v119 offset:2048
	s_waitcnt lgkmcnt(3)
	v_mfma_f32_16x16x32_bf16 v[36:39], v[148:151], v[140:143], v[36:39]
	ds_read_b128 v[104:107], v119 offset:3072
	s_waitcnt lgkmcnt(3)
	v_mfma_f32_16x16x32_bf16 v[32:35], v[148:151], v[144:147], v[32:35]
	ds_read_b128 v[108:111], v119 offset:8256
	s_waitcnt lgkmcnt(3)
	v_mfma_f32_16x16x32_bf16 v[28:31], v[88:91], v[132:135], v[28:31]
	ds_read_b128 v[112:115], v119 offset:9280
	v_mfma_f32_16x16x32_bf16 v[24:27], v[88:91], v[136:139], v[24:27]
	ds_read_b128 v[148:151], v119 offset:10304
	v_mfma_f32_16x16x32_bf16 v[20:23], v[88:91], v[140:143], v[20:23]
	ds_read_b128 v[152:155], v119 offset:11328
	v_mfma_f32_16x16x32_bf16 v[16:19], v[88:91], v[144:147], v[16:19]
	ds_read_b128 v[88:91], v130 offset:24768
	s_waitcnt lgkmcnt(6)
	v_mfma_f32_16x16x32_bf16 v[12:15], v[100:103], v[132:135], v[12:15]
	ds_read_b128 v[156:159], v130 offset:25792
	v_mfma_f32_16x16x32_bf16 v[8:11], v[100:103], v[136:139], v[8:11]
	ds_read_b128 v[160:163], v130 offset:26816
	v_mfma_f32_16x16x32_bf16 v[4:7], v[100:103], v[140:143], v[4:7]
	ds_read_b128 v[164:167], v130 offset:27840
	v_mfma_f32_16x16x32_bf16 v[0:3], v[100:103], v[144:147], v[0:3]
	s_waitcnt lgkmcnt(8)
; template <int WM, int WN> ...
;     ...
; #pragma unroll
;   for (int n = 0; n < 4; ++n) fb0[n] = LDSF(cur + boff + n * 1024);
; #pragma unroll
;   for (int m = 0; m < 4; ++m) fa0[m] = LDSF(cur + aoff + m * 1024);
;   acc[3][0] = MFMA16(pa, pb0, acc[3][0]);
;   acc[3][1] = MFMA16(pa, pb1, acc[3][1]);
;   acc[3][2] = MFMA16(pa, pb2, acc[3][2]);
;   acc[3][3] = MFMA16(pa, pb3, acc[3][3]);
; #pragma unroll
;   for (int n = 0; n < 4; ++n) acc[0][n] = MFMA16(fa0[0], fb0[n], acc[0][n]);
; #pragma unroll
;   for (int m = 0; m < 4; ++m) fa1[m] = LDSF(cur + aoff + APAN + m * 1024);
; #pragma unroll
;   for (int n = 0; n < 4; ++n) acc[1][n] = MFMA16(fa0[1], fb0[n], acc[1][n]);
; #pragma unroll
;   for (int n = 0; n < 4; ++n) fb1[n] = LDSF(cur + boff + BPAN + n * 1024);
; #pragma unroll
;   for (int n = 0; n < 4; ++n) acc[2][n] = MFMA16(fa0[2], fb0[n], acc[2][n]);
;   *reinterpret_cast<uint4*>(nxt + wao) = a0;
;   *reinterpret_cast<uint4*>(nxt + wao + 32 * 64) = a1;
; #pragma unroll
;   for (int n = 0; n < 4; ++n) acc[3][n] = MFMA16(fa0[3], fb0[n], acc[3][n]);
;   *reinterpret_cast<uint4*>(nxt + wao + 64 * 64) = a2;
;   *reinterpret_cast<uint4*>(nxt + wao + 96 * 64) = a3;
; #pragma unroll
;   for (int n = 0; n < 4; ++n) acc[0][n] = MFMA16(fa1[0], fb1[n], acc[0][n]);
;   *reinterpret_cast<uint4*>(nxt + wbo) = b0;
;   *reinterpret_cast<uint4*>(nxt + wbo + 32 * 64) = b1;
; #pragma unroll
;   for (int n = 0; n < 4; ++n) acc[1][n] = MFMA16(fa1[1], fb1[n], acc[1][n]);
;   *reinterpret_cast<uint4*>(nxt + wbo + 64 * 64) = b2;
;   *reinterpret_cast<uint4*>(nxt + wbo + 96 * 64) = b3;
; #pragma unroll
;   for (int n = 0; n < 4; ++n) acc[2][n] = MFMA16(fa1[2], fb1[n], acc[2][n]);
;   pa = fa1[3];
;   pb0 = fb1[0]; pb1 = fb1[1]; pb2 = fb1[2]; pb3 = fb1[3];
;   SGB_(0x100, 5);
;   SGB_(0x008, 4);
; #pragma unroll
;   for (int i_ = 0; i_ < 11; ++i_) { SGB_(0x008, 1); SGB_(0x100, 1); }
; #pragma unroll
;   for (int i_ = 0; i_ < 8; ++i_) { SGB_(0x008, 2); SGB_(0x200, 1); SGB_(0x020, 1); }
;   SGB_(0x008, 1);
; }
; template <int WM, int WN, typename SrcF, typename PostF>
; __device__ __forceinline__ void gemm_stream(const int nsteps, SrcF src, PostF post, f32x4 (&acc)[WM][WN], char* smem) {
;     ...
;   acc[3][0] = MFMA16(pa, pb0, acc[3][0]);
;   acc[3][1] = MFMA16(pa, pb1, acc[3][1]);
;   acc[3][2] = MFMA16(pa, pb2, acc[3][2]);
;   acc[3][3] = MFMA16(pa, pb3, acc[3][3]);
	v_mfma_f32_16x16x32_bf16 v[84:87], v[104:107], v[132:135], v[84:87]
	s_waitcnt vmcnt(7)
	ds_write_b128 v131, v[76:79] offset:33024
	v_mfma_f32_16x16x32_bf16 v[96:99], v[104:107], v[136:139], v[96:99]
	v_mfma_f32_16x16x32_bf16 v[92:95], v[104:107], v[140:143], v[92:95]
	s_waitcnt vmcnt(6)
	ds_write_b128 v131, v[68:71] offset:35072
	v_mfma_f32_16x16x32_bf16 v[80:83], v[104:107], v[144:147], v[80:83]
	s_waitcnt lgkmcnt(5)
	v_mfma_f32_16x16x32_bf16 v[44:47], v[108:111], v[88:91], v[44:47]
	s_waitcnt vmcnt(5)
	ds_write_b128 v131, v[64:67] offset:37120
	s_add_u32 s52, s22, s12
	s_addc_u32 s53, s23, 0
	s_waitcnt lgkmcnt(5)
	v_mfma_f32_16x16x32_bf16 v[40:43], v[108:111], v[156:159], v[40:43]
	s_min_u32 s12, s15, 12
	s_lshl_b32 s12, s12, 7
	s_waitcnt lgkmcnt(4)
	v_mfma_f32_16x16x32_bf16 v[36:39], v[108:111], v[160:163], v[36:39]
	s_waitcnt vmcnt(4)
	ds_write_b128 v131, v[72:75] offset:39168
	s_waitcnt lgkmcnt(4)
	v_mfma_f32_16x16x32_bf16 v[32:35], v[108:111], v[164:167], v[32:35]
	v_mfma_f32_16x16x32_bf16 v[28:31], v[112:115], v[88:91], v[28:31]
	s_waitcnt vmcnt(3)
	ds_write_b128 v131, v[60:63] offset:49536
	v_mfma_f32_16x16x32_bf16 v[24:27], v[112:115], v[156:159], v[24:27]
	v_mfma_f32_16x16x32_bf16 v[20:23], v[112:115], v[160:163], v[20:23]
	s_waitcnt vmcnt(2)
	ds_write_b128 v131, v[56:59] offset:51584
	v_mfma_f32_16x16x32_bf16 v[16:19], v[112:115], v[164:167], v[16:19]
	v_mfma_f32_16x16x32_bf16 v[12:15], v[148:151], v[88:91], v[12:15]
	s_waitcnt vmcnt(1)
	ds_write_b128 v131, v[52:55] offset:53632
	v_mfma_f32_16x16x32_bf16 v[8:11], v[148:151], v[156:159], v[8:11]
	s_add_u32 s52, s20, s12
	s_addc_u32 s53, s21, 0
	s_add_u32 s54, s22, s12
	v_mfma_f32_16x16x32_bf16 v[4:7], v[148:151], v[160:163], v[4:7]
	s_waitcnt vmcnt(0)
	ds_write_b128 v131, v[48:51] offset:55680
	s_addc_u32 s55, s23, 0
	v_mfma_f32_16x16x32_bf16 v[0:3], v[148:151], v[164:167], v[0:3]
	v_mfma_f32_16x16x32_bf16 v[88:91], v[152:155], v[88:91], v[84:87]
	v_mfma_f32_16x16x32_bf16 v[96:99], v[152:155], v[156:159], v[96:99]
	v_mfma_f32_16x16x32_bf16 v[92:95], v[152:155], v[160:163], v[92:95]
	v_mfma_f32_16x16x32_bf16 v[132:135], v[152:155], v[164:167], v[80:83]
	s_waitcnt lgkmcnt(0)
	s_barrier
	s_nop 0
	ds_read_b128 v[80:83], v119 offset:33024
	ds_read_b128 v[100:103], v130 offset:49536
	ds_read_b128 v[112:115], v130 offset:50560
	ds_read_b128 v[136:139], v130 offset:51584
	ds_read_b128 v[140:143], v130 offset:52608
	s_waitcnt lgkmcnt(3)
	v_mfma_f32_16x16x32_bf16 v[44:47], v[80:83], v[100:103], v[44:47]
	s_waitcnt lgkmcnt(2)
	v_mfma_f32_16x16x32_bf16 v[40:43], v[80:83], v[112:115], v[40:43]
	s_waitcnt lgkmcnt(1)
	v_mfma_f32_16x16x32_bf16 v[36:39], v[80:83], v[136:139], v[36:39]
	s_waitcnt lgkmcnt(0)
	v_mfma_f32_16x16x32_bf16 v[32:35], v[80:83], v[140:143], v[32:35]
	ds_read_b128 v[80:83], v119 offset:34048
	s_waitcnt lgkmcnt(0)
	v_mfma_f32_16x16x32_bf16 v[28:31], v[80:83], v[100:103], v[28:31]
	ds_read_b128 v[104:107], v119 offset:35072
	v_mfma_f32_16x16x32_bf16 v[24:27], v[80:83], v[112:115], v[24:27]
	ds_read_b128 v[144:147], v119 offset:36096
	v_mfma_f32_16x16x32_bf16 v[20:23], v[80:83], v[136:139], v[20:23]
	ds_read_b128 v[148:151], v119 offset:41280
	v_mfma_f32_16x16x32_bf16 v[16:19], v[80:83], v[140:143], v[16:19]
	ds_read_b128 v[152:155], v119 offset:42304
	s_waitcnt lgkmcnt(3)
	v_mfma_f32_16x16x32_bf16 v[12:15], v[104:107], v[100:103], v[12:15]
	ds_read_b128 v[156:159], v119 offset:43328
	v_mfma_f32_16x16x32_bf16 v[8:11], v[104:107], v[112:115], v[8:11]
	ds_read_b128 v[80:83], v119 offset:44352
	v_mfma_f32_16x16x32_bf16 v[4:7], v[104:107], v[136:139], v[4:7]
	ds_read_b128 v[84:87], v130 offset:57792
	v_mfma_f32_16x16x32_bf16 v[0:3], v[104:107], v[140:143], v[0:3]
	ds_read_b128 v[104:107], v130 offset:58816
	s_waitcnt lgkmcnt(6)
	v_mfma_f32_16x16x32_bf16 v[100:103], v[144:147], v[100:103], v[88:91]
	ds_read_b128 v[108:111], v130 offset:59840
	v_mfma_f32_16x16x32_bf16 v[96:99], v[144:147], v[112:115], v[96:99]
	ds_read_b128 v[112:115], v130 offset:60864
	v_mfma_f32_16x16x32_bf16 v[92:95], v[144:147], v[136:139], v[92:95]
	v_mfma_f32_16x16x32_bf16 v[88:91], v[144:147], v[140:143], v[132:135]
	ds_write_b128 v131, v[76:79]
	s_waitcnt lgkmcnt(4)
	v_mfma_f32_16x16x32_bf16 v[44:47], v[148:151], v[84:87], v[44:47]
	s_waitcnt lgkmcnt(3)
	v_mfma_f32_16x16x32_bf16 v[40:43], v[148:151], v[104:107], v[40:43]
	ds_write_b128 v131, v[68:71] offset:2048
	s_waitcnt lgkmcnt(3)
	v_mfma_f32_16x16x32_bf16 v[36:39], v[148:151], v[108:111], v[36:39]
	s_waitcnt lgkmcnt(2)
	v_mfma_f32_16x16x32_bf16 v[32:35], v[148:151], v[112:115], v[32:35]
	ds_write_b128 v131, v[64:67] offset:4096
	v_mfma_f32_16x16x32_bf16 v[28:31], v[152:155], v[84:87], v[28:31]
	v_mfma_f32_16x16x32_bf16 v[24:27], v[152:155], v[104:107], v[24:27]
	ds_write_b128 v131, v[72:75] offset:6144
	v_mfma_f32_16x16x32_bf16 v[20:23], v[152:155], v[108:111], v[20:23]
	v_mfma_f32_16x16x32_bf16 v[16:19], v[152:155], v[112:115], v[16:19]
	ds_write_b128 v131, v[60:63] offset:16512
	v_mfma_f32_16x16x32_bf16 v[12:15], v[156:159], v[84:87], v[12:15]
	v_mfma_f32_16x16x32_bf16 v[8:11], v[156:159], v[104:107], v[8:11]
	ds_write_b128 v131, v[56:59] offset:18560
	v_mfma_f32_16x16x32_bf16 v[4:7], v[156:159], v[108:111], v[4:7]
	v_mfma_f32_16x16x32_bf16 v[0:3], v[156:159], v[112:115], v[0:3]
	ds_write_b128 v131, v[52:55] offset:20608
	ds_write_b128 v131, v[48:51] offset:22656
	s_cmp_lt_u32 s15, 14
	s_mov_b32 s12, s15
	s_waitcnt lgkmcnt(0)
	s_barrier
	s_waitcnt vmcnt(3)
	v_mfma_f32_16x16x32_bf16 v[60:63], v[80:83], v[84:87], v[100:103]
	s_add_i32 s12, s16, -12
	s_cmp_gt_u32 s12, 4
	s_waitcnt vmcnt(2)
	v_mfma_f32_16x16x32_bf16 v[56:59], v[80:83], v[104:107], v[96:99]
	s_waitcnt vmcnt(1)
	v_mfma_f32_16x16x32_bf16 v[52:55], v[80:83], v[108:111], v[92:95]
	s_waitcnt vmcnt(0)
	v_mfma_f32_16x16x32_bf16 v[48:51], v[80:83], v[112:115], v[88:91]
	s_cbranch_scc1 .LBB0_1070
; __device__ void phase_inproj(const Params& p, int layer, char* smem) {
;     ...
;     if (cb >= 12 && cb <= 16) {
; #pragma unroll
;       for (int m = 0; m < 4; ++m)
; #pragma unroll
;         for (int j = 0; j < 4; ++j) {
;           int row = row0 + m * 16 + fq * 4 + j;
;           int pos = row & (SEQ - 1);
; #pragma unroll
;           for (int n = 0; n < 2; ++n) {
;             float2 cs2 = RT[pos * 32 + n * 16 + fr];
;             float c = cs2.x, s = cs2.y;
;             float x1 = acc[m][n][j], x2 = acc[m][n + 2][j];
;             acc[m][n][j] = x1 * c - x2 * s;
;             acc[m][n + 2][j] = x2 * c + x1 * s;
;           }
;         }
;     }
	v_lshl_add_u32 v64, s14, 7, v126
	v_and_or_b32 v64, v64, s39, v127
	v_lshl_or_b32 v116, v64, 8, v128
	v_lshl_add_u64 v[92:93], s[8:9], 0, v[116:117]
	v_add_co_u32_e32 v94, vcc, s43, v92
	global_load_dwordx2 v[68:69], v116, s[8:9]
	global_load_dwordx2 v[64:65], v116, s[8:9] offset:256
	global_load_dwordx2 v[66:67], v116, s[8:9] offset:384
	global_load_dwordx2 v[72:73], v116, s[8:9] offset:512
	global_load_dwordx2 v[76:77], v116, s[8:9] offset:128
	global_load_dwordx2 v[74:75], v116, s[8:9] offset:640
	global_load_dwordx2 v[70:71], v116, s[8:9] offset:768
	global_load_dwordx2 v[78:79], v116, s[8:9] offset:896
	v_addc_co_u32_e32 v95, vcc, 0, v93, vcc
	v_add_co_u32_e32 v96, vcc, s44, v92
	s_waitcnt vmcnt(7)
	v_mov_b32_e32 v124, v68
	v_addc_co_u32_e32 v97, vcc, 0, v93, vcc
	global_load_dwordx2 v[82:83], v[96:97], off offset:-4096
	global_load_dwordx2 v[80:81], v[94:95], off offset:256
	global_load_dwordx2 v[84:85], v[94:95], off offset:384
	global_load_dwordx2 v[88:89], v[94:95], off offset:512
	global_load_dwordx2 v[98:99], v[94:95], off offset:128
	global_load_dwordx2 v[90:91], v[94:95], off offset:640
	global_load_dwordx2 v[86:87], v[94:95], off offset:768
	s_waitcnt vmcnt(13)
	v_mov_b32_e32 v125, v64
	v_mov_b32_e32 v64, v69
	s_waitcnt vmcnt(10)
	v_mov_b32_e32 v68, v76
	v_mul_f32_e32 v76, v46, v72
	v_mul_f32_e32 v130, v38, v73
	v_mul_f32_e32 v72, v38, v72
	v_mul_f32_e32 v132, v46, v73
	s_waitcnt vmcnt(9)
	v_mul_f32_e32 v134, v42, v74
	v_mul_f32_e32 v138, v42, v75
	v_mov_b32_e32 v38, v47
	v_mov_b32_e32 v46, v39
	v_mov_b32_e32 v42, v35
	v_add_co_u32_e32 v92, vcc, s45, v92
	v_mov_b32_e32 v69, v66
	v_mov_b32_e32 v66, v77
	v_mul_f32_e32 v136, v34, v75
	v_mul_f32_e32 v74, v34, v74
	v_mov_b32_e32 v34, v43
	v_pk_mul_f32 v[140:141], v[44:45], v[64:65]
	v_pk_mul_f32 v[64:65], v[36:37], v[64:65]
	s_waitcnt vmcnt(8)
	v_pk_mul_f32 v[38:39], v[38:39], v[70:71]
	v_pk_mul_f32 v[46:47], v[46:47], v[70:71]
	s_waitcnt vmcnt(7)
	v_pk_mul_f32 v[42:43], v[42:43], v[78:79]
	v_addc_co_u32_e32 v93, vcc, 0, v93, vcc
	v_pk_mul_f32 v[142:143], v[40:41], v[66:67]
	v_pk_mul_f32 v[66:67], v[32:33], v[66:67]
	v_pk_mul_f32 v[34:35], v[34:35], v[78:79]
	v_mov_b32_e32 v77, v38
	v_mov_b32_e32 v131, v39
	v_pk_fma_f32 v[44:45], v[44:45], v[124:125], v[64:65] neg_lo:[0,0,1] neg_hi:[0,0,1]
	v_mov_b32_e32 v73, v46
	v_mov_b32_e32 v133, v47
	v_mov_b32_e32 v75, v42
	v_mov_b32_e32 v139, v43
	global_load_dwordx2 v[94:95], v[94:95], off offset:896
	s_nop 0
	global_load_dwordx2 v[100:101], v[96:97], off
	global_load_dwordx2 v[102:103], v[96:97], off offset:256
	global_load_dwordx2 v[104:105], v[96:97], off offset:384
	global_load_dwordx2 v[106:107], v[96:97], off offset:128
	global_load_dwordx2 v[108:109], v[96:97], off offset:512
	global_load_dwordx2 v[110:111], v[96:97], off offset:640
	global_load_dwordx2 v[112:113], v[96:97], off offset:768
	s_nop 0
	global_load_dwordx2 v[96:97], v[96:97], off offset:896
	s_nop 0
	global_load_dwordx2 v[114:115], v[92:93], off offset:640
	global_load_dwordx2 v[120:121], v[92:93], off offset:768
	global_load_dwordx2 v[122:123], v[92:93], off offset:896
	v_mov_b32_e32 v135, v34
	v_mov_b32_e32 v137, v35
	v_pk_fma_f32 v[40:41], v[40:41], v[68:69], v[66:67] neg_lo:[0,0,1] neg_hi:[0,0,1]
	v_pk_fma_f32 v[32:33], v[32:33], v[68:69], v[142:143]
	v_pk_add_f32 v[46:47], v[76:77], v[130:131] neg_lo:[0,1] neg_hi:[0,1]
	v_pk_add_f32 v[38:39], v[72:73], v[132:133]
	v_pk_add_f32 v[34:35], v[74:75], v[138:139]
	global_load_dwordx2 v[74:75], v[92:93], off
	global_load_dwordx2 v[76:77], v[92:93], off offset:256
	v_pk_fma_f32 v[36:37], v[36:37], v[124:125], v[140:141]
	v_pk_add_f32 v[42:43], v[134:135], v[136:137] neg_lo:[0,1] neg_hi:[0,1]
	s_waitcnt vmcnt(20)
	v_mov_b32_e32 v64, v82
	s_waitcnt vmcnt(19)
	v_mov_b32_e32 v65, v80
	v_mov_b32_e32 v80, v83
	s_waitcnt vmcnt(18)
	v_mov_b32_e32 v71, v84
	s_waitcnt vmcnt(16)
	v_mov_b32_e32 v84, v99
	v_pk_mul_f32 v[66:67], v[28:29], v[80:81]
	v_pk_mul_f32 v[68:69], v[20:21], v[80:81]
	v_pk_mul_f32 v[72:73], v[24:25], v[84:85]
	v_pk_mul_f32 v[78:79], v[16:17], v[84:85]
	global_load_dwordx2 v[80:81], v[92:93], off offset:384
	global_load_dwordx2 v[82:83], v[92:93], off offset:512
	global_load_dwordx2 v[84:85], v[92:93], off offset:128
	v_mov_b32_e32 v70, v98
	v_mul_f32_e32 v92, v30, v88
	v_mul_f32_e32 v98, v22, v89
	v_mul_f32_e32 v88, v22, v88
	v_mul_f32_e32 v124, v30, v89
	s_waitcnt vmcnt(18)
	v_mul_f32_e32 v130, v26, v90
	v_mul_f32_e32 v132, v18, v91
	v_mul_f32_e32 v90, v18, v90
	v_mul_f32_e32 v134, v26, v91
	v_mov_b32_e32 v22, v31
	v_mov_b32_e32 v30, v23
	v_mov_b32_e32 v18, v27
	v_mov_b32_e32 v26, v19
	s_waitcnt vmcnt(17)
; __device__ void phase_inproj(const Params& p, int layer, char* smem) {
;     ...
;     if (cb >= 12 && cb <= 16) {
; #pragma unroll
;       for (int m = 0; m < 4; ++m)
; #pragma unroll
;         for (int j = 0; j < 4; ++j) {
;           int row = row0 + m * 16 + fq * 4 + j;
;           int pos = row & (SEQ - 1);
; #pragma unroll
;           for (int n = 0; n < 2; ++n) {
;             float2 cs2 = RT[pos * 32 + n * 16 + fr];
;             float c = cs2.x, s = cs2.y;
;             float x1 = acc[m][n][j], x2 = acc[m][n + 2][j];
;             acc[m][n][j] = x1 * c - x2 * s;
;             acc[m][n + 2][j] = x2 * c + x1 * s;
;           }
;         }
;     }
	v_pk_mul_f32 v[136:137], v[22:23], v[86:87]
	v_pk_mul_f32 v[22:23], v[30:31], v[86:87]
	v_mov_b32_e32 v93, v136
	v_mov_b32_e32 v89, v22
	v_mov_b32_e32 v125, v23
	v_mov_b32_e32 v99, v137
	v_pk_add_f32 v[22:23], v[88:89], v[124:125]
	v_pk_fma_f32 v[24:25], v[24:25], v[70:71], v[78:79] neg_lo:[0,0,1] neg_hi:[0,0,1]
	v_pk_fma_f32 v[16:17], v[16:17], v[70:71], v[72:73]
	s_waitcnt vmcnt(16)
	v_pk_mul_f32 v[30:31], v[18:19], v[94:95]
	v_pk_mul_f32 v[18:19], v[26:27], v[94:95]
	s_waitcnt vmcnt(14)
	v_mov_b32_e32 v27, v102
	v_mov_b32_e32 v91, v18
	v_mov_b32_e32 v135, v19
	v_pk_add_f32 v[18:19], v[90:91], v[134:135]
	v_mov_b32_e32 v102, v101
	s_waitcnt vmcnt(13)
	v_mov_b32_e32 v71, v104
	s_waitcnt vmcnt(12)
	v_mov_b32_e32 v104, v107
	s_waitcnt vmcnt(11)
	v_mul_f32_e32 v88, v6, v109
	v_mul_f32_e32 v90, v6, v108
	v_mov_b32_e32 v6, v15
	v_pk_fma_f32 v[28:29], v[28:29], v[64:65], v[68:69] neg_lo:[0,0,1] neg_hi:[0,0,1]
	v_pk_add_f32 v[68:69], v[92:93], v[98:99] neg_lo:[0,1] neg_hi:[0,1]
	v_pk_fma_f32 v[20:21], v[20:21], v[64:65], v[66:67]
	v_mov_b32_e32 v26, v100
	v_pk_mul_f32 v[64:65], v[12:13], v[102:103]
	v_pk_mul_f32 v[66:67], v[4:5], v[102:103]
	v_mov_b32_e32 v70, v106
	v_pk_mul_f32 v[72:73], v[8:9], v[104:105]
	v_pk_mul_f32 v[78:79], v[0:1], v[104:105]
	v_mul_f32_e32 v86, v14, v108
	v_mul_f32_e32 v92, v14, v109
	s_waitcnt vmcnt(10)
	v_mul_f32_e32 v94, v10, v110
	v_mul_f32_e32 v98, v2, v111
	v_mul_f32_e32 v100, v2, v110
	v_mul_f32_e32 v102, v10, v111
	s_waitcnt vmcnt(9)
	v_pk_mul_f32 v[104:105], v[6:7], v[112:113]
	v_mov_b32_e32 v14, v7
	v_mov_b32_e32 v2, v11
	v_mov_b32_e32 v10, v3
	v_mov_b32_e32 v87, v104
	v_mov_b32_e32 v89, v105
	v_pk_mul_f32 v[6:7], v[14:15], v[112:113]
	s_waitcnt vmcnt(8)
	v_pk_mul_f32 v[14:15], v[2:3], v[96:97]
	v_pk_fma_f32 v[8:9], v[8:9], v[70:71], v[78:79] neg_lo:[0,0,1] neg_hi:[0,0,1]
	v_pk_mul_f32 v[2:3], v[10:11], v[96:97]
	v_pk_fma_f32 v[0:1], v[0:1], v[70:71], v[72:73]
	s_waitcnt vmcnt(3)
	v_mov_b32_e32 v11, v76
	v_mov_b32_e32 v76, v75
	v_pk_fma_f32 v[12:13], v[12:13], v[26:27], v[66:67] neg_lo:[0,0,1] neg_hi:[0,0,1]
	v_pk_add_f32 v[66:67], v[86:87], v[88:89] neg_lo:[0,1] neg_hi:[0,1]
	v_mov_b32_e32 v91, v6
	v_mov_b32_e32 v93, v7
	v_pk_fma_f32 v[4:5], v[4:5], v[26:27], v[64:65]
	v_mov_b32_e32 v10, v74
	v_pk_mul_f32 v[26:27], v[60:61], v[76:77]
	v_pk_mul_f32 v[64:65], v[52:53], v[76:77]
	v_mul_f32_e32 v86, v50, v115
	v_mul_f32_e32 v88, v50, v114
	v_mov_b32_e32 v50, v59
	v_pk_add_f32 v[6:7], v[90:91], v[92:93]
	v_mul_f32_e32 v90, v58, v115
	v_pk_fma_f32 v[60:61], v[60:61], v[10:11], v[64:65] neg_lo:[0,0,1] neg_hi:[0,0,1]
	v_pk_fma_f32 v[52:53], v[52:53], v[10:11], v[26:27]
	s_waitcnt vmcnt(2)
	v_mov_b32_e32 v71, v80
	s_waitcnt vmcnt(1)
	v_mul_f32_e32 v78, v54, v83
	s_waitcnt vmcnt(0)
	v_mov_b32_e32 v80, v85
	v_pk_mul_f32 v[72:73], v[56:57], v[80:81]
	v_pk_mul_f32 v[74:75], v[48:49], v[80:81]
	v_mul_f32_e32 v80, v54, v82
	v_mov_b32_e32 v54, v63
	v_mov_b32_e32 v70, v84
	v_mul_f32_e32 v76, v62, v82
	v_mul_f32_e32 v82, v62, v83
	v_mul_f32_e32 v84, v58, v114
	v_pk_mul_f32 v[92:93], v[54:55], v[120:121]
	v_mov_b32_e32 v62, v55
	v_pk_mul_f32 v[10:11], v[50:51], v[122:123]
	v_mov_b32_e32 v58, v51
	v_mov_b32_e32 v131, v30
	v_mov_b32_e32 v133, v31
	v_mov_b32_e32 v95, v14
	v_mov_b32_e32 v99, v15
	v_mov_b32_e32 v77, v92
	v_mov_b32_e32 v79, v93
	v_pk_mul_f32 v[54:55], v[62:63], v[120:121]
	v_mov_b32_e32 v85, v10
	v_mov_b32_e32 v87, v11
	v_pk_mul_f32 v[26:27], v[58:59], v[122:123]
	v_pk_add_f32 v[30:31], v[130:131], v[132:133] neg_lo:[0,1] neg_hi:[0,1]
	v_pk_add_f32 v[14:15], v[94:95], v[98:99] neg_lo:[0,1] neg_hi:[0,1]
	v_mov_b32_e32 v101, v2
	v_mov_b32_e32 v103, v3
	v_pk_add_f32 v[64:65], v[76:77], v[78:79] neg_lo:[0,1] neg_hi:[0,1]
	v_mov_b32_e32 v81, v54
	v_mov_b32_e32 v83, v55
	v_pk_add_f32 v[10:11], v[84:85], v[86:87] neg_lo:[0,1] neg_hi:[0,1]
	v_mov_b32_e32 v89, v26
	v_mov_b32_e32 v91, v27
	v_pk_add_f32 v[2:3], v[100:101], v[102:103]
	v_pk_add_f32 v[54:55], v[80:81], v[82:83]
	v_pk_fma_f32 v[56:57], v[56:57], v[70:71], v[74:75] neg_lo:[0,0,1] neg_hi:[0,0,1]
	v_pk_fma_f32 v[48:49], v[48:49], v[70:71], v[72:73]
	v_pk_add_f32 v[50:51], v[88:89], v[90:91]
	v_mov_b32_e32 v58, v10
	v_mov_b32_e32 v59, v11
	v_mov_b32_e32 v62, v64
	v_mov_b32_e32 v63, v65
	v_mov_b32_e32 v10, v14
	v_mov_b32_e32 v11, v15
	v_mov_b32_e32 v14, v66
	v_mov_b32_e32 v15, v67
	v_mov_b32_e32 v26, v30
	v_mov_b32_e32 v27, v31
	v_mov_b32_e32 v30, v68
	v_mov_b32_e32 v31, v69

; template <int WM, int WN> ...
;     ...
; #pragma unroll
;   for (int n = 0; n < 4; ++n) fb0[n] = LDSF(cur + boff + n * 1024);
; #pragma unroll
;   for (int m = 0; m < 4; ++m) fa0[m] = LDSF(cur + aoff + m * 1024);
;   acc[3][0] = MFMA16(pa, pb0, acc[3][0]);
;   acc[3][1] = MFMA16(pa, pb1, acc[3][1]);
;   acc[3][2] = MFMA16(pa, pb2, acc[3][2]);
;   acc[3][3] = MFMA16(pa, pb3, acc[3][3]);
; #pragma unroll
;   for (int n = 0; n < 4; ++n) acc[0][n] = MFMA16(fa0[0], fb0[n], acc[0][n]);
; #pragma unroll
;   for (int m = 0; m < 4; ++m) fa1[m] = LDSF(cur + aoff + APAN + m * 1024);
; #pragma unroll
;   for (int n = 0; n < 4; ++n) acc[1][n] = MFMA16(fa0[1], fb0[n], acc[1][n]);
; #pragma unroll
;   for (int n = 0; n < 4; ++n) fb1[n] = LDSF(cur + boff + BPAN + n * 1024);
; #pragma unroll
;   for (int n = 0; n < 4; ++n) acc[2][n] = MFMA16(fa0[2], fb0[n], acc[2][n]);
;   *reinterpret_cast<uint4*>(nxt + wao) = a0;
;   *reinterpret_cast<uint4*>(nxt + wao + 32 * 64) = a1;
; #pragma unroll
;   for (int n = 0; n < 4; ++n) acc[3][n] = MFMA16(fa0[3], fb0[n], acc[3][n]);
;   *reinterpret_cast<uint4*>(nxt + wao + 64 * 64) = a2;
;   *reinterpret_cast<uint4*>(nxt + wao + 96 * 64) = a3;
; #pragma unroll
;   for (int n = 0; n < 4; ++n) acc[0][n] = MFMA16(fa1[0], fb1[n], acc[0][n]);
;   *reinterpret_cast<uint4*>(nxt + wbo) = b0;
;   *reinterpret_cast<uint4*>(nxt + wbo + 32 * 64) = b1;
; #pragma unroll
;   for (int n = 0; n < 4; ++n) acc[1][n] = MFMA16(fa1[1], fb1[n], acc[1][n]);
;   *reinterpret_cast<uint4*>(nxt + wbo + 64 * 64) = b2;
;   *reinterpret_cast<uint4*>(nxt + wbo + 96 * 64) = b3;
; #pragma unroll
;   for (int n = 0; n < 4; ++n) acc[2][n] = MFMA16(fa1[2], fb1[n], acc[2][n]);
;   pa = fa1[3];
;   pb0 = fb1[0]; pb1 = fb1[1]; pb2 = fb1[2]; pb3 = fb1[3];
;   SGB_(0x100, 5);
;   SGB_(0x008, 4);
; #pragma unroll
;   for (int i_ = 0; i_ < 11; ++i_) { SGB_(0x008, 1); SGB_(0x100, 1); }
; #pragma unroll
;   for (int i_ = 0; i_ < 8; ++i_) { SGB_(0x008, 2); SGB_(0x200, 1); SGB_(0x020, 1); }
;   SGB_(0x008, 1);
; }
; template <int WM, int WN, typename SrcF, typename PostF>
; __device__ __forceinline__ void gemm_stream(const int nsteps, SrcF src, PostF post, f32x4 (&acc)[WM][WN], char* smem) {
;     ...
;   for (int kt = 0; kt < nsteps; kt += 2) {
;     {
;       TileSrc s = src(min(kt + 2, nsteps - 1));
;       GLOAD_TILE(xa, s.a, s.lda, ACH);
;       GLOAD_TILE(xb, s.b, s.ldb, BCH);
;     }
.LBB0_1281:
	s_add_i32 s27, s5, 2
	s_add_i32 s5, s5, 4
	s_min_u32 s5, s5, 15
	s_lshl_b32 s5, s5, 7
	s_add_u32 s92, s8, s5
	s_addc_u32 s93, s9, 0
	s_add_u32 s94, s10, s5
	s_addc_u32 s95, s11, 0
	ds_read_b128 v[144:147], v124
	ds_read_b128 v[128:131], v125 offset:16512
	ds_read_b128 v[132:135], v125 offset:17536
	ds_read_b128 v[136:139], v125 offset:18560
	ds_read_b128 v[140:143], v125 offset:19584
	v_mfma_f32_16x16x32_bf16 v[64:67], v[48:51], v[64:67], v[92:95]
	v_mfma_f32_16x16x32_bf16 v[88:91], v[48:51], v[104:107], v[88:91]
	s_waitcnt vmcnt(4)
	ds_write_b128 v126, v[32:35] offset:33024
	global_load_dwordx4 v[32:35], v116, s[92:93]
	s_add_u32 s34, s8, s5
	s_addc_u32 s35, s9, 0
	v_mfma_f32_16x16x32_bf16 v[80:83], v[48:51], v[112:115], v[80:83]
	v_mfma_f32_16x16x32_bf16 v[48:51], v[48:51], v[108:111], v[56:59]
	s_waitcnt lgkmcnt(4)
	v_mfma_f32_16x16x32_bf16 v[56:59], v[144:147], v[128:131], v[100:103]
	ds_read_b128 v[92:95], v124 offset:1024
	s_waitcnt lgkmcnt(4)
	v_mfma_f32_16x16x32_bf16 v[96:99], v[144:147], v[132:135], v[96:99]
	ds_write_b128 v126, v[20:23] offset:35072
	global_load_dwordx4 v[20:23], v118, s[92:93]
	ds_read_b128 v[100:103], v124 offset:2048
	s_waitcnt lgkmcnt(5)
	v_mfma_f32_16x16x32_bf16 v[84:87], v[144:147], v[136:139], v[84:87]
	ds_read_b128 v[104:107], v124 offset:3072
	s_waitcnt lgkmcnt(5)
	v_mfma_f32_16x16x32_bf16 v[76:79], v[144:147], v[140:143], v[76:79]
	ds_read_b128 v[108:111], v124 offset:8256
	s_waitcnt lgkmcnt(4)
	v_mfma_f32_16x16x32_bf16 v[72:75], v[92:95], v[128:131], v[72:75]
	ds_read_b128 v[112:115], v124 offset:9280
	v_mfma_f32_16x16x32_bf16 v[68:71], v[92:95], v[132:135], v[68:71]
	ds_read_b128 v[144:147], v124 offset:10304
	v_mfma_f32_16x16x32_bf16 v[60:63], v[92:95], v[136:139], v[60:63]
	ds_write_b128 v126, v[16:19] offset:37120
	global_load_dwordx4 v[16:19], v120, s[92:93]
	ds_read_b128 v[148:151], v124 offset:11328
	v_mfma_f32_16x16x32_bf16 v[52:55], v[92:95], v[140:143], v[52:55]
	ds_read_b128 v[92:95], v125 offset:24768
	s_waitcnt lgkmcnt(7)
	v_mfma_f32_16x16x32_bf16 v[44:47], v[100:103], v[128:131], v[44:47]
	ds_read_b128 v[152:155], v125 offset:25792
	v_mfma_f32_16x16x32_bf16 v[40:43], v[100:103], v[132:135], v[40:43]
	ds_read_b128 v[156:159], v125 offset:26816
	v_mfma_f32_16x16x32_bf16 v[36:39], v[100:103], v[136:139], v[36:39]
	ds_write_b128 v126, v[24:27] offset:39168
	global_load_dwordx4 v[24:27], v122, s[92:93]
	ds_read_b128 v[160:163], v125 offset:27840
	v_mfma_f32_16x16x32_bf16 v[28:31], v[100:103], v[140:143], v[28:31]
	s_waitcnt lgkmcnt(10)
	v_mfma_f32_16x16x32_bf16 v[64:67], v[104:107], v[128:131], v[64:67]
	v_mfma_f32_16x16x32_bf16 v[88:91], v[104:107], v[132:135], v[88:91]
	v_mfma_f32_16x16x32_bf16 v[80:83], v[104:107], v[136:139], v[80:83]
	v_mfma_f32_16x16x32_bf16 v[48:51], v[104:107], v[140:143], v[48:51]
	s_waitcnt vmcnt(4)
	ds_write_b128 v126, v[12:15] offset:49536
	global_load_dwordx4 v[12:15], v116, s[94:95]
	s_waitcnt lgkmcnt(5)
	v_mfma_f32_16x16x32_bf16 v[56:59], v[108:111], v[92:95], v[56:59]
	s_add_u32 s34, s10, s5
	s_addc_u32 s35, s11, 0
	s_waitcnt lgkmcnt(4)
	v_mfma_f32_16x16x32_bf16 v[96:99], v[108:111], v[152:155], v[96:99]
	s_min_u32 s5, s27, 12
	s_lshl_b32 s5, s5, 7
	s_waitcnt lgkmcnt(3)
	v_mfma_f32_16x16x32_bf16 v[84:87], v[108:111], v[156:159], v[84:87]
	s_waitcnt lgkmcnt(1)
	v_mfma_f32_16x16x32_bf16 v[76:79], v[108:111], v[160:163], v[76:79]
	ds_write_b128 v126, v[8:11] offset:51584
	global_load_dwordx4 v[8:11], v118, s[94:95]
	v_mfma_f32_16x16x32_bf16 v[72:75], v[112:115], v[92:95], v[72:75]
	v_mfma_f32_16x16x32_bf16 v[68:71], v[112:115], v[152:155], v[68:71]
	v_mfma_f32_16x16x32_bf16 v[60:63], v[112:115], v[156:159], v[60:63]
	v_mfma_f32_16x16x32_bf16 v[52:55], v[112:115], v[160:163], v[52:55]
	v_mfma_f32_16x16x32_bf16 v[44:47], v[144:147], v[92:95], v[44:47]
	ds_write_b128 v126, v[4:7] offset:53632
	global_load_dwordx4 v[4:7], v120, s[94:95]
	v_mfma_f32_16x16x32_bf16 v[40:43], v[144:147], v[152:155], v[40:43]
	s_add_u32 s34, s8, s5
	s_addc_u32 s35, s9, 0
	s_add_u32 s36, s10, s5
	v_mfma_f32_16x16x32_bf16 v[36:39], v[144:147], v[156:159], v[36:39]
	s_addc_u32 s37, s11, 0
	v_mfma_f32_16x16x32_bf16 v[28:31], v[144:147], v[160:163], v[28:31]
	v_mfma_f32_16x16x32_bf16 v[92:95], v[148:151], v[92:95], v[64:67]
	ds_write_b128 v126, v[0:3] offset:55680
	global_load_dwordx4 v[0:3], v122, s[94:95]
	v_mfma_f32_16x16x32_bf16 v[88:91], v[148:151], v[152:155], v[88:91]
	v_mfma_f32_16x16x32_bf16 v[80:83], v[148:151], v[156:159], v[80:83]
	v_mfma_f32_16x16x32_bf16 v[100:103], v[148:151], v[160:163], v[48:51]
	s_waitcnt lgkmcnt(0)
	s_barrier
	s_nop 0
	ds_read_b128 v[48:51], v124 offset:33024
	ds_read_b128 v[108:111], v125 offset:49536
	ds_read_b128 v[128:131], v125 offset:50560
	ds_read_b128 v[132:135], v125 offset:51584
	ds_read_b128 v[136:139], v125 offset:52608
	s_waitcnt lgkmcnt(3)
	v_mfma_f32_16x16x32_bf16 v[140:143], v[48:51], v[108:111], v[56:59]
	s_waitcnt lgkmcnt(2)
	v_mfma_f32_16x16x32_bf16 v[96:99], v[48:51], v[128:131], v[96:99]
	s_waitcnt vmcnt(4)
	ds_write_b128 v126, v[32:35]
	global_load_dwordx4 v[32:35], v116, s[34:35] offset:384
	s_waitcnt lgkmcnt(2)
	v_mfma_f32_16x16x32_bf16 v[84:87], v[48:51], v[132:135], v[84:87]
	s_waitcnt lgkmcnt(0)
	v_mfma_f32_16x16x32_bf16 v[76:79], v[48:51], v[136:139], v[76:79]
	ds_read_b128 v[48:51], v124 offset:34048
	s_waitcnt lgkmcnt(0)
	v_mfma_f32_16x16x32_bf16 v[72:75], v[48:51], v[108:111], v[72:75]
	ds_write_b128 v126, v[20:23] offset:2048
	global_load_dwordx4 v[20:23], v118, s[34:35] offset:384
	ds_read_b128 v[56:59], v124 offset:35072
	v_mfma_f32_16x16x32_bf16 v[68:71], v[48:51], v[128:131], v[68:71]
	ds_read_b128 v[144:147], v124 offset:36096
	v_mfma_f32_16x16x32_bf16 v[60:63], v[48:51], v[132:135], v[60:63]
	ds_read_b128 v[148:151], v124 offset:41280
	v_mfma_f32_16x16x32_bf16 v[52:55], v[48:51], v[136:139], v[52:55]
	ds_read_b128 v[152:155], v124 offset:42304
	s_waitcnt lgkmcnt(3)
	v_mfma_f32_16x16x32_bf16 v[44:47], v[56:59], v[108:111], v[44:47]
	ds_write_b128 v126, v[16:19] offset:4096
	global_load_dwordx4 v[16:19], v120, s[34:35] offset:384
	ds_read_b128 v[156:159], v124 offset:43328
	v_mfma_f32_16x16x32_bf16 v[40:43], v[56:59], v[128:131], v[40:43]
	ds_read_b128 v[48:51], v124 offset:44352
	v_mfma_f32_16x16x32_bf16 v[36:39], v[56:59], v[132:135], v[36:39]
	ds_read_b128 v[64:67], v125 offset:57792
	v_mfma_f32_16x16x32_bf16 v[28:31], v[56:59], v[136:139], v[28:31]
	ds_write_b128 v126, v[24:27] offset:6144
	global_load_dwordx4 v[24:27], v122, s[34:35] offset:384
	ds_read_b128 v[104:107], v125 offset:58816
	s_waitcnt lgkmcnt(8)
	v_mfma_f32_16x16x32_bf16 v[92:95], v[144:147], v[108:111], v[92:95]
	ds_read_b128 v[112:115], v125 offset:59840
	v_mfma_f32_16x16x32_bf16 v[88:91], v[144:147], v[128:131], v[88:91]
	ds_read_b128 v[108:111], v125 offset:60864
	v_mfma_f32_16x16x32_bf16 v[80:83], v[144:147], v[132:135], v[80:83]
	v_mfma_f32_16x16x32_bf16 v[56:59], v[144:147], v[136:139], v[100:103]
	s_waitcnt vmcnt(4)
	ds_write_b128 v126, v[12:15] offset:16512
	global_load_dwordx4 v[12:15], v116, s[36:37] offset:384
	s_waitcnt lgkmcnt(5)
	v_mfma_f32_16x16x32_bf16 v[100:103], v[148:151], v[64:67], v[140:143]
	s_waitcnt lgkmcnt(3)
	v_mfma_f32_16x16x32_bf16 v[96:99], v[148:151], v[104:107], v[96:99]
	s_waitcnt lgkmcnt(2)
	v_mfma_f32_16x16x32_bf16 v[84:87], v[148:151], v[112:115], v[84:87]
	ds_write_b128 v126, v[8:11] offset:18560
	global_load_dwordx4 v[8:11], v118, s[36:37] offset:384
	s_waitcnt lgkmcnt(2)
	v_mfma_f32_16x16x32_bf16 v[76:79], v[148:151], v[108:111], v[76:79]
	v_mfma_f32_16x16x32_bf16 v[72:75], v[152:155], v[64:67], v[72:75]
	v_mfma_f32_16x16x32_bf16 v[68:71], v[152:155], v[104:107], v[68:71]
	v_mfma_f32_16x16x32_bf16 v[60:63], v[152:155], v[112:115], v[60:63]
	ds_write_b128 v126, v[4:7] offset:20608
	global_load_dwordx4 v[4:7], v120, s[36:37] offset:384
	v_mfma_f32_16x16x32_bf16 v[52:55], v[152:155], v[108:111], v[52:55]
	v_mfma_f32_16x16x32_bf16 v[44:47], v[156:159], v[64:67], v[44:47]
	v_mfma_f32_16x16x32_bf16 v[40:43], v[156:159], v[104:107], v[40:43]
	ds_write_b128 v126, v[0:3] offset:22656
	global_load_dwordx4 v[0:3], v122, s[36:37] offset:384
	v_mfma_f32_16x16x32_bf16 v[36:39], v[156:159], v[112:115], v[36:39]
	v_mfma_f32_16x16x32_bf16 v[28:31], v[156:159], v[108:111], v[28:31]
	s_cmp_lt_u32 s27, 12
	s_mov_b32 s5, s27
	s_waitcnt lgkmcnt(0)
	s_barrier
	s_cbranch_scc1 .LBB0_1281
	ds_read_b128 v[144:147], v124
	ds_read_b128 v[128:131], v125 offset:16512
	ds_read_b128 v[132:135], v125 offset:17536
	ds_read_b128 v[136:139], v125 offset:18560
	ds_read_b128 v[140:143], v125 offset:19584
	v_mfma_f32_16x16x32_bf16 v[64:67], v[48:51], v[64:67], v[92:95]
	s_add_i32 s27, s5, 2
	s_add_i32 s5, s5, 4
	s_min_u32 s5, s5, 15
	v_mfma_f32_16x16x32_bf16 v[88:91], v[48:51], v[104:107], v[88:91]
	s_lshl_b32 s5, s5, 7
	s_add_u32 s34, s8, s5
	s_addc_u32 s35, s9, 0
	v_mfma_f32_16x16x32_bf16 v[80:83], v[48:51], v[112:115], v[80:83]
	v_mfma_f32_16x16x32_bf16 v[48:51], v[48:51], v[108:111], v[56:59]
	s_waitcnt lgkmcnt(3)
	v_mfma_f32_16x16x32_bf16 v[56:59], v[144:147], v[128:131], v[100:103]
	ds_read_b128 v[92:95], v124 offset:1024
	s_waitcnt lgkmcnt(3)
	v_mfma_f32_16x16x32_bf16 v[96:99], v[144:147], v[132:135], v[96:99]
	ds_read_b128 v[100:103], v124 offset:2048
	s_waitcnt lgkmcnt(3)
	v_mfma_f32_16x16x32_bf16 v[84:87], v[144:147], v[136:139], v[84:87]
	ds_read_b128 v[104:107], v124 offset:3072
	s_waitcnt lgkmcnt(3)
	v_mfma_f32_16x16x32_bf16 v[76:79], v[144:147], v[140:143], v[76:79]
	ds_read_b128 v[108:111], v124 offset:8256
	s_waitcnt lgkmcnt(3)
	v_mfma_f32_16x16x32_bf16 v[72:75], v[92:95], v[128:131], v[72:75]
	ds_read_b128 v[112:115], v124 offset:9280
	v_mfma_f32_16x16x32_bf16 v[68:71], v[92:95], v[132:135], v[68:71]
	ds_read_b128 v[144:147], v124 offset:10304
	v_mfma_f32_16x16x32_bf16 v[60:63], v[92:95], v[136:139], v[60:63]
	ds_read_b128 v[148:151], v124 offset:11328
	v_mfma_f32_16x16x32_bf16 v[52:55], v[92:95], v[140:143], v[52:55]
	ds_read_b128 v[92:95], v125 offset:24768
	s_waitcnt lgkmcnt(6)
	v_mfma_f32_16x16x32_bf16 v[44:47], v[100:103], v[128:131], v[44:47]
	ds_read_b128 v[152:155], v125 offset:25792
	v_mfma_f32_16x16x32_bf16 v[40:43], v[100:103], v[132:135], v[40:43]
	ds_read_b128 v[156:159], v125 offset:26816
	v_mfma_f32_16x16x32_bf16 v[36:39], v[100:103], v[136:139], v[36:39]
	ds_read_b128 v[160:163], v125 offset:27840
	v_mfma_f32_16x16x32_bf16 v[28:31], v[100:103], v[140:143], v[28:31]
	s_waitcnt lgkmcnt(8)
	v_mfma_f32_16x16x32_bf16 v[64:67], v[104:107], v[128:131], v[64:67]
	s_waitcnt vmcnt(7)
	ds_write_b128 v126, v[32:35] offset:33024
	v_mfma_f32_16x16x32_bf16 v[88:91], v[104:107], v[132:135], v[88:91]
	v_mfma_f32_16x16x32_bf16 v[80:83], v[104:107], v[136:139], v[80:83]
	s_waitcnt vmcnt(6)
	ds_write_b128 v126, v[20:23] offset:35072
	v_mfma_f32_16x16x32_bf16 v[48:51], v[104:107], v[140:143], v[48:51]
	s_waitcnt lgkmcnt(5)
	v_mfma_f32_16x16x32_bf16 v[56:59], v[108:111], v[92:95], v[56:59]
	s_waitcnt vmcnt(5)
	ds_write_b128 v126, v[16:19] offset:37120
	s_add_u32 s34, s10, s5
	s_addc_u32 s35, s11, 0
	s_waitcnt lgkmcnt(5)
	v_mfma_f32_16x16x32_bf16 v[96:99], v[108:111], v[152:155], v[96:99]
	s_min_u32 s5, s27, 12
	s_lshl_b32 s5, s5, 7
	s_waitcnt lgkmcnt(4)
	v_mfma_f32_16x16x32_bf16 v[84:87], v[108:111], v[156:159], v[84:87]
	s_waitcnt vmcnt(4)
	ds_write_b128 v126, v[24:27] offset:39168
	s_waitcnt lgkmcnt(4)
	v_mfma_f32_16x16x32_bf16 v[76:79], v[108:111], v[160:163], v[76:79]
	v_mfma_f32_16x16x32_bf16 v[72:75], v[112:115], v[92:95], v[72:75]
	s_waitcnt vmcnt(3)
	ds_write_b128 v126, v[12:15] offset:49536
	v_mfma_f32_16x16x32_bf16 v[68:71], v[112:115], v[152:155], v[68:71]
	v_mfma_f32_16x16x32_bf16 v[60:63], v[112:115], v[156:159], v[60:63]
	s_waitcnt vmcnt(2)
	ds_write_b128 v126, v[8:11] offset:51584
	v_mfma_f32_16x16x32_bf16 v[52:55], v[112:115], v[160:163], v[52:55]
	v_mfma_f32_16x16x32_bf16 v[44:47], v[144:147], v[92:95], v[44:47]
	s_waitcnt vmcnt(1)
	ds_write_b128 v126, v[4:7] offset:53632
	v_mfma_f32_16x16x32_bf16 v[40:43], v[144:147], v[152:155], v[40:43]
	s_add_u32 s34, s8, s5
	s_addc_u32 s35, s9, 0
	s_add_u32 s36, s10, s5
	v_mfma_f32_16x16x32_bf16 v[36:39], v[144:147], v[156:159], v[36:39]
	s_waitcnt vmcnt(0)
	ds_write_b128 v126, v[0:3] offset:55680
	s_addc_u32 s37, s11, 0
	v_mfma_f32_16x16x32_bf16 v[28:31], v[144:147], v[160:163], v[28:31]
	v_mfma_f32_16x16x32_bf16 v[92:95], v[148:151], v[92:95], v[64:67]
	v_mfma_f32_16x16x32_bf16 v[88:91], v[148:151], v[152:155], v[88:91]
	v_mfma_f32_16x16x32_bf16 v[80:83], v[148:151], v[156:159], v[80:83]
	v_mfma_f32_16x16x32_bf16 v[100:103], v[148:151], v[160:163], v[48:51]
	s_waitcnt lgkmcnt(0)
	s_barrier
	s_nop 0
	ds_read_b128 v[48:51], v124 offset:33024
	ds_read_b128 v[108:111], v125 offset:49536
	ds_read_b128 v[128:131], v125 offset:50560
	ds_read_b128 v[132:135], v125 offset:51584
	ds_read_b128 v[136:139], v125 offset:52608
	s_waitcnt lgkmcnt(3)
	v_mfma_f32_16x16x32_bf16 v[140:143], v[48:51], v[108:111], v[56:59]
	s_waitcnt lgkmcnt(2)
	v_mfma_f32_16x16x32_bf16 v[96:99], v[48:51], v[128:131], v[96:99]
	s_waitcnt lgkmcnt(1)
	v_mfma_f32_16x16x32_bf16 v[84:87], v[48:51], v[132:135], v[84:87]
	s_waitcnt lgkmcnt(0)
	v_mfma_f32_16x16x32_bf16 v[76:79], v[48:51], v[136:139], v[76:79]
	ds_read_b128 v[48:51], v124 offset:34048
	s_waitcnt lgkmcnt(0)
	v_mfma_f32_16x16x32_bf16 v[72:75], v[48:51], v[108:111], v[72:75]
	ds_read_b128 v[56:59], v124 offset:35072
	v_mfma_f32_16x16x32_bf16 v[68:71], v[48:51], v[128:131], v[68:71]
	ds_read_b128 v[144:147], v124 offset:36096
	v_mfma_f32_16x16x32_bf16 v[60:63], v[48:51], v[132:135], v[60:63]
	ds_read_b128 v[148:151], v124 offset:41280
	v_mfma_f32_16x16x32_bf16 v[52:55], v[48:51], v[136:139], v[52:55]
	ds_read_b128 v[152:155], v124 offset:42304
	s_waitcnt lgkmcnt(3)
	v_mfma_f32_16x16x32_bf16 v[44:47], v[56:59], v[108:111], v[44:47]
	ds_read_b128 v[156:159], v124 offset:43328
	v_mfma_f32_16x16x32_bf16 v[40:43], v[56:59], v[128:131], v[40:43]
	ds_read_b128 v[48:51], v124 offset:44352
	v_mfma_f32_16x16x32_bf16 v[36:39], v[56:59], v[132:135], v[36:39]
	ds_read_b128 v[64:67], v125 offset:57792
	v_mfma_f32_16x16x32_bf16 v[28:31], v[56:59], v[136:139], v[28:31]
	ds_read_b128 v[104:107], v125 offset:58816
	s_waitcnt lgkmcnt(6)
	v_mfma_f32_16x16x32_bf16 v[92:95], v[144:147], v[108:111], v[92:95]
	ds_read_b128 v[112:115], v125 offset:59840
	v_mfma_f32_16x16x32_bf16 v[88:91], v[144:147], v[128:131], v[88:91]
	ds_read_b128 v[108:111], v125 offset:60864
	v_mfma_f32_16x16x32_bf16 v[80:83], v[144:147], v[132:135], v[80:83]
	v_mfma_f32_16x16x32_bf16 v[56:59], v[144:147], v[136:139], v[100:103]
	ds_write_b128 v126, v[32:35]
	s_waitcnt lgkmcnt(4)
	v_mfma_f32_16x16x32_bf16 v[100:103], v[148:151], v[64:67], v[140:143]
	s_waitcnt lgkmcnt(3)
	v_mfma_f32_16x16x32_bf16 v[96:99], v[148:151], v[104:107], v[96:99]
	ds_write_b128 v126, v[20:23] offset:2048
	s_waitcnt lgkmcnt(3)
	v_mfma_f32_16x16x32_bf16 v[84:87], v[148:151], v[112:115], v[84:87]
	s_waitcnt lgkmcnt(2)
	v_mfma_f32_16x16x32_bf16 v[76:79], v[148:151], v[108:111], v[76:79]
	ds_write_b128 v126, v[16:19] offset:4096
	v_mfma_f32_16x16x32_bf16 v[72:75], v[152:155], v[64:67], v[72:75]
	v_mfma_f32_16x16x32_bf16 v[68:71], v[152:155], v[104:107], v[68:71]
	ds_write_b128 v126, v[24:27] offset:6144
	v_mfma_f32_16x16x32_bf16 v[60:63], v[152:155], v[112:115], v[60:63]
	v_mfma_f32_16x16x32_bf16 v[52:55], v[152:155], v[108:111], v[52:55]
	ds_write_b128 v126, v[12:15] offset:16512
	v_mfma_f32_16x16x32_bf16 v[44:47], v[156:159], v[64:67], v[44:47]
	v_mfma_f32_16x16x32_bf16 v[40:43], v[156:159], v[104:107], v[40:43]
	ds_write_b128 v126, v[8:11] offset:18560
	v_mfma_f32_16x16x32_bf16 v[36:39], v[156:159], v[112:115], v[36:39]
	v_mfma_f32_16x16x32_bf16 v[28:31], v[156:159], v[108:111], v[28:31]
	ds_write_b128 v126, v[4:7] offset:20608
	ds_write_b128 v126, v[0:3] offset:22656
	s_cmp_lt_u32 s27, 14
	s_mov_b32 s5, s27
	s_waitcnt lgkmcnt(0)
	s_barrier
	s_waitcnt vmcnt(5)
	v_mov_b32_e32 v16, v232
	s_waitcnt vmcnt(0)
	v_mfma_f32_16x16x32_bf16 v[0:3], v[48:51], v[64:67], v[92:95]
	v_lshrrev_b32_e32 v18, 2, v16
	v_lshrrev_b32_e32 v17, 1, v16
	v_and_b32_e32 v18, 12, v18
	v_and_or_b32 v17, v17, s24, v18
	v_and_b32_e32 v18, 0x4f, v16
	v_mul_lo_u32 v17, v17, s26
	v_lshl_add_u32 v17, v18, 1, v17
	v_cvt_pk_bf16_f32 v18, 0, v101
	ds_write_b16_d16_hi v17, v18 offset:272
	v_cvt_pk_bf16_f32 v18, 0, v102
	ds_write_b16_d16_hi v17, v18 offset:544
	v_cvt_pk_bf16_f32 v18, 0, v103
	ds_write_b16_d16_hi v17, v18 offset:816
	v_cvt_pk_bf16_f32 v18, 0, v96
	ds_write_b16_d16_hi v17, v18 offset:32
	v_cvt_pk_bf16_f32 v18, 0, v97
	ds_write_b16_d16_hi v17, v18 offset:304
	v_cvt_pk_bf16_f32 v18, 0, v98
	ds_write_b16_d16_hi v17, v18 offset:576
	v_cvt_pk_bf16_f32 v18, 0, v99
	ds_write_b16_d16_hi v17, v18 offset:848
	v_cvt_pk_bf16_f32 v18, 0, v84
	ds_write_b16_d16_hi v17, v18 offset:64
	v_cvt_pk_bf16_f32 v18, 0, v85
	ds_write_b16_d16_hi v17, v18 offset:336
	v_cvt_pk_bf16_f32 v18, 0, v86
	ds_write_b16_d16_hi v17, v18 offset:608
	v_cvt_pk_bf16_f32 v18, 0, v87
	ds_write_b16_d16_hi v17, v18 offset:880
	v_cvt_pk_bf16_f32 v18, 0, v76
	ds_write_b16_d16_hi v17, v18 offset:96
	v_cvt_pk_bf16_f32 v18, 0, v77
	ds_write_b16_d16_hi v17, v18 offset:368
	v_cvt_pk_bf16_f32 v18, 0, v78
	ds_write_b16_d16_hi v17, v18 offset:640
	v_cvt_pk_bf16_f32 v18, 0, v79
	ds_write_b16_d16_hi v17, v18 offset:912
	v_cvt_pk_bf16_f32 v18, 0, v72
	ds_write_b16_d16_hi v17, v18 offset:4352
	v_cvt_pk_bf16_f32 v18, 0, v73
	ds_write_b16_d16_hi v17, v18 offset:4624
	v_cvt_pk_bf16_f32 v18, 0, v74
	ds_write_b16_d16_hi v17, v18 offset:4896
	v_cvt_pk_bf16_f32 v18, 0, v75
	ds_write_b16_d16_hi v17, v18 offset:5168
	v_cvt_pk_bf16_f32 v18, 0, v68
	ds_write_b16_d16_hi v17, v18 offset:4384
	v_cvt_pk_bf16_f32 v18, 0, v69
	ds_write_b16_d16_hi v17, v18 offset:4656
	v_cvt_pk_bf16_f32 v18, 0, v70
	ds_write_b16_d16_hi v17, v18 offset:4928
	v_cvt_pk_bf16_f32 v18, 0, v71
	ds_write_b16_d16_hi v17, v18 offset:5200
	v_cvt_pk_bf16_f32 v18, 0, v60
	ds_write_b16_d16_hi v17, v18 offset:4416
	v_cvt_pk_bf16_f32 v18, 0, v61
	ds_write_b16_d16_hi v17, v18 offset:4688
	v_cvt_pk_bf16_f32 v18, 0, v62
	ds_write_b16_d16_hi v17, v18 offset:4960
	v_cvt_pk_bf16_f32 v18, 0, v63
	ds_write_b16_d16_hi v17, v18 offset:5232
	v_cvt_pk_bf16_f32 v18, 0, v52
	ds_write_b16_d16_hi v17, v18 offset:4448
	v_cvt_pk_bf16_f32 v18, 0, v53
	ds_write_b16_d16_hi v17, v18 offset:4720
	v_cvt_pk_bf16_f32 v18, 0, v54
	ds_write_b16_d16_hi v17, v18 offset:4992
	v_cvt_pk_bf16_f32 v18, 0, v55
	ds_write_b16_d16_hi v17, v18 offset:5264
	v_cvt_pk_bf16_f32 v18, 0, v44
	ds_write_b16_d16_hi v17, v18 offset:8704
	v_cvt_pk_bf16_f32 v18, 0, v45
	ds_write_b16_d16_hi v17, v18 offset:8976
	v_cvt_pk_bf16_f32 v18, 0, v46
	ds_write_b16_d16_hi v17, v18 offset:9248
	v_cvt_pk_bf16_f32 v18, 0, v47
	ds_write_b16_d16_hi v17, v18 offset:9520
	v_cvt_pk_bf16_f32 v18, 0, v40
	ds_write_b16_d16_hi v17, v18 offset:8736
	v_cvt_pk_bf16_f32 v18, 0, v41
	ds_write_b16_d16_hi v17, v18 offset:9008
	v_cvt_pk_bf16_f32 v18, 0, v42
	ds_write_b16_d16_hi v17, v18 offset:9280
	v_cvt_pk_bf16_f32 v18, 0, v43
	ds_write_b16_d16_hi v17, v18 offset:9552
	v_cvt_pk_bf16_f32 v18, 0, v36
	ds_write_b16_d16_hi v17, v18 offset:8768
	v_cvt_pk_bf16_f32 v18, 0, v37
	ds_write_b16_d16_hi v17, v18 offset:9040
	v_cvt_pk_bf16_f32 v18, 0, v38
	ds_write_b16_d16_hi v17, v18 offset:9312
	v_cvt_pk_bf16_f32 v18, 0, v39
	ds_write_b16_d16_hi v17, v18 offset:9584
	v_cvt_pk_bf16_f32 v18, 0, v28
	ds_write_b16_d16_hi v17, v18 offset:8800
	v_cvt_pk_bf16_f32 v18, 0, v29
	ds_write_b16_d16_hi v17, v18 offset:9072
	v_cvt_pk_bf16_f32 v18, 0, v30
	ds_write_b16_d16_hi v17, v18 offset:9344
	v_cvt_pk_bf16_f32 v18, 0, v31
	ds_write_b16_d16_hi v17, v18 offset:9616
	v_cvt_pk_bf16_f32 v0, 0, v0
	ds_write_b16_d16_hi v17, v0 offset:13056
	v_cvt_pk_bf16_f32 v0, 0, v1
	v_mfma_f32_16x16x32_bf16 v[4:7], v[48:51], v[104:107], v[88:91]
	ds_write_b16_d16_hi v17, v0 offset:13328
	v_cvt_pk_bf16_f32 v0, 0, v2
	ds_write_b16_d16_hi v17, v0 offset:13600
	v_cvt_pk_bf16_f32 v0, 0, v3
	ds_write_b16_d16_hi v17, v0 offset:13872
	s_nop 0
	s_nop 1
	v_cvt_pk_bf16_f32 v0, 0, v4
	ds_write_b16_d16_hi v17, v0 offset:13088
	v_cvt_pk_bf16_f32 v0, 0, v5
	v_mfma_f32_16x16x32_bf16 v[8:11], v[48:51], v[112:115], v[80:83]
	ds_write_b16_d16_hi v17, v0 offset:13360
	v_cvt_pk_bf16_f32 v0, 0, v6
	ds_write_b16_d16_hi v17, v0 offset:13632
	v_cvt_pk_bf16_f32 v0, 0, v7
	ds_write_b16_d16_hi v17, v0 offset:13904
	s_nop 0
	s_nop 1
	v_cvt_pk_bf16_f32 v0, 0, v8
	ds_write_b16_d16_hi v17, v0 offset:13120
	v_cvt_pk_bf16_f32 v0, 0, v9
	v_mfma_f32_16x16x32_bf16 v[12:15], v[48:51], v[108:111], v[56:59]
	ds_write_b16_d16_hi v17, v0 offset:13392
	v_cvt_pk_bf16_f32 v0, 0, v10
	ds_write_b16_d16_hi v17, v0 offset:13664
	v_cvt_pk_bf16_f32 v0, 0, v11
	ds_write_b16_d16_hi v17, v0 offset:13936
	s_nop 0
	s_nop 1
	v_cvt_pk_bf16_f32 v0, 0, v12
	ds_write_b16_d16_hi v17, v0 offset:13152
	v_cvt_pk_bf16_f32 v0, 0, v13
	ds_write_b16_d16_hi v17, v0 offset:13424
	v_cvt_pk_bf16_f32 v0, 0, v14
	ds_write_b16_d16_hi v17, v0 offset:13696
	s_lshl_b64 s[6:7], s[6:7], 1
	v_cvt_pk_bf16_f32 v0, 0, v15
	s_add_u32 s6, s16, s6
	ds_write_b16_d16_hi v17, v0 offset:13968
	v_ashrrev_i32_e32 v0, 31, v16
	s_addc_u32 s7, s17, s7
	s_lshl_b32 s4, s4, 7
	v_lshrrev_b32_e32 v0, 28, v0
	s_ashr_i32 s5, s4, 31
	v_add_u32_e32 v0, v16, v0
	s_lshl_b64 s[4:5], s[4:5], 1
	v_ashrrev_i32_e32 v4, 4, v0
	v_and_b32_e32 v0, -16, v0
	s_add_u32 s4, s6, s4
	v_sub_u32_e32 v0, v16, v0
	v_ashrrev_i32_e32 v5, 31, v4
	s_addc_u32 s5, s7, s5
	v_mul_lo_u32 v1, v4, s26
	v_lshlrev_b32_e32 v6, 3, v0
	v_lshlrev_b64 v[4:5], 11, v[4:5]
	v_ashrrev_i32_e32 v7, 31, v6
	v_lshl_add_u64 v[4:5], s[4:5], 0, v[4:5]
	v_lshl_add_u64 v[8:9], v[6:7], 1, v[4:5]
	v_add_u32_e32 v4, 0x100, v16
	v_ashrrev_i32_e32 v5, 31, v4
	v_cvt_pk_bf16_f32 v19, 0, v100
	v_lshl_add_u32 v0, v0, 4, v1
	v_lshrrev_b32_e32 v5, 28, v5
	ds_write_b16_d16_hi v17, v19
	s_waitcnt lgkmcnt(0)
	s_barrier
	ds_read_b128 v[0:3], v0
	v_add_u32_e32 v5, v4, v5
	v_ashrrev_i32_e32 v10, 4, v5
	v_and_b32_e32 v5, -16, v5
	v_sub_u32_e32 v11, v4, v5
	v_mul_lo_u32 v4, v10, s26
	v_lshl_add_u32 v4, v11, 4, v4
	ds_read_b128 v[4:7], v4
	s_waitcnt lgkmcnt(1)
	global_store_dwordx4 v[8:9], v[0:3], off
	s_add_i32 s60, s60, s61
	s_cmp_lt_i32 s60, s62
	v_lshlrev_b32_e32 v0, 3, v11
	v_ashrrev_i32_e32 v11, 31, v10
	v_lshlrev_b64 v[2:3], 11, v[10:11]
	v_ashrrev_i32_e32 v1, 31, v0
	v_lshl_add_u64 v[2:3], s[4:5], 0, v[2:3]
	v_lshl_add_u64 v[0:1], v[0:1], 1, v[2:3]
	s_waitcnt lgkmcnt(0)
	global_store_dwordx4 v[0:1], v[4:7], off
	v_add_u32_e32 v0, 0x200, v16
	v_ashrrev_i32_e32 v1, 31, v0
	v_lshrrev_b32_e32 v1, 28, v1
	v_add_u32_e32 v1, v0, v1
	v_ashrrev_i32_e32 v4, 4, v1
	v_and_b32_e32 v1, -16, v1
	v_sub_u32_e32 v0, v0, v1
	v_ashrrev_i32_e32 v5, 31, v4
	v_mul_lo_u32 v1, v4, s26
	v_lshlrev_b32_e32 v6, 3, v0
	v_lshlrev_b64 v[4:5], 11, v[4:5]
	v_ashrrev_i32_e32 v7, 31, v6
	v_lshl_add_u64 v[4:5], s[4:5], 0, v[4:5]
	v_lshl_add_u64 v[8:9], v[6:7], 1, v[4:5]
	v_add_u32_e32 v4, 0x300, v16
	v_ashrrev_i32_e32 v5, 31, v4
	v_lshl_add_u32 v0, v0, 4, v1
	v_lshrrev_b32_e32 v5, 28, v5
	ds_read_b128 v[0:3], v0
	v_add_u32_e32 v5, v4, v5
	v_ashrrev_i32_e32 v10, 4, v5
	v_and_b32_e32 v5, -16, v5
	v_sub_u32_e32 v11, v4, v5
	v_mul_lo_u32 v4, v10, s26
	v_lshl_add_u32 v4, v11, 4, v4
	ds_read_b128 v[4:7], v4
	s_waitcnt lgkmcnt(1)
	global_store_dwordx4 v[8:9], v[0:3], off
	s_nop 1
	v_lshlrev_b32_e32 v0, 3, v11
	v_ashrrev_i32_e32 v11, 31, v10
	v_lshlrev_b64 v[2:3], 11, v[10:11]
	v_ashrrev_i32_e32 v1, 31, v0
	v_lshl_add_u64 v[2:3], s[4:5], 0, v[2:3]
	v_lshl_add_u64 v[0:1], v[0:1], 1, v[2:3]
	s_waitcnt lgkmcnt(0)
	global_store_dwordx4 v[0:1], v[4:7], off
	v_add_u32_e32 v0, 0x400, v16
	v_ashrrev_i32_e32 v1, 31, v0
	v_lshrrev_b32_e32 v1, 28, v1
	v_add_u32_e32 v1, v0, v1
	v_ashrrev_i32_e32 v4, 4, v1
	v_and_b32_e32 v1, -16, v1
	v_sub_u32_e32 v0, v0, v1
	v_ashrrev_i32_e32 v5, 31, v4
	v_mul_lo_u32 v1, v4, s26
	v_lshlrev_b32_e32 v6, 3, v0
	v_lshlrev_b64 v[4:5], 11, v[4:5]
	v_ashrrev_i32_e32 v7, 31, v6
	v_lshl_add_u64 v[4:5], s[4:5], 0, v[4:5]
	v_lshl_add_u64 v[8:9], v[6:7], 1, v[4:5]
	v_add_u32_e32 v4, 0x500, v16
	v_ashrrev_i32_e32 v5, 31, v4
	v_lshl_add_u32 v0, v0, 4, v1
	v_lshrrev_b32_e32 v5, 28, v5
	ds_read_b128 v[0:3], v0
	v_add_u32_e32 v5, v4, v5
	v_ashrrev_i32_e32 v10, 4, v5
	v_and_b32_e32 v5, -16, v5
	v_sub_u32_e32 v11, v4, v5
	v_mul_lo_u32 v4, v10, s26
	v_lshl_add_u32 v4, v11, 4, v4
	ds_read_b128 v[4:7], v4
	s_waitcnt lgkmcnt(1)
	global_store_dwordx4 v[8:9], v[0:3], off
	s_nop 1
	v_lshlrev_b32_e32 v0, 3, v11
	v_ashrrev_i32_e32 v11, 31, v10
	v_lshlrev_b64 v[2:3], 11, v[10:11]
	v_ashrrev_i32_e32 v1, 31, v0
	v_lshl_add_u64 v[2:3], s[4:5], 0, v[2:3]
	v_lshl_add_u64 v[0:1], v[0:1], 1, v[2:3]
	s_waitcnt lgkmcnt(0)
	global_store_dwordx4 v[0:1], v[4:7], off
	v_add_u32_e32 v0, 0x600, v16
	v_ashrrev_i32_e32 v1, 31, v0
	v_lshrrev_b32_e32 v1, 28, v1
	v_add_u32_e32 v1, v0, v1
	v_ashrrev_i32_e32 v4, 4, v1
	v_and_b32_e32 v1, -16, v1
	v_sub_u32_e32 v0, v0, v1
	v_ashrrev_i32_e32 v5, 31, v4
	v_mul_lo_u32 v1, v4, s26
	v_lshlrev_b32_e32 v6, 3, v0
	v_lshlrev_b64 v[4:5], 11, v[4:5]
	v_ashrrev_i32_e32 v7, 31, v6
	v_lshl_add_u64 v[4:5], s[4:5], 0, v[4:5]
	v_lshl_add_u64 v[8:9], v[6:7], 1, v[4:5]
	v_add_u32_e32 v4, 0x700, v16
	v_ashrrev_i32_e32 v5, 31, v4
	v_lshl_add_u32 v0, v0, 4, v1
	v_lshrrev_b32_e32 v5, 28, v5
	ds_read_b128 v[0:3], v0
	v_add_u32_e32 v5, v4, v5
	v_ashrrev_i32_e32 v10, 4, v5
	v_and_b32_e32 v5, -16, v5
	v_sub_u32_e32 v11, v4, v5
	v_mul_lo_u32 v4, v10, s26
	v_lshl_add_u32 v4, v11, 4, v4
	ds_read_b128 v[4:7], v4
	s_waitcnt lgkmcnt(1)
	global_store_dwordx4 v[8:9], v[0:3], off
	s_nop 1
	v_lshlrev_b32_e32 v0, 3, v11
	v_ashrrev_i32_e32 v11, 31, v10
	v_lshlrev_b64 v[2:3], 11, v[10:11]
	v_ashrrev_i32_e32 v1, 31, v0
	v_lshl_add_u64 v[2:3], s[4:5], 0, v[2:3]
	v_lshl_add_u64 v[0:1], v[0:1], 1, v[2:3]
	s_waitcnt lgkmcnt(0)
	global_store_dwordx4 v[0:1], v[4:7], off
	s_cbranch_scc1 .LBB0_1280
